# v10 + GEMM phases: shift/mask tile scheduler (no reciprocal division) and peeled first K-iteration per tile whose counted waits let the previous tile's 16 epilogue stores stay in flight (vmcnt(24))
# baseline (speedup 1.0000x reference)
.LBB0_80:
	s_add_u32 s46, s44, 0x1dc00000
	s_addc_u32 s47, s45, 0
	s_add_u32 s48, s44, 0x900000
	s_addc_u32 s49, s45, 0
	s_lshl_b32 s18, s18, 5
	s_and_b32 s25, s18, 0x60
	s_add_i32 m0, s13, 0x18000
	v_lshl_add_u64 v[8:9], v[8:9], 0, s[78:79]
	s_lshl_b32 s17, s19, 6
	s_lshl_b32 s24, s19, 13
	s_lshl_b32 s26, s25, 7
	s_waitcnt vmcnt(2)
	s_barrier
	global_load_lds_dwordx4 v[8:9], off
	v_lshl_add_u64 v[6:7], v[6:7], 0, s[78:79]
	s_add_i32 m0, s13, 0x1a000
	s_add_i32 s18, s13, 0x8000
	s_add_i32 s19, s13, 0xa000
	global_load_lds_dwordx4 v[6:7], off
	v_lshl_add_u64 v[2:3], v[2:3], 0, s[78:79]
	s_mov_b32 m0, s18
	s_add_u32 s22, s54, 0x80080
	global_load_lds_dwordx4 v[2:3], off
	v_lshl_add_u64 v[2:3], v[4:5], 0, s[78:79]
	s_mov_b32 m0, s19
	s_addc_u32 s23, s55, 0
	global_load_lds_dwordx4 v[2:3], off
	s_add_i32 m0, s13, 0x1c000
	v_lshl_add_u64 v[2:3], s[22:23], 0, v[34:35]
	global_load_lds_dwordx4 v[2:3], off
	v_lshl_add_u64 v[2:3], s[22:23], 0, v[146:147]
	s_add_i32 m0, s13, 0x1e000
	v_and_b32_e32 v137, 15, v10
	global_load_lds_dwordx4 v[2:3], off
	v_lshrrev_b32_e32 v2, 1, v10
	v_and_b32_e32 v2, 24, v2
	v_lshlrev_b32_e32 v3, 1, v2
	v_lshlrev_b32_e32 v4, 2, v10
	v_or_b32_e32 v161, s25, v2
	v_lshlrev_b32_e32 v2, 15, v14
	v_lshl_or_b32 v3, v137, 6, v3
	v_and_b32_e32 v4, 32, v4
	v_and_b32_e32 v2, 0xffff0000, v2
	v_bitop3_b32 v5, v3, s24, v4 bitop3:0xde
	v_bitop3_b32 v160, v3, s26, v4 bitop3:0xde
	v_lshl_add_u32 v2, v15, 12, v2
	v_and_b32_e32 v3, 1, v14
	v_lshl_or_b32 v2, v3, 6, v2
	v_lshl_add_u32 v150, v16, 1, v2
	v_lshlrev_b32_e32 v2, 15, v11
	v_and_b32_e32 v2, 0xffff0000, v2
	s_waitcnt vmcnt(6)
	v_lshl_add_u32 v2, v12, 12, v2
	v_and_b32_e32 v3, 1, v11
	s_cmpk_lt_u32 s20, 0x100
	v_lshl_or_b32 v2, v3, 6, v2
	s_sext_i32_i16 s21, s40
	s_cselect_b64 s[52:53], -1, 0
	v_cmp_lt_u32_e64 s[40:41], 12, v137
	v_add_u32_e32 v148, -13, v137
	v_mov_b32_e32 v149, v35
	v_mov_b32_e32 v151, v35
	v_lshl_add_u32 v152, v13, 1, v2
	v_mov_b32_e32 v153, v35
	s_mov_b32 s20, 0
	v_add_u32_e32 v162, 0, v5
	s_barrier
	s_mov_b32 s98, 0
	s_branch .LBB0_83

.LBB0_83:
	s_add_i32 s20, s20, 1
	s_mul_i32 s22, s20, s2
	s_mul_hi_u32 s23, s20, s33
	s_add_i32 s23, s23, s22
	s_mul_i32 s22, s20, s33
	s_add_u32 s62, s22, s5
	s_addc_u32 s63, s23, s11
	v_cmp_gt_i64_e32 vcc, s[62:63], v[134:135]
	v_cmp_lt_i64_e64 s[42:43], s[62:63], v[132:133]
	s_cbranch_vccnz .LBB0_89
	s_and_b32 s23, s62, 7
	s_lshr_b32 s22, s62, 3
	s_lshl_b32 s23, s23, 9
	s_add_i32 s22, s22, s23
	s_lshr_b32 s24, s22, 8
	s_lshl_b32 s24, s24, 3
	s_and_b32 s22, s22, 0xff
	s_lshr_b32 s56, s22, 3
	s_and_b32 s22, s22, 7
	s_add_i32 s60, s24, s22
.LBB0_89:
	s_ashr_i32 s61, s60, 31
	s_lshl_b64 s[22:23], s[60:61], 20
	s_add_u32 s62, s8, s22
	s_addc_u32 s63, s9, s23
	s_and_b64 s[22:23], s[42:43], exec
	s_cselect_b32 s22, s63, s77
	s_cselect_b32 s23, s62, s76
	s_ashr_i32 s57, s56, 31
	s_lshl_b64 s[24:25], s[56:57], 20
	s_add_u32 s66, s6, s24
	s_addc_u32 s67, s7, s25
	s_and_b64 s[24:25], s[42:43], exec
	s_cselect_b32 s24, s67, s55
	s_cselect_b32 s25, s66, s54
	s_add_u32 s26, s54, 0x100
	s_addc_u32 s27, s55, 0
	s_add_u32 s76, s76, 0x80080
	v_mov_b32_e32 v2, 0
	s_addc_u32 s77, s77, 0
	s_mov_b32 s28, -2
	v_mov_b32_e32 v3, v2
	v_mov_b32_e32 v4, v2
	v_mov_b32_e32 v5, v2
	v_mov_b32_e32 v6, v2
	v_mov_b32_e32 v7, v2
	v_mov_b32_e32 v8, v2
	v_mov_b32_e32 v9, v2
	v_mov_b32_e32 v10, v2
	v_mov_b32_e32 v11, v2
	v_mov_b32_e32 v12, v2
	v_mov_b32_e32 v13, v2
	v_mov_b32_e32 v18, v2
	v_mov_b32_e32 v19, v2
	v_mov_b32_e32 v20, v2
	v_mov_b32_e32 v21, v2
	v_mov_b32_e32 v26, v2
	v_mov_b32_e32 v27, v2
	v_mov_b32_e32 v28, v2
	v_mov_b32_e32 v29, v2
	v_mov_b32_e32 v36, v2
	v_mov_b32_e32 v37, v2
	v_mov_b32_e32 v38, v2
	v_mov_b32_e32 v39, v2
	v_mov_b32_e32 v44, v2
	v_mov_b32_e32 v45, v2
	v_mov_b32_e32 v46, v2
	v_mov_b32_e32 v47, v2
	v_mov_b32_e32 v52, v2
	v_mov_b32_e32 v53, v2
	v_mov_b32_e32 v54, v2
	v_mov_b32_e32 v55, v2
	v_mov_b32_e32 v14, v2
	v_mov_b32_e32 v15, v2
	v_mov_b32_e32 v16, v2
	v_mov_b32_e32 v17, v2
	v_mov_b32_e32 v22, v2
	v_mov_b32_e32 v23, v2
	v_mov_b32_e32 v24, v2
	v_mov_b32_e32 v25, v2
	v_mov_b32_e32 v30, v2
	v_mov_b32_e32 v31, v2
	v_mov_b32_e32 v32, v2
	v_mov_b32_e32 v33, v2
	v_mov_b32_e32 v40, v2
	v_mov_b32_e32 v41, v2
	v_mov_b32_e32 v42, v2
	v_mov_b32_e32 v43, v2
	v_mov_b32_e32 v48, v2
	v_mov_b32_e32 v49, v2
	v_mov_b32_e32 v50, v2
	v_mov_b32_e32 v51, v2
	v_mov_b32_e32 v56, v2
	v_mov_b32_e32 v57, v2
	v_mov_b32_e32 v58, v2
	v_mov_b32_e32 v59, v2
	v_mov_b32_e32 v60, v2
	v_mov_b32_e32 v61, v2
	v_mov_b32_e32 v62, v2
	v_mov_b32_e32 v63, v2
	v_mov_b32_e32 v64, v2
	v_mov_b32_e32 v65, v2
	v_mov_b32_e32 v66, v2
	v_mov_b32_e32 v67, v2
	v_mov_b32_e32 v68, v2
	v_mov_b32_e32 v69, v2
	v_mov_b32_e32 v70, v2
	v_mov_b32_e32 v71, v2
	v_mov_b32_e32 v72, v2
	v_mov_b32_e32 v73, v2
	v_mov_b32_e32 v74, v2
	v_mov_b32_e32 v75, v2
	v_mov_b32_e32 v76, v2
	v_mov_b32_e32 v77, v2
	v_mov_b32_e32 v78, v2
	v_mov_b32_e32 v79, v2
	v_mov_b32_e32 v84, v2
	v_mov_b32_e32 v85, v2
	v_mov_b32_e32 v86, v2
	v_mov_b32_e32 v87, v2
	v_mov_b32_e32 v92, v2
	v_mov_b32_e32 v93, v2
	v_mov_b32_e32 v94, v2
	v_mov_b32_e32 v95, v2
	v_mov_b32_e32 v100, v2
	v_mov_b32_e32 v101, v2
	v_mov_b32_e32 v102, v2
	v_mov_b32_e32 v103, v2
	v_mov_b32_e32 v108, v2
	v_mov_b32_e32 v109, v2
	v_mov_b32_e32 v110, v2
	v_mov_b32_e32 v111, v2
	v_mov_b32_e32 v116, v2
	v_mov_b32_e32 v117, v2
	v_mov_b32_e32 v118, v2
	v_mov_b32_e32 v119, v2
	v_mov_b32_e32 v80, v2
	v_mov_b32_e32 v81, v2
	v_mov_b32_e32 v82, v2
	v_mov_b32_e32 v83, v2
	v_mov_b32_e32 v88, v2
	v_mov_b32_e32 v89, v2
	v_mov_b32_e32 v90, v2
	v_mov_b32_e32 v91, v2
	v_mov_b32_e32 v96, v2
	v_mov_b32_e32 v97, v2
	v_mov_b32_e32 v98, v2
	v_mov_b32_e32 v99, v2
	v_mov_b32_e32 v104, v2
	v_mov_b32_e32 v105, v2
	v_mov_b32_e32 v106, v2
	v_mov_b32_e32 v107, v2
	v_mov_b32_e32 v112, v2
	v_mov_b32_e32 v113, v2
	v_mov_b32_e32 v114, v2
	v_mov_b32_e32 v115, v2
	v_mov_b32_e32 v120, v2
	v_mov_b32_e32 v121, v2
	v_mov_b32_e32 v122, v2
	v_mov_b32_e32 v123, v2
	v_mov_b32_e32 v124, v2
	v_mov_b32_e32 v125, v2
	v_mov_b32_e32 v126, v2
	v_mov_b32_e32 v127, v2
	v_mov_b32_e32 v128, v2
	v_mov_b32_e32 v129, v2
	v_mov_b32_e32 v130, v2
	v_mov_b32_e32 v131, v2
	s_cmp_lg_u32 s98, 0
	s_mov_b32 s98, 1
	s_cbranch_scc0 .LBB0_90
	s_add_u32 s29, s76, 0xfff80080
	s_addc_u32 s30, s77, -1
	s_add_i32 s31, 0, 0x10000
	s_cmp_eq_u32 s28, 28
	s_cselect_b32 s85, s22, s30
	s_cselect_b32 s84, s23, s29
	v_add_u32_e32 v158, s31, v160
	s_cselect_b32 s55, s24, s27
	s_cselect_b32 s54, s25, s26
	s_add_i32 s29, 0, 0x14000
	ds_read_b128 v[154:157], v158
	ds_read_b128 v[180:183], v158 offset:1024
	ds_read_b128 v[184:187], v158 offset:2048
	ds_read_b128 v[188:191], v158 offset:3072
	v_add_u32_e32 v158, s29, v160
	ds_read_b128 v[192:195], v158
	ds_read_b128 v[196:199], v158 offset:1024
	ds_read_b128 v[200:203], v158 offset:2048
	ds_read_b128 v[204:207], v158 offset:3072
	v_lshl_add_u64 v[158:159], s[76:77], 0, v[152:153]
	s_add_i32 m0, s13, 0xc000
	ds_read_b128 v[208:211], v162
	ds_read_b128 v[212:215], v162 offset:1024
	ds_read_b128 v[216:219], v162 offset:2048
	ds_read_b128 v[222:225], v162 offset:3072
	ds_read_b128 v[226:229], v162 offset:4096
	ds_read_b128 v[230:233], v162 offset:5120
	ds_read_b128 v[234:237], v162 offset:6144
	ds_read_b128 v[238:241], v162 offset:7168
	global_load_lds_dwordx4 v[158:159], off
	v_lshl_add_u64 v[158:159], s[76:77], 0, v[150:151]
	s_add_i32 m0, s13, 0xe000
	s_nop 0
	global_load_lds_dwordx4 v[158:159], off
	s_waitcnt vmcnt(24)
	s_waitcnt lgkmcnt(0)
	s_barrier
	s_setprio 1
	s_waitcnt lgkmcnt(0)
	v_mfma_f32_16x16x32_bf16 v[128:131], v[154:157], v[208:211], v[128:131]
	v_mfma_f32_16x16x32_bf16 v[128:131], v[180:183], v[212:215], v[128:131]
	v_mfma_f32_16x16x32_bf16 v[120:123], v[154:157], v[216:219], v[120:123]
	v_mfma_f32_16x16x32_bf16 v[120:123], v[180:183], v[222:225], v[120:123]
	v_mfma_f32_16x16x32_bf16 v[104:107], v[154:157], v[226:229], v[104:107]
	v_mfma_f32_16x16x32_bf16 v[104:107], v[180:183], v[230:233], v[104:107]
	v_mfma_f32_16x16x32_bf16 v[88:91], v[154:157], v[234:237], v[88:91]
	v_mfma_f32_16x16x32_bf16 v[88:91], v[180:183], v[238:241], v[88:91]
	v_mfma_f32_16x16x32_bf16 v[80:83], v[184:187], v[234:237], v[80:83]
	v_mfma_f32_16x16x32_bf16 v[80:83], v[188:191], v[238:241], v[80:83]
	v_mfma_f32_16x16x32_bf16 v[96:99], v[184:187], v[226:229], v[96:99]
	v_mfma_f32_16x16x32_bf16 v[96:99], v[188:191], v[230:233], v[96:99]
	v_mfma_f32_16x16x32_bf16 v[112:115], v[184:187], v[216:219], v[112:115]
	v_mfma_f32_16x16x32_bf16 v[112:115], v[188:191], v[222:225], v[112:115]
	v_mfma_f32_16x16x32_bf16 v[124:127], v[184:187], v[208:211], v[124:127]
	v_mfma_f32_16x16x32_bf16 v[124:127], v[188:191], v[212:215], v[124:127]
	s_setprio 0
	s_setprio 1
	v_mfma_f32_16x16x32_bf16 v[116:119], v[192:195], v[208:211], v[116:119]
	v_mfma_f32_16x16x32_bf16 v[116:119], v[196:199], v[212:215], v[116:119]
	v_mfma_f32_16x16x32_bf16 v[100:103], v[192:195], v[216:219], v[100:103]
	v_mfma_f32_16x16x32_bf16 v[100:103], v[196:199], v[222:225], v[100:103]
	v_mfma_f32_16x16x32_bf16 v[84:87], v[192:195], v[226:229], v[84:87]
	v_mfma_f32_16x16x32_bf16 v[84:87], v[196:199], v[230:233], v[84:87]
	v_mfma_f32_16x16x32_bf16 v[72:75], v[192:195], v[234:237], v[72:75]
	v_mfma_f32_16x16x32_bf16 v[72:75], v[196:199], v[238:241], v[72:75]
	v_mfma_f32_16x16x32_bf16 v[68:71], v[200:203], v[234:237], v[68:71]
	v_mfma_f32_16x16x32_bf16 v[68:71], v[204:207], v[238:241], v[68:71]
	v_mfma_f32_16x16x32_bf16 v[76:79], v[200:203], v[226:229], v[76:79]
	v_mfma_f32_16x16x32_bf16 v[76:79], v[204:207], v[230:233], v[76:79]
	v_mfma_f32_16x16x32_bf16 v[92:95], v[200:203], v[216:219], v[92:95]
	v_mfma_f32_16x16x32_bf16 v[92:95], v[204:207], v[222:225], v[92:95]
	v_mfma_f32_16x16x32_bf16 v[108:111], v[200:203], v[208:211], v[108:111]
	v_mfma_f32_16x16x32_bf16 v[108:111], v[204:207], v[212:215], v[108:111]
	s_setprio 0
	s_barrier
	s_add_i32 s30, s31, s12
	v_lshl_add_u64 v[158:159], s[54:55], 0, v[34:35]
	s_mov_b32 m0, s30
	ds_read_b128 v[208:211], v162 offset:16384
	ds_read_b128 v[212:215], v162 offset:17408
	ds_read_b128 v[216:219], v162 offset:18432
	ds_read_b128 v[222:225], v162 offset:19456
	ds_read_b128 v[226:229], v162 offset:20480
	ds_read_b128 v[230:233], v162 offset:21504
	ds_read_b128 v[234:237], v162 offset:22528
	ds_read_b128 v[238:241], v162 offset:23552
	global_load_lds_dwordx4 v[158:159], off
	s_add_i32 m0, s30, 0x2000
	s_add_u32 s30, s54, 0x80000
	v_lshl_add_u64 v[242:243], s[54:55], 0, v[146:147]
	s_addc_u32 s31, s55, 0
	s_add_i32 s29, s29, s12
	global_load_lds_dwordx4 v[242:243], off
	v_lshl_add_u64 v[244:245], s[30:31], 0, v[34:35]
	s_mov_b32 m0, s29
	v_lshl_add_u64 v[246:247], s[84:85], 0, v[144:145]
	global_load_lds_dwordx4 v[244:245], off
	v_lshl_add_u64 v[244:245], s[30:31], 0, v[146:147]
	s_add_i32 m0, s29, 0x2000
	s_nop 0
	global_load_lds_dwordx4 v[244:245], off
	v_lshl_add_u64 v[244:245], s[84:85], 0, v[142:143]
	s_mov_b32 m0, s13
	s_nop 0
	global_load_lds_dwordx4 v[244:245], off
	s_mov_b32 m0, s14
	s_nop 0
	global_load_lds_dwordx4 v[246:247], off
	s_waitcnt vmcnt(24)
	s_waitcnt lgkmcnt(0)
	s_barrier
	s_setprio 1
	s_waitcnt lgkmcnt(0)
	v_mfma_f32_16x16x32_bf16 v[64:67], v[154:157], v[208:211], v[64:67]
	v_mfma_f32_16x16x32_bf16 v[64:67], v[180:183], v[212:215], v[64:67]
	v_mfma_f32_16x16x32_bf16 v[56:59], v[154:157], v[216:219], v[56:59]
	v_mfma_f32_16x16x32_bf16 v[56:59], v[180:183], v[222:225], v[56:59]
	v_mfma_f32_16x16x32_bf16 v[40:43], v[154:157], v[226:229], v[40:43]
	v_mfma_f32_16x16x32_bf16 v[40:43], v[180:183], v[230:233], v[40:43]
	v_mfma_f32_16x16x32_bf16 v[22:25], v[154:157], v[234:237], v[22:25]
	v_mfma_f32_16x16x32_bf16 v[22:25], v[180:183], v[238:241], v[22:25]
	v_mfma_f32_16x16x32_bf16 v[14:17], v[184:187], v[234:237], v[14:17]
	v_mfma_f32_16x16x32_bf16 v[14:17], v[188:191], v[238:241], v[14:17]
	v_mfma_f32_16x16x32_bf16 v[30:33], v[184:187], v[226:229], v[30:33]
	v_mfma_f32_16x16x32_bf16 v[30:33], v[188:191], v[230:233], v[30:33]
	v_mfma_f32_16x16x32_bf16 v[48:51], v[184:187], v[216:219], v[48:51]
	v_mfma_f32_16x16x32_bf16 v[48:51], v[188:191], v[222:225], v[48:51]
	v_mfma_f32_16x16x32_bf16 v[60:63], v[184:187], v[208:211], v[60:63]
	v_mfma_f32_16x16x32_bf16 v[60:63], v[188:191], v[212:215], v[60:63]
	s_setprio 0
	s_setprio 1
	v_mfma_f32_16x16x32_bf16 v[52:55], v[192:195], v[208:211], v[52:55]
	v_mfma_f32_16x16x32_bf16 v[52:55], v[196:199], v[212:215], v[52:55]
	v_mfma_f32_16x16x32_bf16 v[36:39], v[192:195], v[216:219], v[36:39]
	v_mfma_f32_16x16x32_bf16 v[36:39], v[196:199], v[222:225], v[36:39]
	v_mfma_f32_16x16x32_bf16 v[18:21], v[192:195], v[226:229], v[18:21]
	v_mfma_f32_16x16x32_bf16 v[18:21], v[196:199], v[230:233], v[18:21]
	v_mfma_f32_16x16x32_bf16 v[6:9], v[192:195], v[234:237], v[6:9]
	v_mfma_f32_16x16x32_bf16 v[6:9], v[196:199], v[238:241], v[6:9]
	v_mfma_f32_16x16x32_bf16 v[2:5], v[200:203], v[234:237], v[2:5]
	v_mfma_f32_16x16x32_bf16 v[2:5], v[204:207], v[238:241], v[2:5]
	v_mfma_f32_16x16x32_bf16 v[10:13], v[200:203], v[226:229], v[10:13]
	v_mfma_f32_16x16x32_bf16 v[10:13], v[204:207], v[230:233], v[10:13]
	v_mfma_f32_16x16x32_bf16 v[26:29], v[200:203], v[216:219], v[26:29]
	v_mfma_f32_16x16x32_bf16 v[26:29], v[204:207], v[222:225], v[26:29]
	v_mfma_f32_16x16x32_bf16 v[44:47], v[200:203], v[208:211], v[44:47]
	v_mfma_f32_16x16x32_bf16 v[44:47], v[204:207], v[212:215], v[44:47]
	s_setprio 0
	s_barrier
	s_add_i32 s29, 0, 0x18000
	v_add_u32_e32 v163, s29, v160
	s_add_i32 s39, 0, 0x1c000
	ds_read_b128 v[154:157], v163
	ds_read_b128 v[180:183], v163 offset:1024
	ds_read_b128 v[184:187], v163 offset:2048
	ds_read_b128 v[188:191], v163 offset:3072
	v_add_u32_e32 v163, s39, v160
	ds_read_b128 v[192:195], v163
	ds_read_b128 v[196:199], v163 offset:1024
	ds_read_b128 v[200:203], v163 offset:2048
	ds_read_b128 v[204:207], v163 offset:3072
	s_add_u32 s30, s84, 0x80000
	s_addc_u32 s31, s85, 0
	s_mov_b32 m0, s15
	v_lshl_add_u64 v[248:249], s[30:31], 0, v[142:143]
	ds_read_b128 v[208:211], v162 offset:32768
	ds_read_b128 v[212:215], v162 offset:33792
	ds_read_b128 v[216:219], v162 offset:34816
	ds_read_b128 v[222:225], v162 offset:35840
	ds_read_b128 v[226:229], v162 offset:36864
	ds_read_b128 v[230:233], v162 offset:37888
	ds_read_b128 v[234:237], v162 offset:38912
	ds_read_b128 v[238:241], v162 offset:39936
	global_load_lds_dwordx4 v[248:249], off
	v_lshl_add_u64 v[248:249], s[30:31], 0, v[144:145]
	s_mov_b32 m0, s16
	s_nop 0
	global_load_lds_dwordx4 v[248:249], off
	s_waitcnt vmcnt(8)
	s_waitcnt lgkmcnt(0)
	s_barrier
	s_setprio 1
	s_waitcnt lgkmcnt(0)
	v_mfma_f32_16x16x32_bf16 v[128:131], v[154:157], v[208:211], v[128:131]
	v_mfma_f32_16x16x32_bf16 v[128:131], v[180:183], v[212:215], v[128:131]
	v_mfma_f32_16x16x32_bf16 v[120:123], v[154:157], v[216:219], v[120:123]
	v_mfma_f32_16x16x32_bf16 v[120:123], v[180:183], v[222:225], v[120:123]
	v_mfma_f32_16x16x32_bf16 v[104:107], v[154:157], v[226:229], v[104:107]
	v_mfma_f32_16x16x32_bf16 v[104:107], v[180:183], v[230:233], v[104:107]
	v_mfma_f32_16x16x32_bf16 v[88:91], v[154:157], v[234:237], v[88:91]
	v_mfma_f32_16x16x32_bf16 v[88:91], v[180:183], v[238:241], v[88:91]
	v_mfma_f32_16x16x32_bf16 v[80:83], v[184:187], v[234:237], v[80:83]
	v_mfma_f32_16x16x32_bf16 v[80:83], v[188:191], v[238:241], v[80:83]
	v_mfma_f32_16x16x32_bf16 v[96:99], v[184:187], v[226:229], v[96:99]
	v_mfma_f32_16x16x32_bf16 v[96:99], v[188:191], v[230:233], v[96:99]
	v_mfma_f32_16x16x32_bf16 v[112:115], v[184:187], v[216:219], v[112:115]
	v_mfma_f32_16x16x32_bf16 v[112:115], v[188:191], v[222:225], v[112:115]
	v_mfma_f32_16x16x32_bf16 v[124:127], v[184:187], v[208:211], v[124:127]
	v_mfma_f32_16x16x32_bf16 v[124:127], v[188:191], v[212:215], v[124:127]
	s_setprio 0
	s_setprio 1
	v_mfma_f32_16x16x32_bf16 v[116:119], v[192:195], v[208:211], v[116:119]
	v_mfma_f32_16x16x32_bf16 v[116:119], v[196:199], v[212:215], v[116:119]
	v_mfma_f32_16x16x32_bf16 v[100:103], v[192:195], v[216:219], v[100:103]
	v_mfma_f32_16x16x32_bf16 v[100:103], v[196:199], v[222:225], v[100:103]
	v_mfma_f32_16x16x32_bf16 v[84:87], v[192:195], v[226:229], v[84:87]
	v_mfma_f32_16x16x32_bf16 v[84:87], v[196:199], v[230:233], v[84:87]
	v_mfma_f32_16x16x32_bf16 v[72:75], v[192:195], v[234:237], v[72:75]
	v_mfma_f32_16x16x32_bf16 v[72:75], v[196:199], v[238:241], v[72:75]
	v_mfma_f32_16x16x32_bf16 v[68:71], v[200:203], v[234:237], v[68:71]
	v_mfma_f32_16x16x32_bf16 v[68:71], v[204:207], v[238:241], v[68:71]
	v_mfma_f32_16x16x32_bf16 v[76:79], v[200:203], v[226:229], v[76:79]
	v_mfma_f32_16x16x32_bf16 v[76:79], v[204:207], v[230:233], v[76:79]
	v_mfma_f32_16x16x32_bf16 v[92:95], v[200:203], v[216:219], v[92:95]
	v_mfma_f32_16x16x32_bf16 v[92:95], v[204:207], v[222:225], v[92:95]
	v_mfma_f32_16x16x32_bf16 v[108:111], v[200:203], v[208:211], v[108:111]
	v_mfma_f32_16x16x32_bf16 v[108:111], v[204:207], v[212:215], v[108:111]
	s_setprio 0
	s_barrier
	s_add_i32 s29, s29, s12
	v_lshl_add_u64 v[158:159], v[158:159], 0, s[78:79]
	s_mov_b32 m0, s29
	ds_read_b128 v[208:211], v162 offset:49152
	ds_read_b128 v[212:215], v162 offset:50176
	ds_read_b128 v[216:219], v162 offset:51200
	ds_read_b128 v[222:225], v162 offset:52224
	ds_read_b128 v[226:229], v162 offset:53248
	ds_read_b128 v[230:233], v162 offset:54272
	ds_read_b128 v[234:237], v162 offset:55296
	ds_read_b128 v[238:241], v162 offset:56320
	global_load_lds_dwordx4 v[158:159], off
	s_add_i32 m0, s29, 0x2000
	s_add_u32 s30, s54, 0x80080
	v_lshl_add_u64 v[158:159], v[242:243], 0, s[78:79]
	s_addc_u32 s31, s55, 0
	s_add_i32 s29, s39, s12
	global_load_lds_dwordx4 v[158:159], off
	v_lshl_add_u64 v[158:159], s[30:31], 0, v[34:35]
	s_mov_b32 m0, s29
	s_nop 0
	global_load_lds_dwordx4 v[158:159], off
	v_lshl_add_u64 v[158:159], s[30:31], 0, v[146:147]
	s_add_i32 m0, s29, 0x2000
	s_nop 0
	global_load_lds_dwordx4 v[158:159], off
	v_lshl_add_u64 v[158:159], v[244:245], 0, s[78:79]
	s_mov_b32 m0, s18
	s_nop 0
	global_load_lds_dwordx4 v[158:159], off
	v_lshl_add_u64 v[158:159], v[246:247], 0, s[78:79]
	s_mov_b32 m0, s19
	s_nop 0
	global_load_lds_dwordx4 v[158:159], off
	s_waitcnt vmcnt(8)
	s_waitcnt lgkmcnt(0)
	s_barrier
	s_setprio 1
	s_waitcnt lgkmcnt(0)
	v_mfma_f32_16x16x32_bf16 v[64:67], v[154:157], v[208:211], v[64:67]
	v_mfma_f32_16x16x32_bf16 v[64:67], v[180:183], v[212:215], v[64:67]
	v_mfma_f32_16x16x32_bf16 v[56:59], v[154:157], v[216:219], v[56:59]
	v_mfma_f32_16x16x32_bf16 v[56:59], v[180:183], v[222:225], v[56:59]
	v_mfma_f32_16x16x32_bf16 v[40:43], v[154:157], v[226:229], v[40:43]
	v_mfma_f32_16x16x32_bf16 v[40:43], v[180:183], v[230:233], v[40:43]
	v_mfma_f32_16x16x32_bf16 v[22:25], v[154:157], v[234:237], v[22:25]
	v_mfma_f32_16x16x32_bf16 v[22:25], v[180:183], v[238:241], v[22:25]
	v_mfma_f32_16x16x32_bf16 v[14:17], v[184:187], v[234:237], v[14:17]
	v_mfma_f32_16x16x32_bf16 v[14:17], v[188:191], v[238:241], v[14:17]
	v_mfma_f32_16x16x32_bf16 v[30:33], v[184:187], v[226:229], v[30:33]
	v_mfma_f32_16x16x32_bf16 v[30:33], v[188:191], v[230:233], v[30:33]
	v_mfma_f32_16x16x32_bf16 v[48:51], v[184:187], v[216:219], v[48:51]
	v_mfma_f32_16x16x32_bf16 v[48:51], v[188:191], v[222:225], v[48:51]
	v_mfma_f32_16x16x32_bf16 v[60:63], v[184:187], v[208:211], v[60:63]
	v_mfma_f32_16x16x32_bf16 v[60:63], v[188:191], v[212:215], v[60:63]
	s_setprio 0
	s_setprio 1
	v_mfma_f32_16x16x32_bf16 v[52:55], v[192:195], v[208:211], v[52:55]
	v_mfma_f32_16x16x32_bf16 v[52:55], v[196:199], v[212:215], v[52:55]
	v_mfma_f32_16x16x32_bf16 v[36:39], v[192:195], v[216:219], v[36:39]
	v_mfma_f32_16x16x32_bf16 v[36:39], v[196:199], v[222:225], v[36:39]
	v_mfma_f32_16x16x32_bf16 v[18:21], v[192:195], v[226:229], v[18:21]
	v_mfma_f32_16x16x32_bf16 v[18:21], v[196:199], v[230:233], v[18:21]
	v_mfma_f32_16x16x32_bf16 v[6:9], v[192:195], v[234:237], v[6:9]
	v_mfma_f32_16x16x32_bf16 v[6:9], v[196:199], v[238:241], v[6:9]
	v_mfma_f32_16x16x32_bf16 v[2:5], v[200:203], v[234:237], v[2:5]
	v_mfma_f32_16x16x32_bf16 v[2:5], v[204:207], v[238:241], v[2:5]
	v_mfma_f32_16x16x32_bf16 v[10:13], v[200:203], v[226:229], v[10:13]
	v_mfma_f32_16x16x32_bf16 v[10:13], v[204:207], v[230:233], v[10:13]
	v_mfma_f32_16x16x32_bf16 v[26:29], v[200:203], v[216:219], v[26:29]
	v_mfma_f32_16x16x32_bf16 v[26:29], v[204:207], v[222:225], v[26:29]
	v_mfma_f32_16x16x32_bf16 v[44:47], v[200:203], v[208:211], v[44:47]
	v_mfma_f32_16x16x32_bf16 v[44:47], v[204:207], v[212:215], v[44:47]
	s_setprio 0
	s_barrier
	s_add_i32 s28, s28, 2
	s_add_u32 s26, s26, 0x100
	s_addc_u32 s27, s27, 0
	s_add_u32 s76, s76, 0x100
	s_addc_u32 s77, s77, 0
	s_branch .LBB0_90

.LBB0_834:
	s_sext_i32_i8 s19, s42
	s_add_u32 s42, s40, 0xdc00000
	s_waitcnt vmcnt(0)
	v_lshrrev_b32_e32 v18, 1, v16
	s_addc_u32 s43, s41, 0
	v_and_b32_e32 v18, 24, v18
	s_lshl_b32 s16, s16, 5
	v_and_b32_e32 v17, 15, v16
	v_lshlrev_b32_e32 v19, 1, v18
	v_lshlrev_b32_e32 v16, 2, v16
	s_and_b32 s22, s16, 0x60
	v_lshl_or_b32 v137, s17, 6, v17
	v_lshl_or_b32 v17, v17, 6, v19
	s_lshl_b32 s17, s17, 13
	v_and_b32_e32 v16, 32, v16
	s_lshl_b32 s16, s22, 7
	s_add_i32 m0, s12, 0x18000
	v_lshl_add_u64 v[8:9], v[8:9], 0, s[78:79]
	v_bitop3_b32 v19, v17, s17, v16 bitop3:0xde
	v_bitop3_b32 v154, v17, s16, v16 bitop3:0xde
	s_waitcnt vmcnt(2)
	s_barrier
	global_load_lds_dwordx4 v[8:9], off
	v_lshl_add_u64 v[6:7], v[6:7], 0, s[78:79]
	s_add_i32 m0, s12, 0x1a000
	s_add_i32 s16, s12, 0x8000
	s_add_i32 s17, s12, 0xa000
	global_load_lds_dwordx4 v[6:7], off
	v_lshl_add_u64 v[2:3], v[2:3], 0, s[78:79]
	s_mov_b32 m0, s16
	s_add_u32 s20, s54, 0x80080
	global_load_lds_dwordx4 v[2:3], off
	v_lshl_add_u64 v[2:3], v[4:5], 0, s[78:79]
	s_mov_b32 m0, s17
	s_addc_u32 s21, s55, 0
	global_load_lds_dwordx4 v[2:3], off
	s_add_i32 m0, s12, 0x1c000
	v_lshl_add_u64 v[2:3], s[20:21], 0, v[34:35]
	global_load_lds_dwordx4 v[2:3], off
	v_lshl_add_u64 v[2:3], s[20:21], 0, v[146:147]
	s_add_i32 m0, s12, 0x1e000
	s_cmpk_lt_u32 s18, 0x100
	global_load_lds_dwordx4 v[2:3], off
	v_lshlrev_b32_e32 v2, 17, v13
	v_and_b32_e32 v2, 0xfffc0000, v2
	v_lshl_add_u32 v2, v14, 14, v2
	v_and_b32_e32 v3, 1, v13
	v_lshl_or_b32 v2, v3, 6, v2
	v_lshl_add_u32 v148, v15, 1, v2
	v_lshlrev_b32_e32 v2, 17, v10
	v_and_b32_e32 v2, 0xfffc0000, v2
	s_waitcnt vmcnt(6)
	v_lshl_add_u32 v2, v11, 14, v2
	v_and_b32_e32 v3, 1, v10
	v_lshl_or_b32 v2, v3, 6, v2
	s_cselect_b64 s[44:45], -1, 0
	v_or_b32_e32 v155, s22, v18
	v_mov_b32_e32 v149, v35
	v_lshl_add_u32 v150, v12, 1, v2
	v_mov_b32_e32 v151, v35
	s_mov_b32 s18, 0
	v_add_u32_e32 v156, 0, v19
	s_barrier
	s_mov_b32 s98, 0
	s_branch .LBB0_837

.LBB0_837:
	s_add_i32 s18, s18, 1
	s_mul_i32 s20, s18, s2
	s_mul_hi_u32 s21, s18, s33
	s_add_i32 s21, s21, s20
	s_mul_i32 s20, s18, s33
	s_add_u32 s56, s20, s5
	s_addc_u32 s57, s21, s6
	v_cmp_gt_i64_e32 vcc, s[56:57], v[140:141]
	v_cmp_lt_i64_e64 s[40:41], s[56:57], v[138:139]
	s_cbranch_vccnz .LBB0_843
	s_and_b32 s21, s56, 7
	s_lshr_b32 s20, s56, 3
	s_lshl_b32 s21, s21, 7
	s_add_i32 s20, s20, s21
	s_lshr_b32 s22, s20, 5
	s_lshl_b32 s22, s22, 2
	s_and_b32 s20, s20, 0x1f
	s_lshr_b32 s46, s20, 2
	s_and_b32 s20, s20, 3
	s_add_i32 s48, s22, s20
.LBB0_843:
	s_ashr_i32 s49, s48, 31
	s_lshl_b64 s[20:21], s[48:49], 22
	s_add_u32 s56, s7, s20
	s_addc_u32 s57, s8, s21
	s_and_b64 s[20:21], s[40:41], exec
	s_cselect_b32 s20, s57, s63
	s_cselect_b32 s21, s56, s62
	s_ashr_i32 s47, s46, 31
	s_lshl_b64 s[22:23], s[46:47], 20
	s_add_u32 s60, s9, s22
	s_addc_u32 s61, s10, s23
	s_and_b64 s[22:23], s[40:41], exec
	s_cselect_b32 s22, s61, s55
	s_cselect_b32 s23, s60, s54
	s_add_u32 s24, s54, 0x100
	s_addc_u32 s25, s55, 0
	s_add_u32 s62, s62, 0x200080
	v_mov_b32_e32 v2, 0
	s_addc_u32 s63, s63, 0
	s_mov_b32 s26, -2
	v_mov_b32_e32 v3, v2
	v_mov_b32_e32 v4, v2
	v_mov_b32_e32 v5, v2
	v_mov_b32_e32 v6, v2
	v_mov_b32_e32 v7, v2
	v_mov_b32_e32 v8, v2
	v_mov_b32_e32 v9, v2
	v_mov_b32_e32 v10, v2
	v_mov_b32_e32 v11, v2
	v_mov_b32_e32 v12, v2
	v_mov_b32_e32 v13, v2
	v_mov_b32_e32 v18, v2
	v_mov_b32_e32 v19, v2
	v_mov_b32_e32 v20, v2
	v_mov_b32_e32 v21, v2
	v_mov_b32_e32 v26, v2
	v_mov_b32_e32 v27, v2
	v_mov_b32_e32 v28, v2
	v_mov_b32_e32 v29, v2
	v_mov_b32_e32 v36, v2
	v_mov_b32_e32 v37, v2
	v_mov_b32_e32 v38, v2
	v_mov_b32_e32 v39, v2
	v_mov_b32_e32 v44, v2
	v_mov_b32_e32 v45, v2
	v_mov_b32_e32 v46, v2
	v_mov_b32_e32 v47, v2
	v_mov_b32_e32 v52, v2
	v_mov_b32_e32 v53, v2
	v_mov_b32_e32 v54, v2
	v_mov_b32_e32 v55, v2
	v_mov_b32_e32 v14, v2
	v_mov_b32_e32 v15, v2
	v_mov_b32_e32 v16, v2
	v_mov_b32_e32 v17, v2
	v_mov_b32_e32 v22, v2
	v_mov_b32_e32 v23, v2
	v_mov_b32_e32 v24, v2
	v_mov_b32_e32 v25, v2
	v_mov_b32_e32 v30, v2
	v_mov_b32_e32 v31, v2
	v_mov_b32_e32 v32, v2
	v_mov_b32_e32 v33, v2
	v_mov_b32_e32 v40, v2
	v_mov_b32_e32 v41, v2
	v_mov_b32_e32 v42, v2
	v_mov_b32_e32 v43, v2
	v_mov_b32_e32 v48, v2
	v_mov_b32_e32 v49, v2
	v_mov_b32_e32 v50, v2
	v_mov_b32_e32 v51, v2
	v_mov_b32_e32 v56, v2
	v_mov_b32_e32 v57, v2
	v_mov_b32_e32 v58, v2
	v_mov_b32_e32 v59, v2
	v_mov_b32_e32 v60, v2
	v_mov_b32_e32 v61, v2
	v_mov_b32_e32 v62, v2
	v_mov_b32_e32 v63, v2
	v_mov_b32_e32 v64, v2
	v_mov_b32_e32 v65, v2
	v_mov_b32_e32 v66, v2
	v_mov_b32_e32 v67, v2
	v_mov_b32_e32 v68, v2
	v_mov_b32_e32 v69, v2
	v_mov_b32_e32 v70, v2
	v_mov_b32_e32 v71, v2
	v_mov_b32_e32 v72, v2
	v_mov_b32_e32 v73, v2
	v_mov_b32_e32 v74, v2
	v_mov_b32_e32 v75, v2
	v_mov_b32_e32 v76, v2
	v_mov_b32_e32 v77, v2
	v_mov_b32_e32 v78, v2
	v_mov_b32_e32 v79, v2
	v_mov_b32_e32 v84, v2
	v_mov_b32_e32 v85, v2
	v_mov_b32_e32 v86, v2
	v_mov_b32_e32 v87, v2
	v_mov_b32_e32 v92, v2
	v_mov_b32_e32 v93, v2
	v_mov_b32_e32 v94, v2
	v_mov_b32_e32 v95, v2
	v_mov_b32_e32 v100, v2
	v_mov_b32_e32 v101, v2
	v_mov_b32_e32 v102, v2
	v_mov_b32_e32 v103, v2
	v_mov_b32_e32 v108, v2
	v_mov_b32_e32 v109, v2
	v_mov_b32_e32 v110, v2
	v_mov_b32_e32 v111, v2
	v_mov_b32_e32 v116, v2
	v_mov_b32_e32 v117, v2
	v_mov_b32_e32 v118, v2
	v_mov_b32_e32 v119, v2
	v_mov_b32_e32 v80, v2
	v_mov_b32_e32 v81, v2
	v_mov_b32_e32 v82, v2
	v_mov_b32_e32 v83, v2
	v_mov_b32_e32 v88, v2
	v_mov_b32_e32 v89, v2
	v_mov_b32_e32 v90, v2
	v_mov_b32_e32 v91, v2
	v_mov_b32_e32 v96, v2
	v_mov_b32_e32 v97, v2
	v_mov_b32_e32 v98, v2
	v_mov_b32_e32 v99, v2
	v_mov_b32_e32 v104, v2
	v_mov_b32_e32 v105, v2
	v_mov_b32_e32 v106, v2
	v_mov_b32_e32 v107, v2
	v_mov_b32_e32 v112, v2
	v_mov_b32_e32 v113, v2
	v_mov_b32_e32 v114, v2
	v_mov_b32_e32 v115, v2
	v_mov_b32_e32 v120, v2
	v_mov_b32_e32 v121, v2
	v_mov_b32_e32 v122, v2
	v_mov_b32_e32 v123, v2
	v_mov_b32_e32 v124, v2
	v_mov_b32_e32 v125, v2
	v_mov_b32_e32 v126, v2
	v_mov_b32_e32 v127, v2
	v_mov_b32_e32 v128, v2
	v_mov_b32_e32 v129, v2
	v_mov_b32_e32 v130, v2
	v_mov_b32_e32 v131, v2
	s_cmp_lg_u32 s98, 0
	s_mov_b32 s98, 1
	s_cbranch_scc0 .LBB0_844
	s_add_u32 s27, s62, 0xffe00080
	s_addc_u32 s28, s63, -1
	s_add_i32 s29, 0, 0x10000
	s_cmp_eq_u32 s26, 28
	s_cselect_b32 s67, s20, s28
	s_cselect_b32 s66, s21, s27
	v_add_u32_e32 v152, s29, v154
	s_cselect_b32 s55, s22, s25
	s_cselect_b32 s54, s23, s24
	s_add_i32 s27, 0, 0x14000
	ds_read_b128 v[158:161], v152
	ds_read_b128 v[180:183], v152 offset:1024
	ds_read_b128 v[184:187], v152 offset:2048
	ds_read_b128 v[188:191], v152 offset:3072
	v_add_u32_e32 v152, s27, v154
	ds_read_b128 v[192:195], v152
	ds_read_b128 v[196:199], v152 offset:1024
	ds_read_b128 v[200:203], v152 offset:2048
	ds_read_b128 v[204:207], v152 offset:3072
	v_lshl_add_u64 v[152:153], s[62:63], 0, v[150:151]
	s_add_i32 m0, s12, 0xc000
	ds_read_b128 v[208:211], v156
	ds_read_b128 v[212:215], v156 offset:1024
	ds_read_b128 v[216:219], v156 offset:2048
	ds_read_b128 v[222:225], v156 offset:3072
	ds_read_b128 v[226:229], v156 offset:4096
	ds_read_b128 v[230:233], v156 offset:5120
	ds_read_b128 v[234:237], v156 offset:6144
	ds_read_b128 v[238:241], v156 offset:7168
	global_load_lds_dwordx4 v[152:153], off
	v_lshl_add_u64 v[152:153], s[62:63], 0, v[148:149]
	s_add_i32 m0, s12, 0xe000
	s_nop 0
	global_load_lds_dwordx4 v[152:153], off
	s_waitcnt vmcnt(24)
	s_waitcnt lgkmcnt(0)
	s_barrier
	s_setprio 1
	s_waitcnt lgkmcnt(0)
	v_mfma_f32_16x16x32_bf16 v[128:131], v[158:161], v[208:211], v[128:131]
	v_mfma_f32_16x16x32_bf16 v[128:131], v[180:183], v[212:215], v[128:131]
	v_mfma_f32_16x16x32_bf16 v[120:123], v[158:161], v[216:219], v[120:123]
	v_mfma_f32_16x16x32_bf16 v[120:123], v[180:183], v[222:225], v[120:123]
	v_mfma_f32_16x16x32_bf16 v[104:107], v[158:161], v[226:229], v[104:107]
	v_mfma_f32_16x16x32_bf16 v[104:107], v[180:183], v[230:233], v[104:107]
	v_mfma_f32_16x16x32_bf16 v[88:91], v[158:161], v[234:237], v[88:91]
	v_mfma_f32_16x16x32_bf16 v[88:91], v[180:183], v[238:241], v[88:91]
	v_mfma_f32_16x16x32_bf16 v[80:83], v[184:187], v[234:237], v[80:83]
	v_mfma_f32_16x16x32_bf16 v[80:83], v[188:191], v[238:241], v[80:83]
	v_mfma_f32_16x16x32_bf16 v[96:99], v[184:187], v[226:229], v[96:99]
	v_mfma_f32_16x16x32_bf16 v[96:99], v[188:191], v[230:233], v[96:99]
	v_mfma_f32_16x16x32_bf16 v[112:115], v[184:187], v[216:219], v[112:115]
	v_mfma_f32_16x16x32_bf16 v[112:115], v[188:191], v[222:225], v[112:115]
	v_mfma_f32_16x16x32_bf16 v[124:127], v[184:187], v[208:211], v[124:127]
	v_mfma_f32_16x16x32_bf16 v[124:127], v[188:191], v[212:215], v[124:127]
	s_setprio 0
	s_setprio 1
	v_mfma_f32_16x16x32_bf16 v[116:119], v[192:195], v[208:211], v[116:119]
	v_mfma_f32_16x16x32_bf16 v[116:119], v[196:199], v[212:215], v[116:119]
	v_mfma_f32_16x16x32_bf16 v[100:103], v[192:195], v[216:219], v[100:103]
	v_mfma_f32_16x16x32_bf16 v[100:103], v[196:199], v[222:225], v[100:103]
	v_mfma_f32_16x16x32_bf16 v[84:87], v[192:195], v[226:229], v[84:87]
	v_mfma_f32_16x16x32_bf16 v[84:87], v[196:199], v[230:233], v[84:87]
	v_mfma_f32_16x16x32_bf16 v[72:75], v[192:195], v[234:237], v[72:75]
	v_mfma_f32_16x16x32_bf16 v[72:75], v[196:199], v[238:241], v[72:75]
	v_mfma_f32_16x16x32_bf16 v[68:71], v[200:203], v[234:237], v[68:71]
	v_mfma_f32_16x16x32_bf16 v[68:71], v[204:207], v[238:241], v[68:71]
	v_mfma_f32_16x16x32_bf16 v[76:79], v[200:203], v[226:229], v[76:79]
	v_mfma_f32_16x16x32_bf16 v[76:79], v[204:207], v[230:233], v[76:79]
	v_mfma_f32_16x16x32_bf16 v[92:95], v[200:203], v[216:219], v[92:95]
	v_mfma_f32_16x16x32_bf16 v[92:95], v[204:207], v[222:225], v[92:95]
	v_mfma_f32_16x16x32_bf16 v[108:111], v[200:203], v[208:211], v[108:111]
	v_mfma_f32_16x16x32_bf16 v[108:111], v[204:207], v[212:215], v[108:111]
	s_setprio 0
	s_barrier
	s_add_i32 s28, s29, s11
	v_lshl_add_u64 v[152:153], s[54:55], 0, v[34:35]
	s_mov_b32 m0, s28
	ds_read_b128 v[208:211], v156 offset:16384
	ds_read_b128 v[212:215], v156 offset:17408
	ds_read_b128 v[216:219], v156 offset:18432
	ds_read_b128 v[222:225], v156 offset:19456
	ds_read_b128 v[226:229], v156 offset:20480
	ds_read_b128 v[230:233], v156 offset:21504
	ds_read_b128 v[234:237], v156 offset:22528
	ds_read_b128 v[238:241], v156 offset:23552
	global_load_lds_dwordx4 v[152:153], off
	s_add_i32 m0, s28, 0x2000
	s_add_u32 s28, s54, 0x80000
	v_lshl_add_u64 v[162:163], s[54:55], 0, v[146:147]
	s_addc_u32 s29, s55, 0
	s_add_i32 s27, s27, s11
	global_load_lds_dwordx4 v[162:163], off
	v_lshl_add_u64 v[242:243], s[28:29], 0, v[34:35]
	s_mov_b32 m0, s27
	v_lshl_add_u64 v[244:245], s[66:67], 0, v[144:145]
	global_load_lds_dwordx4 v[242:243], off
	v_lshl_add_u64 v[242:243], s[28:29], 0, v[146:147]
	s_add_i32 m0, s27, 0x2000
	s_nop 0
	global_load_lds_dwordx4 v[242:243], off
	v_lshl_add_u64 v[242:243], s[66:67], 0, v[142:143]
	s_mov_b32 m0, s12
	s_nop 0
	global_load_lds_dwordx4 v[242:243], off
	s_mov_b32 m0, s13
	s_nop 0
	global_load_lds_dwordx4 v[244:245], off
	s_waitcnt vmcnt(24)
	s_waitcnt lgkmcnt(0)
	s_barrier
	s_setprio 1
	s_waitcnt lgkmcnt(0)
	v_mfma_f32_16x16x32_bf16 v[64:67], v[158:161], v[208:211], v[64:67]
	v_mfma_f32_16x16x32_bf16 v[64:67], v[180:183], v[212:215], v[64:67]
	v_mfma_f32_16x16x32_bf16 v[56:59], v[158:161], v[216:219], v[56:59]
	v_mfma_f32_16x16x32_bf16 v[56:59], v[180:183], v[222:225], v[56:59]
	v_mfma_f32_16x16x32_bf16 v[40:43], v[158:161], v[226:229], v[40:43]
	v_mfma_f32_16x16x32_bf16 v[40:43], v[180:183], v[230:233], v[40:43]
	v_mfma_f32_16x16x32_bf16 v[22:25], v[158:161], v[234:237], v[22:25]
	v_mfma_f32_16x16x32_bf16 v[22:25], v[180:183], v[238:241], v[22:25]
	v_mfma_f32_16x16x32_bf16 v[14:17], v[184:187], v[234:237], v[14:17]
	v_mfma_f32_16x16x32_bf16 v[14:17], v[188:191], v[238:241], v[14:17]
	v_mfma_f32_16x16x32_bf16 v[30:33], v[184:187], v[226:229], v[30:33]
	v_mfma_f32_16x16x32_bf16 v[30:33], v[188:191], v[230:233], v[30:33]
	v_mfma_f32_16x16x32_bf16 v[48:51], v[184:187], v[216:219], v[48:51]
	v_mfma_f32_16x16x32_bf16 v[48:51], v[188:191], v[222:225], v[48:51]
	v_mfma_f32_16x16x32_bf16 v[60:63], v[184:187], v[208:211], v[60:63]
	v_mfma_f32_16x16x32_bf16 v[60:63], v[188:191], v[212:215], v[60:63]
	s_setprio 0
	s_setprio 1
	v_mfma_f32_16x16x32_bf16 v[52:55], v[192:195], v[208:211], v[52:55]
	v_mfma_f32_16x16x32_bf16 v[52:55], v[196:199], v[212:215], v[52:55]
	v_mfma_f32_16x16x32_bf16 v[36:39], v[192:195], v[216:219], v[36:39]
	v_mfma_f32_16x16x32_bf16 v[36:39], v[196:199], v[222:225], v[36:39]
	v_mfma_f32_16x16x32_bf16 v[18:21], v[192:195], v[226:229], v[18:21]
	v_mfma_f32_16x16x32_bf16 v[18:21], v[196:199], v[230:233], v[18:21]
	v_mfma_f32_16x16x32_bf16 v[6:9], v[192:195], v[234:237], v[6:9]
	v_mfma_f32_16x16x32_bf16 v[6:9], v[196:199], v[238:241], v[6:9]
	v_mfma_f32_16x16x32_bf16 v[2:5], v[200:203], v[234:237], v[2:5]
	v_mfma_f32_16x16x32_bf16 v[2:5], v[204:207], v[238:241], v[2:5]
	v_mfma_f32_16x16x32_bf16 v[10:13], v[200:203], v[226:229], v[10:13]
	v_mfma_f32_16x16x32_bf16 v[10:13], v[204:207], v[230:233], v[10:13]
	v_mfma_f32_16x16x32_bf16 v[26:29], v[200:203], v[216:219], v[26:29]
	v_mfma_f32_16x16x32_bf16 v[26:29], v[204:207], v[222:225], v[26:29]
	v_mfma_f32_16x16x32_bf16 v[44:47], v[200:203], v[208:211], v[44:47]
	v_mfma_f32_16x16x32_bf16 v[44:47], v[204:207], v[212:215], v[44:47]
	s_setprio 0
	s_barrier
	s_add_i32 s27, 0, 0x18000
	v_add_u32_e32 v157, s27, v154
	s_add_i32 s30, 0, 0x1c000
	ds_read_b128 v[158:161], v157
	ds_read_b128 v[180:183], v157 offset:1024
	ds_read_b128 v[184:187], v157 offset:2048
	ds_read_b128 v[188:191], v157 offset:3072
	v_add_u32_e32 v157, s30, v154
	ds_read_b128 v[192:195], v157
	ds_read_b128 v[196:199], v157 offset:1024
	ds_read_b128 v[200:203], v157 offset:2048
	ds_read_b128 v[204:207], v157 offset:3072
	s_add_u32 s28, s66, 0x200000
	s_addc_u32 s29, s67, 0
	s_mov_b32 m0, s14
	v_lshl_add_u64 v[246:247], s[28:29], 0, v[142:143]
	ds_read_b128 v[208:211], v156 offset:32768
	ds_read_b128 v[212:215], v156 offset:33792
	ds_read_b128 v[216:219], v156 offset:34816
	ds_read_b128 v[222:225], v156 offset:35840
	ds_read_b128 v[226:229], v156 offset:36864
	ds_read_b128 v[230:233], v156 offset:37888
	ds_read_b128 v[234:237], v156 offset:38912
	ds_read_b128 v[238:241], v156 offset:39936
	global_load_lds_dwordx4 v[246:247], off
	v_lshl_add_u64 v[246:247], s[28:29], 0, v[144:145]
	s_mov_b32 m0, s15
	s_nop 0
	global_load_lds_dwordx4 v[246:247], off
	s_waitcnt vmcnt(8)
	s_waitcnt lgkmcnt(0)
	s_barrier
	s_setprio 1
	s_waitcnt lgkmcnt(0)
	v_mfma_f32_16x16x32_bf16 v[128:131], v[158:161], v[208:211], v[128:131]
	v_mfma_f32_16x16x32_bf16 v[128:131], v[180:183], v[212:215], v[128:131]
	v_mfma_f32_16x16x32_bf16 v[120:123], v[158:161], v[216:219], v[120:123]
	v_mfma_f32_16x16x32_bf16 v[120:123], v[180:183], v[222:225], v[120:123]
	v_mfma_f32_16x16x32_bf16 v[104:107], v[158:161], v[226:229], v[104:107]
	v_mfma_f32_16x16x32_bf16 v[104:107], v[180:183], v[230:233], v[104:107]
	v_mfma_f32_16x16x32_bf16 v[88:91], v[158:161], v[234:237], v[88:91]
	v_mfma_f32_16x16x32_bf16 v[88:91], v[180:183], v[238:241], v[88:91]
	v_mfma_f32_16x16x32_bf16 v[80:83], v[184:187], v[234:237], v[80:83]
	v_mfma_f32_16x16x32_bf16 v[80:83], v[188:191], v[238:241], v[80:83]
	v_mfma_f32_16x16x32_bf16 v[96:99], v[184:187], v[226:229], v[96:99]
	v_mfma_f32_16x16x32_bf16 v[96:99], v[188:191], v[230:233], v[96:99]
	v_mfma_f32_16x16x32_bf16 v[112:115], v[184:187], v[216:219], v[112:115]
	v_mfma_f32_16x16x32_bf16 v[112:115], v[188:191], v[222:225], v[112:115]
	v_mfma_f32_16x16x32_bf16 v[124:127], v[184:187], v[208:211], v[124:127]
	v_mfma_f32_16x16x32_bf16 v[124:127], v[188:191], v[212:215], v[124:127]
	s_setprio 0
	s_setprio 1
	v_mfma_f32_16x16x32_bf16 v[116:119], v[192:195], v[208:211], v[116:119]
	v_mfma_f32_16x16x32_bf16 v[116:119], v[196:199], v[212:215], v[116:119]
	v_mfma_f32_16x16x32_bf16 v[100:103], v[192:195], v[216:219], v[100:103]
	v_mfma_f32_16x16x32_bf16 v[100:103], v[196:199], v[222:225], v[100:103]
	v_mfma_f32_16x16x32_bf16 v[84:87], v[192:195], v[226:229], v[84:87]
	v_mfma_f32_16x16x32_bf16 v[84:87], v[196:199], v[230:233], v[84:87]
	v_mfma_f32_16x16x32_bf16 v[72:75], v[192:195], v[234:237], v[72:75]
	v_mfma_f32_16x16x32_bf16 v[72:75], v[196:199], v[238:241], v[72:75]
	v_mfma_f32_16x16x32_bf16 v[68:71], v[200:203], v[234:237], v[68:71]
	v_mfma_f32_16x16x32_bf16 v[68:71], v[204:207], v[238:241], v[68:71]
	v_mfma_f32_16x16x32_bf16 v[76:79], v[200:203], v[226:229], v[76:79]
	v_mfma_f32_16x16x32_bf16 v[76:79], v[204:207], v[230:233], v[76:79]
	v_mfma_f32_16x16x32_bf16 v[92:95], v[200:203], v[216:219], v[92:95]
	v_mfma_f32_16x16x32_bf16 v[92:95], v[204:207], v[222:225], v[92:95]
	v_mfma_f32_16x16x32_bf16 v[108:111], v[200:203], v[208:211], v[108:111]
	v_mfma_f32_16x16x32_bf16 v[108:111], v[204:207], v[212:215], v[108:111]
	s_setprio 0
	s_barrier
	s_add_i32 s27, s27, s11
	v_lshl_add_u64 v[152:153], v[152:153], 0, s[78:79]
	s_mov_b32 m0, s27
	ds_read_b128 v[208:211], v156 offset:49152
	ds_read_b128 v[212:215], v156 offset:50176
	ds_read_b128 v[216:219], v156 offset:51200
	ds_read_b128 v[222:225], v156 offset:52224
	ds_read_b128 v[226:229], v156 offset:53248
	ds_read_b128 v[230:233], v156 offset:54272
	ds_read_b128 v[234:237], v156 offset:55296
	ds_read_b128 v[238:241], v156 offset:56320
	global_load_lds_dwordx4 v[152:153], off
	s_add_i32 m0, s27, 0x2000
	s_add_u32 s28, s54, 0x80080
	v_lshl_add_u64 v[152:153], v[162:163], 0, s[78:79]
	s_addc_u32 s29, s55, 0
	s_add_i32 s27, s30, s11
	global_load_lds_dwordx4 v[152:153], off
	v_lshl_add_u64 v[152:153], s[28:29], 0, v[34:35]
	s_mov_b32 m0, s27
	s_nop 0
	global_load_lds_dwordx4 v[152:153], off
	v_lshl_add_u64 v[152:153], s[28:29], 0, v[146:147]
	s_add_i32 m0, s27, 0x2000
	s_nop 0
	global_load_lds_dwordx4 v[152:153], off
	v_lshl_add_u64 v[152:153], v[242:243], 0, s[78:79]
	s_mov_b32 m0, s16
	s_nop 0
	global_load_lds_dwordx4 v[152:153], off
	v_lshl_add_u64 v[152:153], v[244:245], 0, s[78:79]
	s_mov_b32 m0, s17
	s_nop 0
	global_load_lds_dwordx4 v[152:153], off
	s_waitcnt vmcnt(8)
	s_waitcnt lgkmcnt(0)
	s_barrier
	s_setprio 1
	s_waitcnt lgkmcnt(0)
	v_mfma_f32_16x16x32_bf16 v[64:67], v[158:161], v[208:211], v[64:67]
	v_mfma_f32_16x16x32_bf16 v[64:67], v[180:183], v[212:215], v[64:67]
	v_mfma_f32_16x16x32_bf16 v[56:59], v[158:161], v[216:219], v[56:59]
	v_mfma_f32_16x16x32_bf16 v[56:59], v[180:183], v[222:225], v[56:59]
	v_mfma_f32_16x16x32_bf16 v[40:43], v[158:161], v[226:229], v[40:43]
	v_mfma_f32_16x16x32_bf16 v[40:43], v[180:183], v[230:233], v[40:43]
	v_mfma_f32_16x16x32_bf16 v[22:25], v[158:161], v[234:237], v[22:25]
	v_mfma_f32_16x16x32_bf16 v[22:25], v[180:183], v[238:241], v[22:25]
	v_mfma_f32_16x16x32_bf16 v[14:17], v[184:187], v[234:237], v[14:17]
	v_mfma_f32_16x16x32_bf16 v[14:17], v[188:191], v[238:241], v[14:17]
	v_mfma_f32_16x16x32_bf16 v[30:33], v[184:187], v[226:229], v[30:33]
	v_mfma_f32_16x16x32_bf16 v[30:33], v[188:191], v[230:233], v[30:33]
	v_mfma_f32_16x16x32_bf16 v[48:51], v[184:187], v[216:219], v[48:51]
	v_mfma_f32_16x16x32_bf16 v[48:51], v[188:191], v[222:225], v[48:51]
	v_mfma_f32_16x16x32_bf16 v[60:63], v[184:187], v[208:211], v[60:63]
	v_mfma_f32_16x16x32_bf16 v[60:63], v[188:191], v[212:215], v[60:63]
	s_setprio 0
	s_setprio 1
	v_mfma_f32_16x16x32_bf16 v[52:55], v[192:195], v[208:211], v[52:55]
	v_mfma_f32_16x16x32_bf16 v[52:55], v[196:199], v[212:215], v[52:55]
	v_mfma_f32_16x16x32_bf16 v[36:39], v[192:195], v[216:219], v[36:39]
	v_mfma_f32_16x16x32_bf16 v[36:39], v[196:199], v[222:225], v[36:39]
	v_mfma_f32_16x16x32_bf16 v[18:21], v[192:195], v[226:229], v[18:21]
	v_mfma_f32_16x16x32_bf16 v[18:21], v[196:199], v[230:233], v[18:21]
	v_mfma_f32_16x16x32_bf16 v[6:9], v[192:195], v[234:237], v[6:9]
	v_mfma_f32_16x16x32_bf16 v[6:9], v[196:199], v[238:241], v[6:9]
	v_mfma_f32_16x16x32_bf16 v[2:5], v[200:203], v[234:237], v[2:5]
	v_mfma_f32_16x16x32_bf16 v[2:5], v[204:207], v[238:241], v[2:5]
	v_mfma_f32_16x16x32_bf16 v[10:13], v[200:203], v[226:229], v[10:13]
	v_mfma_f32_16x16x32_bf16 v[10:13], v[204:207], v[230:233], v[10:13]
	v_mfma_f32_16x16x32_bf16 v[26:29], v[200:203], v[216:219], v[26:29]
	v_mfma_f32_16x16x32_bf16 v[26:29], v[204:207], v[222:225], v[26:29]
	v_mfma_f32_16x16x32_bf16 v[44:47], v[200:203], v[208:211], v[44:47]
	v_mfma_f32_16x16x32_bf16 v[44:47], v[204:207], v[212:215], v[44:47]
	s_setprio 0
	s_barrier
	s_add_i32 s26, s26, 2
	s_add_u32 s24, s24, 0x100
	s_addc_u32 s25, s25, 0
	s_add_u32 s62, s62, 0x100
	s_addc_u32 s63, s63, 0
	s_branch .LBB0_844

.LBB0_975:
	s_waitcnt vmcnt(0)
	v_lshrrev_b32_e32 v18, 1, v16
	v_and_b32_e32 v18, 24, v18
	s_add_u32 s44, s36, 0x1dc00000
	v_and_b32_e32 v17, 15, v16
	v_lshlrev_b32_e32 v19, 1, v18
	v_lshlrev_b32_e32 v16, 2, v16
	s_addc_u32 s45, s37, 0
	v_lshl_or_b32 v137, s16, 6, v17
	v_lshl_or_b32 v17, v17, 6, v19
	s_lshl_b32 s16, s16, 13
	v_and_b32_e32 v16, 32, v16
	v_bitop3_b32 v19, v17, s16, v16 bitop3:0xde
	s_lshl_b32 s16, s17, 5
	s_and_b32 s22, s16, 0x60
	s_lshl_b32 s16, s22, 7
	s_add_i32 m0, s12, 0x18000
	v_lshl_add_u64 v[8:9], v[8:9], 0, s[78:79]
	v_bitop3_b32 v154, v17, s16, v16 bitop3:0xde
	s_waitcnt vmcnt(2)
	s_barrier
	global_load_lds_dwordx4 v[8:9], off
	v_lshl_add_u64 v[6:7], v[6:7], 0, s[78:79]
	s_add_i32 m0, s12, 0x1a000
	s_add_i32 s16, s12, 0x8000
	s_add_i32 s17, s12, 0xa000
	global_load_lds_dwordx4 v[6:7], off
	v_lshl_add_u64 v[2:3], v[2:3], 0, s[78:79]
	s_mov_b32 m0, s16
	s_add_u32 s20, s54, 0x80080
	global_load_lds_dwordx4 v[2:3], off
	v_lshl_add_u64 v[2:3], v[4:5], 0, s[78:79]
	s_mov_b32 m0, s17
	s_addc_u32 s21, s55, 0
	global_load_lds_dwordx4 v[2:3], off
	s_add_i32 m0, s12, 0x1c000
	v_lshl_add_u64 v[2:3], s[20:21], 0, v[34:35]
	global_load_lds_dwordx4 v[2:3], off
	v_lshl_add_u64 v[2:3], s[20:21], 0, v[146:147]
	s_add_i32 m0, s12, 0x1e000
	s_cmpk_lt_u32 s18, 0x100
	global_load_lds_dwordx4 v[2:3], off
	v_lshlrev_b32_e32 v2, 15, v13
	v_and_b32_e32 v2, 0xffff0000, v2
	v_lshl_add_u32 v2, v14, 12, v2
	v_and_b32_e32 v3, 1, v13
	v_lshl_or_b32 v2, v3, 6, v2
	v_lshl_add_u32 v148, v15, 1, v2
	v_lshlrev_b32_e32 v2, 15, v10
	v_and_b32_e32 v2, 0xffff0000, v2
	s_waitcnt vmcnt(6)
	v_lshl_add_u32 v2, v11, 12, v2
	v_and_b32_e32 v3, 1, v10
	v_lshl_or_b32 v2, v3, 6, v2
	s_sext_i32_i16 s19, s40
	s_cselect_b64 s[36:37], -1, 0
	v_or_b32_e32 v155, s22, v18
	v_mov_b32_e32 v149, v35
	v_lshl_add_u32 v150, v12, 1, v2
	v_mov_b32_e32 v151, v35
	s_mov_b32 s18, 0
	v_add_u32_e32 v156, 0, v19
	s_barrier
	s_mov_b32 s98, 0
	s_branch .LBB0_978

.LBB0_978:
	s_add_i32 s18, s18, 1
	s_mul_i32 s20, s18, s2
	s_mul_hi_u32 s21, s18, s33
	s_add_i32 s21, s21, s20
	s_mul_i32 s20, s18, s33
	s_add_u32 s52, s20, s5
	s_addc_u32 s53, s21, s6
	v_cmp_gt_i64_e32 vcc, s[52:53], v[134:135]
	v_cmp_lt_i64_e64 s[40:41], s[52:53], v[132:133]
	s_cbranch_vccnz .LBB0_984
	s_and_b32 s21, s52, 7
	s_lshr_b32 s20, s52, 3
	s_lshl_b32 s21, s21, 9
	s_add_i32 s20, s20, s21
	s_lshr_b32 s22, s20, 8
	s_lshl_b32 s22, s22, 3
	s_and_b32 s20, s20, 0xff
	s_lshr_b32 s46, s20, 3
	s_and_b32 s20, s20, 7
	s_add_i32 s48, s22, s20
.LBB0_984:
	s_ashr_i32 s49, s48, 31
	s_lshl_b64 s[20:21], s[48:49], 20
	s_add_u32 s52, s7, s20
	s_addc_u32 s53, s8, s21
	s_and_b64 s[20:21], s[40:41], exec
	s_cselect_b32 s20, s53, s63
	s_cselect_b32 s21, s52, s62
	s_ashr_i32 s47, s46, 31
	s_lshl_b64 s[22:23], s[46:47], 20
	s_add_u32 s56, s9, s22
	s_addc_u32 s57, s10, s23
	s_and_b64 s[22:23], s[40:41], exec
	s_cselect_b32 s22, s57, s55
	s_cselect_b32 s23, s56, s54
	s_add_u32 s24, s54, 0x100
	s_addc_u32 s25, s55, 0
	s_add_u32 s62, s62, 0x80080
	v_mov_b32_e32 v2, 0
	s_addc_u32 s63, s63, 0
	s_mov_b32 s26, -2
	v_mov_b32_e32 v3, v2
	v_mov_b32_e32 v4, v2
	v_mov_b32_e32 v5, v2
	v_mov_b32_e32 v6, v2
	v_mov_b32_e32 v7, v2
	v_mov_b32_e32 v8, v2
	v_mov_b32_e32 v9, v2
	v_mov_b32_e32 v18, v2
	v_mov_b32_e32 v19, v2
	v_mov_b32_e32 v20, v2
	v_mov_b32_e32 v21, v2
	v_mov_b32_e32 v22, v2
	v_mov_b32_e32 v23, v2
	v_mov_b32_e32 v24, v2
	v_mov_b32_e32 v25, v2
	v_mov_b32_e32 v36, v2
	v_mov_b32_e32 v37, v2
	v_mov_b32_e32 v38, v2
	v_mov_b32_e32 v39, v2
	v_mov_b32_e32 v40, v2
	v_mov_b32_e32 v41, v2
	v_mov_b32_e32 v42, v2
	v_mov_b32_e32 v43, v2
	v_mov_b32_e32 v52, v2
	v_mov_b32_e32 v53, v2
	v_mov_b32_e32 v54, v2
	v_mov_b32_e32 v55, v2
	v_mov_b32_e32 v56, v2
	v_mov_b32_e32 v57, v2
	v_mov_b32_e32 v58, v2
	v_mov_b32_e32 v59, v2
	v_mov_b32_e32 v10, v2
	v_mov_b32_e32 v11, v2
	v_mov_b32_e32 v12, v2
	v_mov_b32_e32 v13, v2
	v_mov_b32_e32 v14, v2
	v_mov_b32_e32 v15, v2
	v_mov_b32_e32 v16, v2
	v_mov_b32_e32 v17, v2
	v_mov_b32_e32 v26, v2
	v_mov_b32_e32 v27, v2
	v_mov_b32_e32 v28, v2
	v_mov_b32_e32 v29, v2
	v_mov_b32_e32 v30, v2
	v_mov_b32_e32 v31, v2
	v_mov_b32_e32 v32, v2
	v_mov_b32_e32 v33, v2
	v_mov_b32_e32 v44, v2
	v_mov_b32_e32 v45, v2
	v_mov_b32_e32 v46, v2
	v_mov_b32_e32 v47, v2
	v_mov_b32_e32 v48, v2
	v_mov_b32_e32 v49, v2
	v_mov_b32_e32 v50, v2
	v_mov_b32_e32 v51, v2
	v_mov_b32_e32 v60, v2
	v_mov_b32_e32 v61, v2
	v_mov_b32_e32 v62, v2
	v_mov_b32_e32 v63, v2
	v_mov_b32_e32 v64, v2
	v_mov_b32_e32 v65, v2
	v_mov_b32_e32 v66, v2
	v_mov_b32_e32 v67, v2
	v_mov_b32_e32 v68, v2
	v_mov_b32_e32 v69, v2
	v_mov_b32_e32 v70, v2
	v_mov_b32_e32 v71, v2
	v_mov_b32_e32 v72, v2
	v_mov_b32_e32 v73, v2
	v_mov_b32_e32 v74, v2
	v_mov_b32_e32 v75, v2
	v_mov_b32_e32 v84, v2
	v_mov_b32_e32 v85, v2
	v_mov_b32_e32 v86, v2
	v_mov_b32_e32 v87, v2
	v_mov_b32_e32 v88, v2
	v_mov_b32_e32 v89, v2
	v_mov_b32_e32 v90, v2
	v_mov_b32_e32 v91, v2
	v_mov_b32_e32 v100, v2
	v_mov_b32_e32 v101, v2
	v_mov_b32_e32 v102, v2
	v_mov_b32_e32 v103, v2
	v_mov_b32_e32 v104, v2
	v_mov_b32_e32 v105, v2
	v_mov_b32_e32 v106, v2
	v_mov_b32_e32 v107, v2
	v_mov_b32_e32 v116, v2
	v_mov_b32_e32 v117, v2
	v_mov_b32_e32 v118, v2
	v_mov_b32_e32 v119, v2
	v_mov_b32_e32 v120, v2
	v_mov_b32_e32 v121, v2
	v_mov_b32_e32 v122, v2
	v_mov_b32_e32 v123, v2
	v_mov_b32_e32 v76, v2
	v_mov_b32_e32 v77, v2
	v_mov_b32_e32 v78, v2
	v_mov_b32_e32 v79, v2
	v_mov_b32_e32 v80, v2
	v_mov_b32_e32 v81, v2
	v_mov_b32_e32 v82, v2
	v_mov_b32_e32 v83, v2
	v_mov_b32_e32 v92, v2
	v_mov_b32_e32 v93, v2
	v_mov_b32_e32 v94, v2
	v_mov_b32_e32 v95, v2
	v_mov_b32_e32 v96, v2
	v_mov_b32_e32 v97, v2
	v_mov_b32_e32 v98, v2
	v_mov_b32_e32 v99, v2
	v_mov_b32_e32 v108, v2
	v_mov_b32_e32 v109, v2
	v_mov_b32_e32 v110, v2
	v_mov_b32_e32 v111, v2
	v_mov_b32_e32 v112, v2
	v_mov_b32_e32 v113, v2
	v_mov_b32_e32 v114, v2
	v_mov_b32_e32 v115, v2
	v_mov_b32_e32 v124, v2
	v_mov_b32_e32 v125, v2
	v_mov_b32_e32 v126, v2
	v_mov_b32_e32 v127, v2
	v_mov_b32_e32 v128, v2
	v_mov_b32_e32 v129, v2
	v_mov_b32_e32 v130, v2
	v_mov_b32_e32 v131, v2
	s_cmp_lg_u32 s98, 0
	s_mov_b32 s98, 1
	s_cbranch_scc0 .LBB0_985
	s_add_u32 s27, s62, 0xfff80080
	s_addc_u32 s28, s63, -1
	s_add_i32 s29, 0, 0x10000
	s_cmp_eq_u32 s26, 28
	s_cselect_b32 s67, s20, s28
	s_cselect_b32 s66, s21, s27
	v_add_u32_e32 v152, s29, v154
	s_cselect_b32 s55, s22, s25
	s_cselect_b32 s54, s23, s24
	s_add_i32 s27, 0, 0x14000
	ds_read_b128 v[158:161], v152
	ds_read_b128 v[180:183], v152 offset:1024
	ds_read_b128 v[184:187], v152 offset:2048
	ds_read_b128 v[188:191], v152 offset:3072
	v_add_u32_e32 v152, s27, v154
	ds_read_b128 v[192:195], v152
	ds_read_b128 v[196:199], v152 offset:1024
	ds_read_b128 v[200:203], v152 offset:2048
	ds_read_b128 v[204:207], v152 offset:3072
	v_lshl_add_u64 v[152:153], s[62:63], 0, v[150:151]
	s_add_i32 m0, s12, 0xc000
	ds_read_b128 v[208:211], v156
	ds_read_b128 v[212:215], v156 offset:1024
	ds_read_b128 v[216:219], v156 offset:2048
	ds_read_b128 v[222:225], v156 offset:3072
	ds_read_b128 v[226:229], v156 offset:4096
	ds_read_b128 v[230:233], v156 offset:5120
	ds_read_b128 v[234:237], v156 offset:6144
	ds_read_b128 v[238:241], v156 offset:7168
	global_load_lds_dwordx4 v[152:153], off
	v_lshl_add_u64 v[152:153], s[62:63], 0, v[148:149]
	s_add_i32 m0, s12, 0xe000
	s_nop 0
	global_load_lds_dwordx4 v[152:153], off
	s_waitcnt vmcnt(24)
	s_waitcnt lgkmcnt(0)
	s_barrier
	s_setprio 1
	s_waitcnt lgkmcnt(0)
	v_mfma_f32_16x16x32_bf16 v[128:131], v[158:161], v[208:211], v[128:131]
	v_mfma_f32_16x16x32_bf16 v[128:131], v[180:183], v[212:215], v[128:131]
	v_mfma_f32_16x16x32_bf16 v[112:115], v[158:161], v[216:219], v[112:115]
	v_mfma_f32_16x16x32_bf16 v[112:115], v[180:183], v[222:225], v[112:115]
	v_mfma_f32_16x16x32_bf16 v[96:99], v[158:161], v[226:229], v[96:99]
	v_mfma_f32_16x16x32_bf16 v[96:99], v[180:183], v[230:233], v[96:99]
	v_mfma_f32_16x16x32_bf16 v[80:83], v[158:161], v[234:237], v[80:83]
	v_mfma_f32_16x16x32_bf16 v[80:83], v[180:183], v[238:241], v[80:83]
	v_mfma_f32_16x16x32_bf16 v[76:79], v[184:187], v[234:237], v[76:79]
	v_mfma_f32_16x16x32_bf16 v[76:79], v[188:191], v[238:241], v[76:79]
	v_mfma_f32_16x16x32_bf16 v[92:95], v[184:187], v[226:229], v[92:95]
	v_mfma_f32_16x16x32_bf16 v[92:95], v[188:191], v[230:233], v[92:95]
	v_mfma_f32_16x16x32_bf16 v[108:111], v[184:187], v[216:219], v[108:111]
	v_mfma_f32_16x16x32_bf16 v[108:111], v[188:191], v[222:225], v[108:111]
	v_mfma_f32_16x16x32_bf16 v[124:127], v[184:187], v[208:211], v[124:127]
	v_mfma_f32_16x16x32_bf16 v[124:127], v[188:191], v[212:215], v[124:127]
	s_setprio 0
	s_setprio 1
	v_mfma_f32_16x16x32_bf16 v[120:123], v[192:195], v[208:211], v[120:123]
	v_mfma_f32_16x16x32_bf16 v[120:123], v[196:199], v[212:215], v[120:123]
	v_mfma_f32_16x16x32_bf16 v[104:107], v[192:195], v[216:219], v[104:107]
	v_mfma_f32_16x16x32_bf16 v[104:107], v[196:199], v[222:225], v[104:107]
	v_mfma_f32_16x16x32_bf16 v[88:91], v[192:195], v[226:229], v[88:91]
	v_mfma_f32_16x16x32_bf16 v[88:91], v[196:199], v[230:233], v[88:91]
	v_mfma_f32_16x16x32_bf16 v[72:75], v[192:195], v[234:237], v[72:75]
	v_mfma_f32_16x16x32_bf16 v[72:75], v[196:199], v[238:241], v[72:75]
	v_mfma_f32_16x16x32_bf16 v[68:71], v[200:203], v[234:237], v[68:71]
	v_mfma_f32_16x16x32_bf16 v[68:71], v[204:207], v[238:241], v[68:71]
	v_mfma_f32_16x16x32_bf16 v[84:87], v[200:203], v[226:229], v[84:87]
	v_mfma_f32_16x16x32_bf16 v[84:87], v[204:207], v[230:233], v[84:87]
	v_mfma_f32_16x16x32_bf16 v[100:103], v[200:203], v[216:219], v[100:103]
	v_mfma_f32_16x16x32_bf16 v[100:103], v[204:207], v[222:225], v[100:103]
	v_mfma_f32_16x16x32_bf16 v[116:119], v[200:203], v[208:211], v[116:119]
	v_mfma_f32_16x16x32_bf16 v[116:119], v[204:207], v[212:215], v[116:119]
	s_setprio 0
	s_barrier
	s_add_i32 s28, s29, s11
	v_lshl_add_u64 v[152:153], s[54:55], 0, v[34:35]
	s_mov_b32 m0, s28
	ds_read_b128 v[208:211], v156 offset:16384
	ds_read_b128 v[212:215], v156 offset:17408
	ds_read_b128 v[216:219], v156 offset:18432
	ds_read_b128 v[222:225], v156 offset:19456
	ds_read_b128 v[226:229], v156 offset:20480
	ds_read_b128 v[230:233], v156 offset:21504
	ds_read_b128 v[234:237], v156 offset:22528
	ds_read_b128 v[238:241], v156 offset:23552
	global_load_lds_dwordx4 v[152:153], off
	s_add_i32 m0, s28, 0x2000
	s_add_u32 s28, s54, 0x80000
	v_lshl_add_u64 v[162:163], s[54:55], 0, v[146:147]
	s_addc_u32 s29, s55, 0
	s_add_i32 s27, s27, s11
	global_load_lds_dwordx4 v[162:163], off
	v_lshl_add_u64 v[242:243], s[28:29], 0, v[34:35]
	s_mov_b32 m0, s27
	v_lshl_add_u64 v[244:245], s[66:67], 0, v[144:145]
	global_load_lds_dwordx4 v[242:243], off
	v_lshl_add_u64 v[242:243], s[28:29], 0, v[146:147]
	s_add_i32 m0, s27, 0x2000
	s_nop 0
	global_load_lds_dwordx4 v[242:243], off
	v_lshl_add_u64 v[242:243], s[66:67], 0, v[142:143]
	s_mov_b32 m0, s12
	s_nop 0
	global_load_lds_dwordx4 v[242:243], off
	s_mov_b32 m0, s13
	s_nop 0
	global_load_lds_dwordx4 v[244:245], off
	s_waitcnt vmcnt(24)
	s_waitcnt lgkmcnt(0)
	s_barrier
	s_setprio 1
	s_waitcnt lgkmcnt(0)
	v_mfma_f32_16x16x32_bf16 v[64:67], v[158:161], v[208:211], v[64:67]
	v_mfma_f32_16x16x32_bf16 v[64:67], v[180:183], v[212:215], v[64:67]
	v_mfma_f32_16x16x32_bf16 v[48:51], v[158:161], v[216:219], v[48:51]
	v_mfma_f32_16x16x32_bf16 v[48:51], v[180:183], v[222:225], v[48:51]
	v_mfma_f32_16x16x32_bf16 v[30:33], v[158:161], v[226:229], v[30:33]
	v_mfma_f32_16x16x32_bf16 v[30:33], v[180:183], v[230:233], v[30:33]
	v_mfma_f32_16x16x32_bf16 v[14:17], v[158:161], v[234:237], v[14:17]
	v_mfma_f32_16x16x32_bf16 v[14:17], v[180:183], v[238:241], v[14:17]
	v_mfma_f32_16x16x32_bf16 v[10:13], v[184:187], v[234:237], v[10:13]
	v_mfma_f32_16x16x32_bf16 v[10:13], v[188:191], v[238:241], v[10:13]
	v_mfma_f32_16x16x32_bf16 v[26:29], v[184:187], v[226:229], v[26:29]
	v_mfma_f32_16x16x32_bf16 v[26:29], v[188:191], v[230:233], v[26:29]
	v_mfma_f32_16x16x32_bf16 v[44:47], v[184:187], v[216:219], v[44:47]
	v_mfma_f32_16x16x32_bf16 v[44:47], v[188:191], v[222:225], v[44:47]
	v_mfma_f32_16x16x32_bf16 v[60:63], v[184:187], v[208:211], v[60:63]
	v_mfma_f32_16x16x32_bf16 v[60:63], v[188:191], v[212:215], v[60:63]
	s_setprio 0
	s_setprio 1
	v_mfma_f32_16x16x32_bf16 v[56:59], v[192:195], v[208:211], v[56:59]
	v_mfma_f32_16x16x32_bf16 v[56:59], v[196:199], v[212:215], v[56:59]
	v_mfma_f32_16x16x32_bf16 v[40:43], v[192:195], v[216:219], v[40:43]
	v_mfma_f32_16x16x32_bf16 v[40:43], v[196:199], v[222:225], v[40:43]
	v_mfma_f32_16x16x32_bf16 v[22:25], v[192:195], v[226:229], v[22:25]
	v_mfma_f32_16x16x32_bf16 v[22:25], v[196:199], v[230:233], v[22:25]
	v_mfma_f32_16x16x32_bf16 v[6:9], v[192:195], v[234:237], v[6:9]
	v_mfma_f32_16x16x32_bf16 v[6:9], v[196:199], v[238:241], v[6:9]
	v_mfma_f32_16x16x32_bf16 v[2:5], v[200:203], v[234:237], v[2:5]
	v_mfma_f32_16x16x32_bf16 v[2:5], v[204:207], v[238:241], v[2:5]
	v_mfma_f32_16x16x32_bf16 v[18:21], v[200:203], v[226:229], v[18:21]
	v_mfma_f32_16x16x32_bf16 v[18:21], v[204:207], v[230:233], v[18:21]
	v_mfma_f32_16x16x32_bf16 v[36:39], v[200:203], v[216:219], v[36:39]
	v_mfma_f32_16x16x32_bf16 v[36:39], v[204:207], v[222:225], v[36:39]
	v_mfma_f32_16x16x32_bf16 v[52:55], v[200:203], v[208:211], v[52:55]
	v_mfma_f32_16x16x32_bf16 v[52:55], v[204:207], v[212:215], v[52:55]
	s_setprio 0
	s_barrier
	s_add_i32 s27, 0, 0x18000
	v_add_u32_e32 v157, s27, v154
	s_add_i32 s30, 0, 0x1c000
	ds_read_b128 v[158:161], v157
	ds_read_b128 v[180:183], v157 offset:1024
	ds_read_b128 v[184:187], v157 offset:2048
	ds_read_b128 v[188:191], v157 offset:3072
	v_add_u32_e32 v157, s30, v154
	ds_read_b128 v[192:195], v157
	ds_read_b128 v[196:199], v157 offset:1024
	ds_read_b128 v[200:203], v157 offset:2048
	ds_read_b128 v[204:207], v157 offset:3072
	s_add_u32 s28, s66, 0x80000
	s_addc_u32 s29, s67, 0
	s_mov_b32 m0, s14
	v_lshl_add_u64 v[246:247], s[28:29], 0, v[142:143]
	ds_read_b128 v[208:211], v156 offset:32768
	ds_read_b128 v[212:215], v156 offset:33792
	ds_read_b128 v[216:219], v156 offset:34816
	ds_read_b128 v[222:225], v156 offset:35840
	ds_read_b128 v[226:229], v156 offset:36864
	ds_read_b128 v[230:233], v156 offset:37888
	ds_read_b128 v[234:237], v156 offset:38912
	ds_read_b128 v[238:241], v156 offset:39936
	global_load_lds_dwordx4 v[246:247], off
	v_lshl_add_u64 v[246:247], s[28:29], 0, v[144:145]
	s_mov_b32 m0, s15
	s_nop 0
	global_load_lds_dwordx4 v[246:247], off
	s_waitcnt vmcnt(8)
	s_waitcnt lgkmcnt(0)
	s_barrier
	s_setprio 1
	s_waitcnt lgkmcnt(0)
	v_mfma_f32_16x16x32_bf16 v[128:131], v[158:161], v[208:211], v[128:131]
	v_mfma_f32_16x16x32_bf16 v[128:131], v[180:183], v[212:215], v[128:131]
	v_mfma_f32_16x16x32_bf16 v[112:115], v[158:161], v[216:219], v[112:115]
	v_mfma_f32_16x16x32_bf16 v[112:115], v[180:183], v[222:225], v[112:115]
	v_mfma_f32_16x16x32_bf16 v[96:99], v[158:161], v[226:229], v[96:99]
	v_mfma_f32_16x16x32_bf16 v[96:99], v[180:183], v[230:233], v[96:99]
	v_mfma_f32_16x16x32_bf16 v[80:83], v[158:161], v[234:237], v[80:83]
	v_mfma_f32_16x16x32_bf16 v[80:83], v[180:183], v[238:241], v[80:83]
	v_mfma_f32_16x16x32_bf16 v[76:79], v[184:187], v[234:237], v[76:79]
	v_mfma_f32_16x16x32_bf16 v[76:79], v[188:191], v[238:241], v[76:79]
	v_mfma_f32_16x16x32_bf16 v[92:95], v[184:187], v[226:229], v[92:95]
	v_mfma_f32_16x16x32_bf16 v[92:95], v[188:191], v[230:233], v[92:95]
	v_mfma_f32_16x16x32_bf16 v[108:111], v[184:187], v[216:219], v[108:111]
	v_mfma_f32_16x16x32_bf16 v[108:111], v[188:191], v[222:225], v[108:111]
	v_mfma_f32_16x16x32_bf16 v[124:127], v[184:187], v[208:211], v[124:127]
	v_mfma_f32_16x16x32_bf16 v[124:127], v[188:191], v[212:215], v[124:127]
	s_setprio 0
	s_setprio 1
	v_mfma_f32_16x16x32_bf16 v[120:123], v[192:195], v[208:211], v[120:123]
	v_mfma_f32_16x16x32_bf16 v[120:123], v[196:199], v[212:215], v[120:123]
	v_mfma_f32_16x16x32_bf16 v[104:107], v[192:195], v[216:219], v[104:107]
	v_mfma_f32_16x16x32_bf16 v[104:107], v[196:199], v[222:225], v[104:107]
	v_mfma_f32_16x16x32_bf16 v[88:91], v[192:195], v[226:229], v[88:91]
	v_mfma_f32_16x16x32_bf16 v[88:91], v[196:199], v[230:233], v[88:91]
	v_mfma_f32_16x16x32_bf16 v[72:75], v[192:195], v[234:237], v[72:75]
	v_mfma_f32_16x16x32_bf16 v[72:75], v[196:199], v[238:241], v[72:75]
	v_mfma_f32_16x16x32_bf16 v[68:71], v[200:203], v[234:237], v[68:71]
	v_mfma_f32_16x16x32_bf16 v[68:71], v[204:207], v[238:241], v[68:71]
	v_mfma_f32_16x16x32_bf16 v[84:87], v[200:203], v[226:229], v[84:87]
	v_mfma_f32_16x16x32_bf16 v[84:87], v[204:207], v[230:233], v[84:87]
	v_mfma_f32_16x16x32_bf16 v[100:103], v[200:203], v[216:219], v[100:103]
	v_mfma_f32_16x16x32_bf16 v[100:103], v[204:207], v[222:225], v[100:103]
	v_mfma_f32_16x16x32_bf16 v[116:119], v[200:203], v[208:211], v[116:119]
	v_mfma_f32_16x16x32_bf16 v[116:119], v[204:207], v[212:215], v[116:119]
	s_setprio 0
	s_barrier
	s_add_i32 s27, s27, s11
	v_lshl_add_u64 v[152:153], v[152:153], 0, s[78:79]
	s_mov_b32 m0, s27
	ds_read_b128 v[208:211], v156 offset:49152
	ds_read_b128 v[212:215], v156 offset:50176
	ds_read_b128 v[216:219], v156 offset:51200
	ds_read_b128 v[222:225], v156 offset:52224
	ds_read_b128 v[226:229], v156 offset:53248
	ds_read_b128 v[230:233], v156 offset:54272
	ds_read_b128 v[234:237], v156 offset:55296
	ds_read_b128 v[238:241], v156 offset:56320
	global_load_lds_dwordx4 v[152:153], off
	s_add_i32 m0, s27, 0x2000
	s_add_u32 s28, s54, 0x80080
	v_lshl_add_u64 v[152:153], v[162:163], 0, s[78:79]
	s_addc_u32 s29, s55, 0
	s_add_i32 s27, s30, s11
	global_load_lds_dwordx4 v[152:153], off
	v_lshl_add_u64 v[152:153], s[28:29], 0, v[34:35]
	s_mov_b32 m0, s27
	s_nop 0
	global_load_lds_dwordx4 v[152:153], off
	v_lshl_add_u64 v[152:153], s[28:29], 0, v[146:147]
	s_add_i32 m0, s27, 0x2000
	s_nop 0
	global_load_lds_dwordx4 v[152:153], off
	v_lshl_add_u64 v[152:153], v[242:243], 0, s[78:79]
	s_mov_b32 m0, s16
	s_nop 0
	global_load_lds_dwordx4 v[152:153], off
	v_lshl_add_u64 v[152:153], v[244:245], 0, s[78:79]
	s_mov_b32 m0, s17
	s_nop 0
	global_load_lds_dwordx4 v[152:153], off
	s_waitcnt vmcnt(8)
	s_waitcnt lgkmcnt(0)
	s_barrier
	s_setprio 1
	s_waitcnt lgkmcnt(0)
	v_mfma_f32_16x16x32_bf16 v[64:67], v[158:161], v[208:211], v[64:67]
	v_mfma_f32_16x16x32_bf16 v[64:67], v[180:183], v[212:215], v[64:67]
	v_mfma_f32_16x16x32_bf16 v[48:51], v[158:161], v[216:219], v[48:51]
	v_mfma_f32_16x16x32_bf16 v[48:51], v[180:183], v[222:225], v[48:51]
	v_mfma_f32_16x16x32_bf16 v[30:33], v[158:161], v[226:229], v[30:33]
	v_mfma_f32_16x16x32_bf16 v[30:33], v[180:183], v[230:233], v[30:33]
	v_mfma_f32_16x16x32_bf16 v[14:17], v[158:161], v[234:237], v[14:17]
	v_mfma_f32_16x16x32_bf16 v[14:17], v[180:183], v[238:241], v[14:17]
	v_mfma_f32_16x16x32_bf16 v[10:13], v[184:187], v[234:237], v[10:13]
	v_mfma_f32_16x16x32_bf16 v[10:13], v[188:191], v[238:241], v[10:13]
	v_mfma_f32_16x16x32_bf16 v[26:29], v[184:187], v[226:229], v[26:29]
	v_mfma_f32_16x16x32_bf16 v[26:29], v[188:191], v[230:233], v[26:29]
	v_mfma_f32_16x16x32_bf16 v[44:47], v[184:187], v[216:219], v[44:47]
	v_mfma_f32_16x16x32_bf16 v[44:47], v[188:191], v[222:225], v[44:47]
	v_mfma_f32_16x16x32_bf16 v[60:63], v[184:187], v[208:211], v[60:63]
	v_mfma_f32_16x16x32_bf16 v[60:63], v[188:191], v[212:215], v[60:63]
	s_setprio 0
	s_setprio 1
	v_mfma_f32_16x16x32_bf16 v[56:59], v[192:195], v[208:211], v[56:59]
	v_mfma_f32_16x16x32_bf16 v[56:59], v[196:199], v[212:215], v[56:59]
	v_mfma_f32_16x16x32_bf16 v[40:43], v[192:195], v[216:219], v[40:43]
	v_mfma_f32_16x16x32_bf16 v[40:43], v[196:199], v[222:225], v[40:43]
	v_mfma_f32_16x16x32_bf16 v[22:25], v[192:195], v[226:229], v[22:25]
	v_mfma_f32_16x16x32_bf16 v[22:25], v[196:199], v[230:233], v[22:25]
	v_mfma_f32_16x16x32_bf16 v[6:9], v[192:195], v[234:237], v[6:9]
	v_mfma_f32_16x16x32_bf16 v[6:9], v[196:199], v[238:241], v[6:9]
	v_mfma_f32_16x16x32_bf16 v[2:5], v[200:203], v[234:237], v[2:5]
	v_mfma_f32_16x16x32_bf16 v[2:5], v[204:207], v[238:241], v[2:5]
	v_mfma_f32_16x16x32_bf16 v[18:21], v[200:203], v[226:229], v[18:21]
	v_mfma_f32_16x16x32_bf16 v[18:21], v[204:207], v[230:233], v[18:21]
	v_mfma_f32_16x16x32_bf16 v[36:39], v[200:203], v[216:219], v[36:39]
	v_mfma_f32_16x16x32_bf16 v[36:39], v[204:207], v[222:225], v[36:39]
	v_mfma_f32_16x16x32_bf16 v[52:55], v[200:203], v[208:211], v[52:55]
	v_mfma_f32_16x16x32_bf16 v[52:55], v[204:207], v[212:215], v[52:55]
	s_setprio 0
	s_barrier
	s_add_i32 s26, s26, 2
	s_add_u32 s24, s24, 0x100
	s_addc_u32 s25, s25, 0
	s_add_u32 s62, s62, 0x100
	s_addc_u32 s63, s63, 0
	s_branch .LBB0_985

.LBB0_1054:
	s_sext_i32_i8 s19, s42
	s_add_u32 s42, s40, 0xdc00000
	s_waitcnt vmcnt(0)
	v_lshrrev_b32_e32 v18, 1, v16
	s_addc_u32 s43, s41, 0
	v_and_b32_e32 v18, 24, v18
	s_lshl_b32 s16, s16, 5
	v_and_b32_e32 v17, 15, v16
	v_lshlrev_b32_e32 v19, 1, v18
	v_lshlrev_b32_e32 v16, 2, v16
	s_and_b32 s22, s16, 0x60
	v_lshl_or_b32 v137, s17, 6, v17
	v_lshl_or_b32 v17, v17, 6, v19
	s_lshl_b32 s17, s17, 13
	v_and_b32_e32 v16, 32, v16
	s_lshl_b32 s16, s22, 7
	s_add_i32 m0, s12, 0x18000
	v_lshl_add_u64 v[8:9], v[8:9], 0, s[78:79]
	v_bitop3_b32 v19, v17, s17, v16 bitop3:0xde
	v_bitop3_b32 v154, v17, s16, v16 bitop3:0xde
	s_waitcnt vmcnt(2)
	s_barrier
	global_load_lds_dwordx4 v[8:9], off
	v_lshl_add_u64 v[6:7], v[6:7], 0, s[78:79]
	s_add_i32 m0, s12, 0x1a000
	s_add_i32 s16, s12, 0x8000
	s_add_i32 s17, s12, 0xa000
	global_load_lds_dwordx4 v[6:7], off
	v_lshl_add_u64 v[2:3], v[2:3], 0, s[78:79]
	s_mov_b32 m0, s16
	s_add_u32 s20, s54, 0x200080
	global_load_lds_dwordx4 v[2:3], off
	v_lshl_add_u64 v[2:3], v[4:5], 0, s[78:79]
	s_mov_b32 m0, s17
	s_addc_u32 s21, s55, 0
	global_load_lds_dwordx4 v[2:3], off
	s_add_i32 m0, s12, 0x1c000
	v_lshl_add_u64 v[2:3], s[20:21], 0, v[34:35]
	global_load_lds_dwordx4 v[2:3], off
	v_lshl_add_u64 v[2:3], s[20:21], 0, v[146:147]
	s_add_i32 m0, s12, 0x1e000
	s_cmpk_lt_u32 s18, 0x100
	global_load_lds_dwordx4 v[2:3], off
	v_lshlrev_b32_e32 v2, 17, v13
	v_and_b32_e32 v2, 0xfffc0000, v2
	v_lshl_add_u32 v2, v14, 14, v2
	v_and_b32_e32 v3, 1, v13
	v_lshl_or_b32 v2, v3, 6, v2
	v_lshl_add_u32 v148, v15, 1, v2
	v_lshlrev_b32_e32 v2, 17, v10
	v_and_b32_e32 v2, 0xfffc0000, v2
	s_waitcnt vmcnt(6)
	v_lshl_add_u32 v2, v11, 14, v2
	v_and_b32_e32 v3, 1, v10
	v_lshl_or_b32 v2, v3, 6, v2
	s_cselect_b64 s[44:45], -1, 0
	v_or_b32_e32 v155, s22, v18
	v_mov_b32_e32 v149, v35
	v_lshl_add_u32 v150, v12, 1, v2
	v_mov_b32_e32 v151, v35
	s_mov_b32 s18, 0
	v_add_u32_e32 v156, 0, v19
	s_barrier
	s_mov_b32 s98, 0
	s_branch .LBB0_1057

.LBB0_1063:
	s_ashr_i32 s49, s48, 31
	s_lshl_b64 s[20:21], s[48:49], 22
	s_add_u32 s56, s7, s20
	s_addc_u32 s57, s8, s21
	s_and_b64 s[20:21], s[40:41], exec
	s_cselect_b32 s20, s57, s63
	s_cselect_b32 s21, s56, s62
	s_ashr_i32 s47, s46, 31
	s_lshl_b64 s[22:23], s[46:47], 22
	s_add_u32 s60, s9, s22
	s_addc_u32 s61, s10, s23
	s_and_b64 s[22:23], s[40:41], exec
	s_cselect_b32 s22, s61, s55
	s_cselect_b32 s23, s60, s54
	s_add_u32 s24, s54, 0x100
	s_addc_u32 s25, s55, 0
	s_add_u32 s62, s62, 0x200080
	v_mov_b32_e32 v2, 0
	s_addc_u32 s63, s63, 0
	s_mov_b32 s26, -2
	v_mov_b32_e32 v3, v2
	v_mov_b32_e32 v4, v2
	v_mov_b32_e32 v5, v2
	v_mov_b32_e32 v6, v2
	v_mov_b32_e32 v7, v2
	v_mov_b32_e32 v8, v2
	v_mov_b32_e32 v9, v2
	v_mov_b32_e32 v10, v2
	v_mov_b32_e32 v11, v2
	v_mov_b32_e32 v12, v2
	v_mov_b32_e32 v13, v2
	v_mov_b32_e32 v18, v2
	v_mov_b32_e32 v19, v2
	v_mov_b32_e32 v20, v2
	v_mov_b32_e32 v21, v2
	v_mov_b32_e32 v26, v2
	v_mov_b32_e32 v27, v2
	v_mov_b32_e32 v28, v2
	v_mov_b32_e32 v29, v2
	v_mov_b32_e32 v36, v2
	v_mov_b32_e32 v37, v2
	v_mov_b32_e32 v38, v2
	v_mov_b32_e32 v39, v2
	v_mov_b32_e32 v44, v2
	v_mov_b32_e32 v45, v2
	v_mov_b32_e32 v46, v2
	v_mov_b32_e32 v47, v2
	v_mov_b32_e32 v52, v2
	v_mov_b32_e32 v53, v2
	v_mov_b32_e32 v54, v2
	v_mov_b32_e32 v55, v2
	v_mov_b32_e32 v14, v2
	v_mov_b32_e32 v15, v2
	v_mov_b32_e32 v16, v2
	v_mov_b32_e32 v17, v2
	v_mov_b32_e32 v22, v2
	v_mov_b32_e32 v23, v2
	v_mov_b32_e32 v24, v2
	v_mov_b32_e32 v25, v2
	v_mov_b32_e32 v30, v2
	v_mov_b32_e32 v31, v2
	v_mov_b32_e32 v32, v2
	v_mov_b32_e32 v33, v2
	v_mov_b32_e32 v40, v2
	v_mov_b32_e32 v41, v2
	v_mov_b32_e32 v42, v2
	v_mov_b32_e32 v43, v2
	v_mov_b32_e32 v48, v2
	v_mov_b32_e32 v49, v2
	v_mov_b32_e32 v50, v2
	v_mov_b32_e32 v51, v2
	v_mov_b32_e32 v56, v2
	v_mov_b32_e32 v57, v2
	v_mov_b32_e32 v58, v2
	v_mov_b32_e32 v59, v2
	v_mov_b32_e32 v60, v2
	v_mov_b32_e32 v61, v2
	v_mov_b32_e32 v62, v2
	v_mov_b32_e32 v63, v2
	v_mov_b32_e32 v64, v2
	v_mov_b32_e32 v65, v2
	v_mov_b32_e32 v66, v2
	v_mov_b32_e32 v67, v2
	v_mov_b32_e32 v68, v2
	v_mov_b32_e32 v69, v2
	v_mov_b32_e32 v70, v2
	v_mov_b32_e32 v71, v2
	v_mov_b32_e32 v72, v2
	v_mov_b32_e32 v73, v2
	v_mov_b32_e32 v74, v2
	v_mov_b32_e32 v75, v2
	v_mov_b32_e32 v76, v2
	v_mov_b32_e32 v77, v2
	v_mov_b32_e32 v78, v2
	v_mov_b32_e32 v79, v2
	v_mov_b32_e32 v84, v2
	v_mov_b32_e32 v85, v2
	v_mov_b32_e32 v86, v2
	v_mov_b32_e32 v87, v2
	v_mov_b32_e32 v92, v2
	v_mov_b32_e32 v93, v2
	v_mov_b32_e32 v94, v2
	v_mov_b32_e32 v95, v2
	v_mov_b32_e32 v100, v2
	v_mov_b32_e32 v101, v2
	v_mov_b32_e32 v102, v2
	v_mov_b32_e32 v103, v2
	v_mov_b32_e32 v108, v2
	v_mov_b32_e32 v109, v2
	v_mov_b32_e32 v110, v2
	v_mov_b32_e32 v111, v2
	v_mov_b32_e32 v116, v2
	v_mov_b32_e32 v117, v2
	v_mov_b32_e32 v118, v2
	v_mov_b32_e32 v119, v2
	v_mov_b32_e32 v80, v2
	v_mov_b32_e32 v81, v2
	v_mov_b32_e32 v82, v2
	v_mov_b32_e32 v83, v2
	v_mov_b32_e32 v88, v2
	v_mov_b32_e32 v89, v2
	v_mov_b32_e32 v90, v2
	v_mov_b32_e32 v91, v2
	v_mov_b32_e32 v96, v2
	v_mov_b32_e32 v97, v2
	v_mov_b32_e32 v98, v2
	v_mov_b32_e32 v99, v2
	v_mov_b32_e32 v104, v2
	v_mov_b32_e32 v105, v2
	v_mov_b32_e32 v106, v2
	v_mov_b32_e32 v107, v2
	v_mov_b32_e32 v112, v2
	v_mov_b32_e32 v113, v2
	v_mov_b32_e32 v114, v2
	v_mov_b32_e32 v115, v2
	v_mov_b32_e32 v120, v2
	v_mov_b32_e32 v121, v2
	v_mov_b32_e32 v122, v2
	v_mov_b32_e32 v123, v2
	v_mov_b32_e32 v124, v2
	v_mov_b32_e32 v125, v2
	v_mov_b32_e32 v126, v2
	v_mov_b32_e32 v127, v2
	v_mov_b32_e32 v128, v2
	v_mov_b32_e32 v129, v2
	v_mov_b32_e32 v130, v2
	v_mov_b32_e32 v131, v2
	s_cmp_lg_u32 s98, 0
	s_mov_b32 s98, 1
	s_cbranch_scc0 .LBB0_1064
	s_add_u32 s27, s62, 0xffe00080
	s_addc_u32 s28, s63, -1
	s_add_i32 s29, 0, 0x10000
	s_cmpk_eq_i32 s26, 0x7c
	s_cselect_b32 s67, s20, s28
	s_cselect_b32 s66, s21, s27
	v_add_u32_e32 v152, s29, v154
	s_cselect_b32 s55, s22, s25
	s_cselect_b32 s54, s23, s24
	s_add_i32 s27, 0, 0x14000
	ds_read_b128 v[158:161], v152
	ds_read_b128 v[180:183], v152 offset:1024
	ds_read_b128 v[184:187], v152 offset:2048
	ds_read_b128 v[188:191], v152 offset:3072
	v_add_u32_e32 v152, s27, v154
	ds_read_b128 v[192:195], v152
	ds_read_b128 v[196:199], v152 offset:1024
	ds_read_b128 v[200:203], v152 offset:2048
	ds_read_b128 v[204:207], v152 offset:3072
	v_lshl_add_u64 v[152:153], s[62:63], 0, v[150:151]
	s_add_i32 m0, s12, 0xc000
	ds_read_b128 v[208:211], v156
	ds_read_b128 v[212:215], v156 offset:1024
	ds_read_b128 v[216:219], v156 offset:2048
	ds_read_b128 v[222:225], v156 offset:3072
	ds_read_b128 v[226:229], v156 offset:4096
	ds_read_b128 v[230:233], v156 offset:5120
	ds_read_b128 v[234:237], v156 offset:6144
	ds_read_b128 v[238:241], v156 offset:7168
	global_load_lds_dwordx4 v[152:153], off
	v_lshl_add_u64 v[152:153], s[62:63], 0, v[148:149]
	s_add_i32 m0, s12, 0xe000
	s_nop 0
	global_load_lds_dwordx4 v[152:153], off
	s_waitcnt vmcnt(24)
	s_waitcnt lgkmcnt(0)
	s_barrier
	s_setprio 1
	s_waitcnt lgkmcnt(0)
	v_mfma_f32_16x16x32_bf16 v[128:131], v[158:161], v[208:211], v[128:131]
	v_mfma_f32_16x16x32_bf16 v[128:131], v[180:183], v[212:215], v[128:131]
	v_mfma_f32_16x16x32_bf16 v[120:123], v[158:161], v[216:219], v[120:123]
	v_mfma_f32_16x16x32_bf16 v[120:123], v[180:183], v[222:225], v[120:123]
	v_mfma_f32_16x16x32_bf16 v[104:107], v[158:161], v[226:229], v[104:107]
	v_mfma_f32_16x16x32_bf16 v[104:107], v[180:183], v[230:233], v[104:107]
	v_mfma_f32_16x16x32_bf16 v[88:91], v[158:161], v[234:237], v[88:91]
	v_mfma_f32_16x16x32_bf16 v[88:91], v[180:183], v[238:241], v[88:91]
	v_mfma_f32_16x16x32_bf16 v[80:83], v[184:187], v[234:237], v[80:83]
	v_mfma_f32_16x16x32_bf16 v[80:83], v[188:191], v[238:241], v[80:83]
	v_mfma_f32_16x16x32_bf16 v[96:99], v[184:187], v[226:229], v[96:99]
	v_mfma_f32_16x16x32_bf16 v[96:99], v[188:191], v[230:233], v[96:99]
	v_mfma_f32_16x16x32_bf16 v[112:115], v[184:187], v[216:219], v[112:115]
	v_mfma_f32_16x16x32_bf16 v[112:115], v[188:191], v[222:225], v[112:115]
	v_mfma_f32_16x16x32_bf16 v[124:127], v[184:187], v[208:211], v[124:127]
	v_mfma_f32_16x16x32_bf16 v[124:127], v[188:191], v[212:215], v[124:127]
	s_setprio 0
	s_setprio 1
	v_mfma_f32_16x16x32_bf16 v[116:119], v[192:195], v[208:211], v[116:119]
	v_mfma_f32_16x16x32_bf16 v[116:119], v[196:199], v[212:215], v[116:119]
	v_mfma_f32_16x16x32_bf16 v[100:103], v[192:195], v[216:219], v[100:103]
	v_mfma_f32_16x16x32_bf16 v[100:103], v[196:199], v[222:225], v[100:103]
	v_mfma_f32_16x16x32_bf16 v[84:87], v[192:195], v[226:229], v[84:87]
	v_mfma_f32_16x16x32_bf16 v[84:87], v[196:199], v[230:233], v[84:87]
	v_mfma_f32_16x16x32_bf16 v[72:75], v[192:195], v[234:237], v[72:75]
	v_mfma_f32_16x16x32_bf16 v[72:75], v[196:199], v[238:241], v[72:75]
	v_mfma_f32_16x16x32_bf16 v[68:71], v[200:203], v[234:237], v[68:71]
	v_mfma_f32_16x16x32_bf16 v[68:71], v[204:207], v[238:241], v[68:71]
	v_mfma_f32_16x16x32_bf16 v[76:79], v[200:203], v[226:229], v[76:79]
	v_mfma_f32_16x16x32_bf16 v[76:79], v[204:207], v[230:233], v[76:79]
	v_mfma_f32_16x16x32_bf16 v[92:95], v[200:203], v[216:219], v[92:95]
	v_mfma_f32_16x16x32_bf16 v[92:95], v[204:207], v[222:225], v[92:95]
	v_mfma_f32_16x16x32_bf16 v[108:111], v[200:203], v[208:211], v[108:111]
	v_mfma_f32_16x16x32_bf16 v[108:111], v[204:207], v[212:215], v[108:111]
	s_setprio 0
	s_barrier
	s_add_i32 s28, s29, s11
	v_lshl_add_u64 v[152:153], s[54:55], 0, v[34:35]
	s_mov_b32 m0, s28
	ds_read_b128 v[208:211], v156 offset:16384
	ds_read_b128 v[212:215], v156 offset:17408
	ds_read_b128 v[216:219], v156 offset:18432
	ds_read_b128 v[222:225], v156 offset:19456
	ds_read_b128 v[226:229], v156 offset:20480
	ds_read_b128 v[230:233], v156 offset:21504
	ds_read_b128 v[234:237], v156 offset:22528
	ds_read_b128 v[238:241], v156 offset:23552
	global_load_lds_dwordx4 v[152:153], off
	s_add_i32 m0, s28, 0x2000
	s_add_u32 s28, s54, 0x200000
	v_lshl_add_u64 v[162:163], s[54:55], 0, v[146:147]
	s_addc_u32 s29, s55, 0
	s_add_i32 s27, s27, s11
	global_load_lds_dwordx4 v[162:163], off
	v_lshl_add_u64 v[242:243], s[28:29], 0, v[34:35]
	s_mov_b32 m0, s27
	v_lshl_add_u64 v[244:245], s[66:67], 0, v[144:145]
	global_load_lds_dwordx4 v[242:243], off
	v_lshl_add_u64 v[242:243], s[28:29], 0, v[146:147]
	s_add_i32 m0, s27, 0x2000
	s_nop 0
	global_load_lds_dwordx4 v[242:243], off
	v_lshl_add_u64 v[242:243], s[66:67], 0, v[142:143]
	s_mov_b32 m0, s12
	s_nop 0
	global_load_lds_dwordx4 v[242:243], off
	s_mov_b32 m0, s13
	s_nop 0
	global_load_lds_dwordx4 v[244:245], off
	s_waitcnt vmcnt(24)
	s_waitcnt lgkmcnt(0)
	s_barrier
	s_setprio 1
	s_waitcnt lgkmcnt(0)
	v_mfma_f32_16x16x32_bf16 v[64:67], v[158:161], v[208:211], v[64:67]
	v_mfma_f32_16x16x32_bf16 v[64:67], v[180:183], v[212:215], v[64:67]
	v_mfma_f32_16x16x32_bf16 v[56:59], v[158:161], v[216:219], v[56:59]
	v_mfma_f32_16x16x32_bf16 v[56:59], v[180:183], v[222:225], v[56:59]
	v_mfma_f32_16x16x32_bf16 v[40:43], v[158:161], v[226:229], v[40:43]
	v_mfma_f32_16x16x32_bf16 v[40:43], v[180:183], v[230:233], v[40:43]
	v_mfma_f32_16x16x32_bf16 v[22:25], v[158:161], v[234:237], v[22:25]
	v_mfma_f32_16x16x32_bf16 v[22:25], v[180:183], v[238:241], v[22:25]
	v_mfma_f32_16x16x32_bf16 v[14:17], v[184:187], v[234:237], v[14:17]
	v_mfma_f32_16x16x32_bf16 v[14:17], v[188:191], v[238:241], v[14:17]
	v_mfma_f32_16x16x32_bf16 v[30:33], v[184:187], v[226:229], v[30:33]
	v_mfma_f32_16x16x32_bf16 v[30:33], v[188:191], v[230:233], v[30:33]
	v_mfma_f32_16x16x32_bf16 v[48:51], v[184:187], v[216:219], v[48:51]
	v_mfma_f32_16x16x32_bf16 v[48:51], v[188:191], v[222:225], v[48:51]
	v_mfma_f32_16x16x32_bf16 v[60:63], v[184:187], v[208:211], v[60:63]
	v_mfma_f32_16x16x32_bf16 v[60:63], v[188:191], v[212:215], v[60:63]
	s_setprio 0
	s_setprio 1
	v_mfma_f32_16x16x32_bf16 v[52:55], v[192:195], v[208:211], v[52:55]
	v_mfma_f32_16x16x32_bf16 v[52:55], v[196:199], v[212:215], v[52:55]
	v_mfma_f32_16x16x32_bf16 v[36:39], v[192:195], v[216:219], v[36:39]
	v_mfma_f32_16x16x32_bf16 v[36:39], v[196:199], v[222:225], v[36:39]
	v_mfma_f32_16x16x32_bf16 v[18:21], v[192:195], v[226:229], v[18:21]
	v_mfma_f32_16x16x32_bf16 v[18:21], v[196:199], v[230:233], v[18:21]
	v_mfma_f32_16x16x32_bf16 v[6:9], v[192:195], v[234:237], v[6:9]
	v_mfma_f32_16x16x32_bf16 v[6:9], v[196:199], v[238:241], v[6:9]
	v_mfma_f32_16x16x32_bf16 v[2:5], v[200:203], v[234:237], v[2:5]
	v_mfma_f32_16x16x32_bf16 v[2:5], v[204:207], v[238:241], v[2:5]
	v_mfma_f32_16x16x32_bf16 v[10:13], v[200:203], v[226:229], v[10:13]
	v_mfma_f32_16x16x32_bf16 v[10:13], v[204:207], v[230:233], v[10:13]
	v_mfma_f32_16x16x32_bf16 v[26:29], v[200:203], v[216:219], v[26:29]
	v_mfma_f32_16x16x32_bf16 v[26:29], v[204:207], v[222:225], v[26:29]
	v_mfma_f32_16x16x32_bf16 v[44:47], v[200:203], v[208:211], v[44:47]
	v_mfma_f32_16x16x32_bf16 v[44:47], v[204:207], v[212:215], v[44:47]
	s_setprio 0
	s_barrier
	s_add_i32 s27, 0, 0x18000
	v_add_u32_e32 v157, s27, v154
	s_add_i32 s30, 0, 0x1c000
	ds_read_b128 v[158:161], v157
	ds_read_b128 v[180:183], v157 offset:1024
	ds_read_b128 v[184:187], v157 offset:2048
	ds_read_b128 v[188:191], v157 offset:3072
	v_add_u32_e32 v157, s30, v154
	ds_read_b128 v[192:195], v157
	ds_read_b128 v[196:199], v157 offset:1024
	ds_read_b128 v[200:203], v157 offset:2048
	ds_read_b128 v[204:207], v157 offset:3072
	s_add_u32 s28, s66, 0x200000
	s_addc_u32 s29, s67, 0
	s_mov_b32 m0, s14
	v_lshl_add_u64 v[246:247], s[28:29], 0, v[142:143]
	ds_read_b128 v[208:211], v156 offset:32768
	ds_read_b128 v[212:215], v156 offset:33792
	ds_read_b128 v[216:219], v156 offset:34816
	ds_read_b128 v[222:225], v156 offset:35840
	ds_read_b128 v[226:229], v156 offset:36864
	ds_read_b128 v[230:233], v156 offset:37888
	ds_read_b128 v[234:237], v156 offset:38912
	ds_read_b128 v[238:241], v156 offset:39936
	global_load_lds_dwordx4 v[246:247], off
	v_lshl_add_u64 v[246:247], s[28:29], 0, v[144:145]
	s_mov_b32 m0, s15
	s_nop 0
	global_load_lds_dwordx4 v[246:247], off
	s_waitcnt vmcnt(8)
	s_waitcnt lgkmcnt(0)
	s_barrier
	s_setprio 1
	s_waitcnt lgkmcnt(0)
	v_mfma_f32_16x16x32_bf16 v[128:131], v[158:161], v[208:211], v[128:131]
	v_mfma_f32_16x16x32_bf16 v[128:131], v[180:183], v[212:215], v[128:131]
	v_mfma_f32_16x16x32_bf16 v[120:123], v[158:161], v[216:219], v[120:123]
	v_mfma_f32_16x16x32_bf16 v[120:123], v[180:183], v[222:225], v[120:123]
	v_mfma_f32_16x16x32_bf16 v[104:107], v[158:161], v[226:229], v[104:107]
	v_mfma_f32_16x16x32_bf16 v[104:107], v[180:183], v[230:233], v[104:107]
	v_mfma_f32_16x16x32_bf16 v[88:91], v[158:161], v[234:237], v[88:91]
	v_mfma_f32_16x16x32_bf16 v[88:91], v[180:183], v[238:241], v[88:91]
	v_mfma_f32_16x16x32_bf16 v[80:83], v[184:187], v[234:237], v[80:83]
	v_mfma_f32_16x16x32_bf16 v[80:83], v[188:191], v[238:241], v[80:83]
	v_mfma_f32_16x16x32_bf16 v[96:99], v[184:187], v[226:229], v[96:99]
	v_mfma_f32_16x16x32_bf16 v[96:99], v[188:191], v[230:233], v[96:99]
	v_mfma_f32_16x16x32_bf16 v[112:115], v[184:187], v[216:219], v[112:115]
	v_mfma_f32_16x16x32_bf16 v[112:115], v[188:191], v[222:225], v[112:115]
	v_mfma_f32_16x16x32_bf16 v[124:127], v[184:187], v[208:211], v[124:127]
	v_mfma_f32_16x16x32_bf16 v[124:127], v[188:191], v[212:215], v[124:127]
	s_setprio 0
	s_setprio 1
	v_mfma_f32_16x16x32_bf16 v[116:119], v[192:195], v[208:211], v[116:119]
	v_mfma_f32_16x16x32_bf16 v[116:119], v[196:199], v[212:215], v[116:119]
	v_mfma_f32_16x16x32_bf16 v[100:103], v[192:195], v[216:219], v[100:103]
	v_mfma_f32_16x16x32_bf16 v[100:103], v[196:199], v[222:225], v[100:103]
	v_mfma_f32_16x16x32_bf16 v[84:87], v[192:195], v[226:229], v[84:87]
	v_mfma_f32_16x16x32_bf16 v[84:87], v[196:199], v[230:233], v[84:87]
	v_mfma_f32_16x16x32_bf16 v[72:75], v[192:195], v[234:237], v[72:75]
	v_mfma_f32_16x16x32_bf16 v[72:75], v[196:199], v[238:241], v[72:75]
	v_mfma_f32_16x16x32_bf16 v[68:71], v[200:203], v[234:237], v[68:71]
	v_mfma_f32_16x16x32_bf16 v[68:71], v[204:207], v[238:241], v[68:71]
	v_mfma_f32_16x16x32_bf16 v[76:79], v[200:203], v[226:229], v[76:79]
	v_mfma_f32_16x16x32_bf16 v[76:79], v[204:207], v[230:233], v[76:79]
	v_mfma_f32_16x16x32_bf16 v[92:95], v[200:203], v[216:219], v[92:95]
	v_mfma_f32_16x16x32_bf16 v[92:95], v[204:207], v[222:225], v[92:95]
	v_mfma_f32_16x16x32_bf16 v[108:111], v[200:203], v[208:211], v[108:111]
	v_mfma_f32_16x16x32_bf16 v[108:111], v[204:207], v[212:215], v[108:111]
	s_setprio 0
	s_barrier
	s_add_i32 s27, s27, s11
	v_lshl_add_u64 v[152:153], v[152:153], 0, s[78:79]
	s_mov_b32 m0, s27
	ds_read_b128 v[208:211], v156 offset:49152
	ds_read_b128 v[212:215], v156 offset:50176
	ds_read_b128 v[216:219], v156 offset:51200
	ds_read_b128 v[222:225], v156 offset:52224
	ds_read_b128 v[226:229], v156 offset:53248
	ds_read_b128 v[230:233], v156 offset:54272
	ds_read_b128 v[234:237], v156 offset:55296
	ds_read_b128 v[238:241], v156 offset:56320
	global_load_lds_dwordx4 v[152:153], off
	s_add_i32 m0, s27, 0x2000
	s_add_u32 s28, s54, 0x200080
	v_lshl_add_u64 v[152:153], v[162:163], 0, s[78:79]
	s_addc_u32 s29, s55, 0
	s_add_i32 s27, s30, s11
	global_load_lds_dwordx4 v[152:153], off
	v_lshl_add_u64 v[152:153], s[28:29], 0, v[34:35]
	s_mov_b32 m0, s27
	s_nop 0
	global_load_lds_dwordx4 v[152:153], off
	v_lshl_add_u64 v[152:153], s[28:29], 0, v[146:147]
	s_add_i32 m0, s27, 0x2000
	s_nop 0
	global_load_lds_dwordx4 v[152:153], off
	v_lshl_add_u64 v[152:153], v[242:243], 0, s[78:79]
	s_mov_b32 m0, s16
	s_nop 0
	global_load_lds_dwordx4 v[152:153], off
	v_lshl_add_u64 v[152:153], v[244:245], 0, s[78:79]
	s_mov_b32 m0, s17
	s_nop 0
	global_load_lds_dwordx4 v[152:153], off
	s_waitcnt vmcnt(8)
	s_waitcnt lgkmcnt(0)
	s_barrier
	s_setprio 1
	s_waitcnt lgkmcnt(0)
	v_mfma_f32_16x16x32_bf16 v[64:67], v[158:161], v[208:211], v[64:67]
	v_mfma_f32_16x16x32_bf16 v[64:67], v[180:183], v[212:215], v[64:67]
	v_mfma_f32_16x16x32_bf16 v[56:59], v[158:161], v[216:219], v[56:59]
	v_mfma_f32_16x16x32_bf16 v[56:59], v[180:183], v[222:225], v[56:59]
	v_mfma_f32_16x16x32_bf16 v[40:43], v[158:161], v[226:229], v[40:43]
	v_mfma_f32_16x16x32_bf16 v[40:43], v[180:183], v[230:233], v[40:43]
	v_mfma_f32_16x16x32_bf16 v[22:25], v[158:161], v[234:237], v[22:25]
	v_mfma_f32_16x16x32_bf16 v[22:25], v[180:183], v[238:241], v[22:25]
	v_mfma_f32_16x16x32_bf16 v[14:17], v[184:187], v[234:237], v[14:17]
	v_mfma_f32_16x16x32_bf16 v[14:17], v[188:191], v[238:241], v[14:17]
	v_mfma_f32_16x16x32_bf16 v[30:33], v[184:187], v[226:229], v[30:33]
	v_mfma_f32_16x16x32_bf16 v[30:33], v[188:191], v[230:233], v[30:33]
	v_mfma_f32_16x16x32_bf16 v[48:51], v[184:187], v[216:219], v[48:51]
	v_mfma_f32_16x16x32_bf16 v[48:51], v[188:191], v[222:225], v[48:51]
	v_mfma_f32_16x16x32_bf16 v[60:63], v[184:187], v[208:211], v[60:63]
	v_mfma_f32_16x16x32_bf16 v[60:63], v[188:191], v[212:215], v[60:63]
	s_setprio 0
	s_setprio 1
	v_mfma_f32_16x16x32_bf16 v[52:55], v[192:195], v[208:211], v[52:55]
	v_mfma_f32_16x16x32_bf16 v[52:55], v[196:199], v[212:215], v[52:55]
	v_mfma_f32_16x16x32_bf16 v[36:39], v[192:195], v[216:219], v[36:39]
	v_mfma_f32_16x16x32_bf16 v[36:39], v[196:199], v[222:225], v[36:39]
	v_mfma_f32_16x16x32_bf16 v[18:21], v[192:195], v[226:229], v[18:21]
	v_mfma_f32_16x16x32_bf16 v[18:21], v[196:199], v[230:233], v[18:21]
	v_mfma_f32_16x16x32_bf16 v[6:9], v[192:195], v[234:237], v[6:9]
	v_mfma_f32_16x16x32_bf16 v[6:9], v[196:199], v[238:241], v[6:9]
	v_mfma_f32_16x16x32_bf16 v[2:5], v[200:203], v[234:237], v[2:5]
	v_mfma_f32_16x16x32_bf16 v[2:5], v[204:207], v[238:241], v[2:5]
	v_mfma_f32_16x16x32_bf16 v[10:13], v[200:203], v[226:229], v[10:13]
	v_mfma_f32_16x16x32_bf16 v[10:13], v[204:207], v[230:233], v[10:13]
	v_mfma_f32_16x16x32_bf16 v[26:29], v[200:203], v[216:219], v[26:29]
	v_mfma_f32_16x16x32_bf16 v[26:29], v[204:207], v[222:225], v[26:29]
	v_mfma_f32_16x16x32_bf16 v[44:47], v[200:203], v[208:211], v[44:47]
	v_mfma_f32_16x16x32_bf16 v[44:47], v[204:207], v[212:215], v[44:47]
	s_setprio 0
	s_barrier
	s_add_i32 s26, s26, 2
	s_add_u32 s24, s24, 0x100
	s_addc_u32 s25, s25, 0
	s_add_u32 s62, s62, 0x100
	s_addc_u32 s63, s63, 0
	s_branch .LBB0_1064

.LBB0_1201:
	s_and_b64 s[24:25], s[86:87], exec
	s_mov_b32 s19, 0x1dc00000
	s_cselect_b32 s22, s19, 0x2dc00000
	s_add_u32 s52, s36, s22
	s_waitcnt vmcnt(0)
	v_lshrrev_b32_e32 v18, 1, v16
	s_addc_u32 s53, s37, 0
	v_and_b32_e32 v18, 24, v18
	s_lshl_b32 s20, s20, 5
	v_and_b32_e32 v17, 15, v16
	v_lshlrev_b32_e32 v19, 1, v18
	v_lshlrev_b32_e32 v16, 2, v16
	s_and_b32 s26, s20, 0x60
	v_lshl_or_b32 v143, s21, 6, v17
	v_lshl_or_b32 v17, v17, 6, v19
	s_lshl_b32 s21, s21, 13
	v_and_b32_e32 v16, 32, v16
	s_lshl_b32 s20, s26, 7
	v_bitop3_b32 v19, v17, s21, v16 bitop3:0xde
	v_bitop3_b32 v146, v17, s20, v16 bitop3:0xde
	s_and_b64 s[20:21], s[86:87], exec
	s_cselect_b32 s20, 2, 0
	s_add_i32 m0, s15, 0x18000
	v_lshl_add_u64 v[8:9], v[8:9], 0, s[56:57]
	s_waitcnt vmcnt(2)
	s_barrier
	global_load_lds_dwordx4 v[8:9], off
	v_lshl_add_u64 v[6:7], v[6:7], 0, s[56:57]
	s_add_i32 m0, s15, 0x1a000
	s_add_i32 s21, s15, 0x8000
	s_add_i32 s22, s15, 0xa000
	global_load_lds_dwordx4 v[6:7], off
	v_lshl_add_u64 v[2:3], v[2:3], 0, s[56:57]
	s_mov_b32 m0, s21
	s_add_u32 s24, s54, 0x80080
	global_load_lds_dwordx4 v[2:3], off
	v_lshl_add_u64 v[2:3], v[4:5], 0, s[56:57]
	s_mov_b32 m0, s22
	s_addc_u32 s25, s55, 0
	global_load_lds_dwordx4 v[2:3], off
	s_add_i32 m0, s15, 0x1c000
	v_lshl_add_u64 v[2:3], s[24:25], 0, v[194:195]
	global_load_lds_dwordx4 v[2:3], off
	v_lshl_add_u64 v[2:3], s[24:25], 0, v[130:131]
	s_add_i32 m0, s15, 0x1e000
	s_cmpk_lt_u32 s23, 0x100
	global_load_lds_dwordx4 v[2:3], off
	v_lshlrev_b32_e32 v2, 15, v10
	v_and_b32_e32 v2, 0xffff0000, v2
	v_lshl_add_u32 v2, v11, 12, v2
	v_and_b32_e32 v3, 1, v10
	v_lshl_or_b32 v2, v3, 6, v2
	v_lshl_add_u32 v136, v12, 1, v2
	v_lshlrev_b32_e32 v2, 15, v14
	v_and_b32_e32 v2, 0xffff0000, v2
	s_waitcnt vmcnt(6)
	v_lshl_add_u32 v2, v13, 12, v2
	v_and_b32_e32 v3, 1, v14
	v_lshl_or_b32 v2, v3, 6, v2
	s_sext_i32_i16 s1, s38
	s_mov_b32 s19, 0
	s_cselect_b64 s[36:37], -1, 0
	v_or_b32_e32 v147, s26, v18
	v_mov_b32_e32 v137, v195
	v_lshl_add_u32 v138, v15, 1, v2
	v_mov_b32_e32 v139, v195
	v_add_u32_e32 v148, 0, v19
	v_mov_b64_e32 v[140:141], s[40:41]
	s_barrier
	s_mov_b32 s98, 0
	s_branch .LBB0_1204

.LBB0_1206:
	s_ashr_i32 s81, s80, 31
	s_lshl_b64 s[24:25], s[80:81], 20
	s_add_u32 s82, s6, s24
	s_addc_u32 s83, s7, s25
	s_and_b64 s[24:25], s[38:39], exec
	s_cselect_b32 s23, s83, s91
	s_cselect_b32 s24, s82, s90
	s_ashr_i32 s79, s78, 31
	s_lshl_b64 s[26:27], s[78:79], 20
	s_add_u32 s88, s8, s26
	s_addc_u32 s89, s9, s27
	s_and_b64 s[26:27], s[38:39], exec
	s_cselect_b32 s25, s89, s55
	s_cselect_b32 s26, s88, s54
	s_add_u32 s27, s54, 0x100
	s_addc_u32 s28, s55, 0
	s_add_u32 s90, s90, 0x80080
	v_mov_b32_e32 v2, 0
	s_addc_u32 s91, s91, 0
	s_mov_b32 s29, -2
	v_mov_b32_e32 v3, v2
	v_mov_b32_e32 v4, v2
	v_mov_b32_e32 v5, v2
	v_mov_b32_e32 v6, v2
	v_mov_b32_e32 v7, v2
	v_mov_b32_e32 v8, v2
	v_mov_b32_e32 v9, v2
	v_mov_b32_e32 v14, v2
	v_mov_b32_e32 v15, v2
	v_mov_b32_e32 v16, v2
	v_mov_b32_e32 v17, v2
	v_mov_b32_e32 v22, v2
	v_mov_b32_e32 v23, v2
	v_mov_b32_e32 v24, v2
	v_mov_b32_e32 v25, v2
	v_mov_b32_e32 v30, v2
	v_mov_b32_e32 v31, v2
	v_mov_b32_e32 v32, v2
	v_mov_b32_e32 v33, v2
	v_mov_b32_e32 v38, v2
	v_mov_b32_e32 v39, v2
	v_mov_b32_e32 v40, v2
	v_mov_b32_e32 v41, v2
	v_mov_b32_e32 v46, v2
	v_mov_b32_e32 v47, v2
	v_mov_b32_e32 v48, v2
	v_mov_b32_e32 v49, v2
	v_mov_b32_e32 v54, v2
	v_mov_b32_e32 v55, v2
	v_mov_b32_e32 v56, v2
	v_mov_b32_e32 v57, v2
	v_mov_b32_e32 v10, v2
	v_mov_b32_e32 v11, v2
	v_mov_b32_e32 v12, v2
	v_mov_b32_e32 v13, v2
	v_mov_b32_e32 v18, v2
	v_mov_b32_e32 v19, v2
	v_mov_b32_e32 v20, v2
	v_mov_b32_e32 v21, v2
	v_mov_b32_e32 v26, v2
	v_mov_b32_e32 v27, v2
	v_mov_b32_e32 v28, v2
	v_mov_b32_e32 v29, v2
	v_mov_b32_e32 v34, v2
	v_mov_b32_e32 v35, v2
	v_mov_b32_e32 v36, v2
	v_mov_b32_e32 v37, v2
	v_mov_b32_e32 v42, v2
	v_mov_b32_e32 v43, v2
	v_mov_b32_e32 v44, v2
	v_mov_b32_e32 v45, v2
	v_mov_b32_e32 v50, v2
	v_mov_b32_e32 v51, v2
	v_mov_b32_e32 v52, v2
	v_mov_b32_e32 v53, v2
	v_mov_b32_e32 v58, v2
	v_mov_b32_e32 v59, v2
	v_mov_b32_e32 v60, v2
	v_mov_b32_e32 v61, v2
	v_mov_b32_e32 v62, v2
	v_mov_b32_e32 v63, v2
	v_mov_b32_e32 v64, v2
	v_mov_b32_e32 v65, v2
	v_mov_b32_e32 v66, v2
	v_mov_b32_e32 v67, v2
	v_mov_b32_e32 v68, v2
	v_mov_b32_e32 v69, v2
	v_mov_b32_e32 v70, v2
	v_mov_b32_e32 v71, v2
	v_mov_b32_e32 v72, v2
	v_mov_b32_e32 v73, v2
	v_mov_b32_e32 v78, v2
	v_mov_b32_e32 v79, v2
	v_mov_b32_e32 v80, v2
	v_mov_b32_e32 v81, v2
	v_mov_b32_e32 v86, v2
	v_mov_b32_e32 v87, v2
	v_mov_b32_e32 v88, v2
	v_mov_b32_e32 v89, v2
	v_mov_b32_e32 v94, v2
	v_mov_b32_e32 v95, v2
	v_mov_b32_e32 v96, v2
	v_mov_b32_e32 v97, v2
	v_mov_b32_e32 v102, v2
	v_mov_b32_e32 v103, v2
	v_mov_b32_e32 v104, v2
	v_mov_b32_e32 v105, v2
	v_mov_b32_e32 v110, v2
	v_mov_b32_e32 v111, v2
	v_mov_b32_e32 v112, v2
	v_mov_b32_e32 v113, v2
	v_mov_b32_e32 v118, v2
	v_mov_b32_e32 v119, v2
	v_mov_b32_e32 v120, v2
	v_mov_b32_e32 v121, v2
	v_mov_b32_e32 v74, v2
	v_mov_b32_e32 v75, v2
	v_mov_b32_e32 v76, v2
	v_mov_b32_e32 v77, v2
	v_mov_b32_e32 v82, v2
	v_mov_b32_e32 v83, v2
	v_mov_b32_e32 v84, v2
	v_mov_b32_e32 v85, v2
	v_mov_b32_e32 v90, v2
	v_mov_b32_e32 v91, v2
	v_mov_b32_e32 v92, v2
	v_mov_b32_e32 v93, v2
	v_mov_b32_e32 v98, v2
	v_mov_b32_e32 v99, v2
	v_mov_b32_e32 v100, v2
	v_mov_b32_e32 v101, v2
	v_mov_b32_e32 v106, v2
	v_mov_b32_e32 v107, v2
	v_mov_b32_e32 v108, v2
	v_mov_b32_e32 v109, v2
	v_mov_b32_e32 v114, v2
	v_mov_b32_e32 v115, v2
	v_mov_b32_e32 v116, v2
	v_mov_b32_e32 v117, v2
	v_mov_b32_e32 v122, v2
	v_mov_b32_e32 v123, v2
	v_mov_b32_e32 v124, v2
	v_mov_b32_e32 v125, v2
	v_mov_b32_e32 v126, v2
	v_mov_b32_e32 v127, v2
	v_mov_b32_e32 v128, v2
	v_mov_b32_e32 v129, v2
	s_cmp_lg_u32 s98, 0
	s_mov_b32 s98, 1
	s_cbranch_scc0 .LBB0_1207
	s_add_u32 s30, s90, 0xfff80080
	s_addc_u32 s31, s91, -1
	s_add_i32 s40, 0, 0x10000
	s_cmp_eq_u32 s29, 28
	s_cselect_b32 vcc_hi, s23, s31
	s_cselect_b32 vcc_lo, s24, s30
	v_add_u32_e32 v142, s40, v146
	s_cselect_b32 s55, s25, s28
	s_cselect_b32 s54, s26, s27
	s_add_i32 s44, 0, 0x14000
	ds_read_b128 v[150:153], v142
	ds_read_b128 v[154:157], v142 offset:1024
	ds_read_b128 v[158:161], v142 offset:2048
	ds_read_b128 v[162:165], v142 offset:3072
	v_add_u32_e32 v142, s44, v146
	ds_read_b128 v[166:169], v142
	ds_read_b128 v[170:173], v142 offset:1024
	ds_read_b128 v[174:177], v142 offset:2048
	ds_read_b128 v[178:181], v142 offset:3072
	v_lshl_add_u64 v[144:145], s[90:91], 0, v[138:139]
	s_add_i32 m0, s15, 0xc000
	ds_read_b128 v[182:185], v148
	ds_read_b128 v[186:189], v148 offset:1024
	ds_read_b128 v[190:193], v148 offset:2048
	ds_read_b128 v[210:213], v148 offset:3072
	ds_read_b128 v[214:217], v148 offset:4096
	ds_read_b128 v[230:233], v148 offset:5120
	ds_read_b128 v[234:237], v148 offset:6144
	ds_read_b128 v[238:241], v148 offset:7168
	global_load_lds_dwordx4 v[144:145], off
	v_lshl_add_u64 v[144:145], s[90:91], 0, v[136:137]
	s_add_i32 m0, s15, 0xe000
	s_nop 0
	global_load_lds_dwordx4 v[144:145], off
	s_waitcnt vmcnt(24)
	s_waitcnt lgkmcnt(0)
	s_barrier
	s_setprio 1
	s_waitcnt lgkmcnt(0)
	v_mfma_f32_16x16x32_bf16 v[126:129], v[150:153], v[182:185], v[126:129]
	v_mfma_f32_16x16x32_bf16 v[126:129], v[154:157], v[186:189], v[126:129]
	v_mfma_f32_16x16x32_bf16 v[114:117], v[150:153], v[190:193], v[114:117]
	v_mfma_f32_16x16x32_bf16 v[114:117], v[154:157], v[210:213], v[114:117]
	v_mfma_f32_16x16x32_bf16 v[98:101], v[150:153], v[214:217], v[98:101]
	v_mfma_f32_16x16x32_bf16 v[98:101], v[154:157], v[230:233], v[98:101]
	v_mfma_f32_16x16x32_bf16 v[82:85], v[150:153], v[234:237], v[82:85]
	v_mfma_f32_16x16x32_bf16 v[82:85], v[154:157], v[238:241], v[82:85]
	v_mfma_f32_16x16x32_bf16 v[74:77], v[158:161], v[234:237], v[74:77]
	v_mfma_f32_16x16x32_bf16 v[74:77], v[162:165], v[238:241], v[74:77]
	v_mfma_f32_16x16x32_bf16 v[90:93], v[158:161], v[214:217], v[90:93]
	v_mfma_f32_16x16x32_bf16 v[90:93], v[162:165], v[230:233], v[90:93]
	v_mfma_f32_16x16x32_bf16 v[106:109], v[158:161], v[190:193], v[106:109]
	v_mfma_f32_16x16x32_bf16 v[106:109], v[162:165], v[210:213], v[106:109]
	v_mfma_f32_16x16x32_bf16 v[122:125], v[158:161], v[182:185], v[122:125]
	v_mfma_f32_16x16x32_bf16 v[122:125], v[162:165], v[186:189], v[122:125]
	s_setprio 0
	s_setprio 1
	v_mfma_f32_16x16x32_bf16 v[118:121], v[166:169], v[182:185], v[118:121]
	v_mfma_f32_16x16x32_bf16 v[118:121], v[170:173], v[186:189], v[118:121]
	v_mfma_f32_16x16x32_bf16 v[102:105], v[166:169], v[190:193], v[102:105]
	v_mfma_f32_16x16x32_bf16 v[102:105], v[170:173], v[210:213], v[102:105]
	v_mfma_f32_16x16x32_bf16 v[86:89], v[166:169], v[214:217], v[86:89]
	v_mfma_f32_16x16x32_bf16 v[86:89], v[170:173], v[230:233], v[86:89]
	v_mfma_f32_16x16x32_bf16 v[70:73], v[166:169], v[234:237], v[70:73]
	v_mfma_f32_16x16x32_bf16 v[70:73], v[170:173], v[238:241], v[70:73]
	v_mfma_f32_16x16x32_bf16 v[66:69], v[174:177], v[234:237], v[66:69]
	v_mfma_f32_16x16x32_bf16 v[66:69], v[178:181], v[238:241], v[66:69]
	v_mfma_f32_16x16x32_bf16 v[78:81], v[174:177], v[214:217], v[78:81]
	v_mfma_f32_16x16x32_bf16 v[78:81], v[178:181], v[230:233], v[78:81]
	v_mfma_f32_16x16x32_bf16 v[94:97], v[174:177], v[190:193], v[94:97]
	v_mfma_f32_16x16x32_bf16 v[94:97], v[178:181], v[210:213], v[94:97]
	v_mfma_f32_16x16x32_bf16 v[110:113], v[174:177], v[182:185], v[110:113]
	v_mfma_f32_16x16x32_bf16 v[110:113], v[178:181], v[186:189], v[110:113]
	s_setprio 0
	s_barrier
	s_add_i32 s30, s40, s10
	v_lshl_add_u64 v[144:145], s[54:55], 0, v[194:195]
	s_mov_b32 m0, s30
	ds_read_b128 v[182:185], v148 offset:16384
	ds_read_b128 v[186:189], v148 offset:17408
	ds_read_b128 v[190:193], v148 offset:18432
	ds_read_b128 v[210:213], v148 offset:19456
	ds_read_b128 v[214:217], v148 offset:20480
	ds_read_b128 v[230:233], v148 offset:21504
	ds_read_b128 v[234:237], v148 offset:22528
	ds_read_b128 v[238:241], v148 offset:23552
	global_load_lds_dwordx4 v[144:145], off
	s_add_i32 m0, s30, 0x2000
	s_add_u32 s30, s54, 0x80000
	v_lshl_add_u64 v[218:219], s[54:55], 0, v[130:131]
	s_addc_u32 s31, s55, 0
	s_add_i32 s40, s44, s10
	global_load_lds_dwordx4 v[218:219], off
	v_lshl_add_u64 v[242:243], s[30:31], 0, v[194:195]
	s_mov_b32 m0, s40
	v_lshl_add_u64 v[244:245], vcc, 0, v[132:133]
	global_load_lds_dwordx4 v[242:243], off
	v_lshl_add_u64 v[242:243], s[30:31], 0, v[130:131]
	s_add_i32 m0, s40, 0x2000
	s_nop 0
	global_load_lds_dwordx4 v[242:243], off
	v_lshl_add_u64 v[242:243], vcc, 0, v[134:135]
	s_mov_b32 m0, s15
	s_nop 0
	global_load_lds_dwordx4 v[242:243], off
	s_mov_b32 m0, s16
	s_nop 0
	global_load_lds_dwordx4 v[244:245], off
	s_waitcnt vmcnt(24)
	s_waitcnt lgkmcnt(0)
	s_barrier
	s_setprio 1
	s_waitcnt lgkmcnt(0)
	v_mfma_f32_16x16x32_bf16 v[62:65], v[150:153], v[182:185], v[62:65]
	v_mfma_f32_16x16x32_bf16 v[62:65], v[154:157], v[186:189], v[62:65]
	v_mfma_f32_16x16x32_bf16 v[50:53], v[150:153], v[190:193], v[50:53]
	v_mfma_f32_16x16x32_bf16 v[50:53], v[154:157], v[210:213], v[50:53]
	v_mfma_f32_16x16x32_bf16 v[34:37], v[150:153], v[214:217], v[34:37]
	v_mfma_f32_16x16x32_bf16 v[34:37], v[154:157], v[230:233], v[34:37]
	v_mfma_f32_16x16x32_bf16 v[18:21], v[150:153], v[234:237], v[18:21]
	v_mfma_f32_16x16x32_bf16 v[18:21], v[154:157], v[238:241], v[18:21]
	v_mfma_f32_16x16x32_bf16 v[10:13], v[158:161], v[234:237], v[10:13]
	v_mfma_f32_16x16x32_bf16 v[10:13], v[162:165], v[238:241], v[10:13]
	v_mfma_f32_16x16x32_bf16 v[26:29], v[158:161], v[214:217], v[26:29]
	v_mfma_f32_16x16x32_bf16 v[26:29], v[162:165], v[230:233], v[26:29]
	v_mfma_f32_16x16x32_bf16 v[42:45], v[158:161], v[190:193], v[42:45]
	v_mfma_f32_16x16x32_bf16 v[42:45], v[162:165], v[210:213], v[42:45]
	v_mfma_f32_16x16x32_bf16 v[58:61], v[158:161], v[182:185], v[58:61]
	v_mfma_f32_16x16x32_bf16 v[58:61], v[162:165], v[186:189], v[58:61]
	s_setprio 0
	s_setprio 1
	v_mfma_f32_16x16x32_bf16 v[54:57], v[166:169], v[182:185], v[54:57]
	v_mfma_f32_16x16x32_bf16 v[54:57], v[170:173], v[186:189], v[54:57]
	v_mfma_f32_16x16x32_bf16 v[38:41], v[166:169], v[190:193], v[38:41]
	v_mfma_f32_16x16x32_bf16 v[38:41], v[170:173], v[210:213], v[38:41]
	v_mfma_f32_16x16x32_bf16 v[22:25], v[166:169], v[214:217], v[22:25]
	v_mfma_f32_16x16x32_bf16 v[22:25], v[170:173], v[230:233], v[22:25]
	v_mfma_f32_16x16x32_bf16 v[6:9], v[166:169], v[234:237], v[6:9]
	v_mfma_f32_16x16x32_bf16 v[6:9], v[170:173], v[238:241], v[6:9]
	v_mfma_f32_16x16x32_bf16 v[2:5], v[174:177], v[234:237], v[2:5]
	v_mfma_f32_16x16x32_bf16 v[2:5], v[178:181], v[238:241], v[2:5]
	v_mfma_f32_16x16x32_bf16 v[14:17], v[174:177], v[214:217], v[14:17]
	v_mfma_f32_16x16x32_bf16 v[14:17], v[178:181], v[230:233], v[14:17]
	v_mfma_f32_16x16x32_bf16 v[30:33], v[174:177], v[190:193], v[30:33]
	v_mfma_f32_16x16x32_bf16 v[30:33], v[178:181], v[210:213], v[30:33]
	v_mfma_f32_16x16x32_bf16 v[46:49], v[174:177], v[182:185], v[46:49]
	v_mfma_f32_16x16x32_bf16 v[46:49], v[178:181], v[186:189], v[46:49]
	s_setprio 0
	s_barrier
	s_add_i32 s40, 0, 0x18000
	v_add_u32_e32 v142, s40, v146
	s_add_i32 s44, 0, 0x1c000
	ds_read_b128 v[150:153], v142
	ds_read_b128 v[154:157], v142 offset:1024
	ds_read_b128 v[158:161], v142 offset:2048
	ds_read_b128 v[162:165], v142 offset:3072
	v_add_u32_e32 v142, s44, v146
	ds_read_b128 v[166:169], v142
	ds_read_b128 v[170:173], v142 offset:1024
	ds_read_b128 v[174:177], v142 offset:2048
	ds_read_b128 v[178:181], v142 offset:3072
	s_add_u32 s30, vcc_lo, 0x80000
	s_addc_u32 s31, vcc_hi, 0
	s_mov_b32 m0, s17
	v_lshl_add_u64 v[246:247], s[30:31], 0, v[134:135]
	ds_read_b128 v[182:185], v148 offset:32768
	ds_read_b128 v[186:189], v148 offset:33792
	ds_read_b128 v[190:193], v148 offset:34816
	ds_read_b128 v[210:213], v148 offset:35840
	ds_read_b128 v[214:217], v148 offset:36864
	ds_read_b128 v[230:233], v148 offset:37888
	ds_read_b128 v[234:237], v148 offset:38912
	ds_read_b128 v[238:241], v148 offset:39936
	global_load_lds_dwordx4 v[246:247], off
	v_lshl_add_u64 v[246:247], s[30:31], 0, v[132:133]
	s_mov_b32 m0, s18
	s_nop 0
	global_load_lds_dwordx4 v[246:247], off
	s_waitcnt vmcnt(8)
	s_waitcnt lgkmcnt(0)
	s_barrier
	s_setprio 1
	s_waitcnt lgkmcnt(0)
	v_mfma_f32_16x16x32_bf16 v[126:129], v[150:153], v[182:185], v[126:129]
	v_mfma_f32_16x16x32_bf16 v[126:129], v[154:157], v[186:189], v[126:129]
	v_mfma_f32_16x16x32_bf16 v[114:117], v[150:153], v[190:193], v[114:117]
	v_mfma_f32_16x16x32_bf16 v[114:117], v[154:157], v[210:213], v[114:117]
	v_mfma_f32_16x16x32_bf16 v[98:101], v[150:153], v[214:217], v[98:101]
	v_mfma_f32_16x16x32_bf16 v[98:101], v[154:157], v[230:233], v[98:101]
	v_mfma_f32_16x16x32_bf16 v[82:85], v[150:153], v[234:237], v[82:85]
	v_mfma_f32_16x16x32_bf16 v[82:85], v[154:157], v[238:241], v[82:85]
	v_mfma_f32_16x16x32_bf16 v[74:77], v[158:161], v[234:237], v[74:77]
	v_mfma_f32_16x16x32_bf16 v[74:77], v[162:165], v[238:241], v[74:77]
	v_mfma_f32_16x16x32_bf16 v[90:93], v[158:161], v[214:217], v[90:93]
	v_mfma_f32_16x16x32_bf16 v[90:93], v[162:165], v[230:233], v[90:93]
	v_mfma_f32_16x16x32_bf16 v[106:109], v[158:161], v[190:193], v[106:109]
	v_mfma_f32_16x16x32_bf16 v[106:109], v[162:165], v[210:213], v[106:109]
	v_mfma_f32_16x16x32_bf16 v[122:125], v[158:161], v[182:185], v[122:125]
	v_mfma_f32_16x16x32_bf16 v[122:125], v[162:165], v[186:189], v[122:125]
	s_setprio 0
	s_setprio 1
	v_mfma_f32_16x16x32_bf16 v[118:121], v[166:169], v[182:185], v[118:121]
	v_mfma_f32_16x16x32_bf16 v[118:121], v[170:173], v[186:189], v[118:121]
	v_mfma_f32_16x16x32_bf16 v[102:105], v[166:169], v[190:193], v[102:105]
	v_mfma_f32_16x16x32_bf16 v[102:105], v[170:173], v[210:213], v[102:105]
	v_mfma_f32_16x16x32_bf16 v[86:89], v[166:169], v[214:217], v[86:89]
	v_mfma_f32_16x16x32_bf16 v[86:89], v[170:173], v[230:233], v[86:89]
	v_mfma_f32_16x16x32_bf16 v[70:73], v[166:169], v[234:237], v[70:73]
	v_mfma_f32_16x16x32_bf16 v[70:73], v[170:173], v[238:241], v[70:73]
	v_mfma_f32_16x16x32_bf16 v[66:69], v[174:177], v[234:237], v[66:69]
	v_mfma_f32_16x16x32_bf16 v[66:69], v[178:181], v[238:241], v[66:69]
	v_mfma_f32_16x16x32_bf16 v[78:81], v[174:177], v[214:217], v[78:81]
	v_mfma_f32_16x16x32_bf16 v[78:81], v[178:181], v[230:233], v[78:81]
	v_mfma_f32_16x16x32_bf16 v[94:97], v[174:177], v[190:193], v[94:97]
	v_mfma_f32_16x16x32_bf16 v[94:97], v[178:181], v[210:213], v[94:97]
	v_mfma_f32_16x16x32_bf16 v[110:113], v[174:177], v[182:185], v[110:113]
	v_mfma_f32_16x16x32_bf16 v[110:113], v[178:181], v[186:189], v[110:113]
	s_setprio 0
	s_barrier
	s_add_i32 s30, s40, s10
	v_lshl_add_u64 v[144:145], v[144:145], 0, s[56:57]
	s_mov_b32 m0, s30
	ds_read_b128 v[182:185], v148 offset:49152
	ds_read_b128 v[186:189], v148 offset:50176
	ds_read_b128 v[190:193], v148 offset:51200
	ds_read_b128 v[210:213], v148 offset:52224
	ds_read_b128 v[214:217], v148 offset:53248
	ds_read_b128 v[230:233], v148 offset:54272
	ds_read_b128 v[234:237], v148 offset:55296
	ds_read_b128 v[238:241], v148 offset:56320
	global_load_lds_dwordx4 v[144:145], off
	s_add_i32 m0, s30, 0x2000
	s_add_u32 s30, s54, 0x80080
	v_lshl_add_u64 v[144:145], v[218:219], 0, s[56:57]
	s_addc_u32 s31, s55, 0
	s_add_i32 s40, s44, s10
	global_load_lds_dwordx4 v[144:145], off
	v_lshl_add_u64 v[144:145], s[30:31], 0, v[194:195]
	s_mov_b32 m0, s40
	s_nop 0
	global_load_lds_dwordx4 v[144:145], off
	v_lshl_add_u64 v[144:145], s[30:31], 0, v[130:131]
	s_add_i32 m0, s40, 0x2000
	s_nop 0
	global_load_lds_dwordx4 v[144:145], off
	v_lshl_add_u64 v[144:145], v[242:243], 0, s[56:57]
	s_mov_b32 m0, s21
	s_nop 0
	global_load_lds_dwordx4 v[144:145], off
	v_lshl_add_u64 v[144:145], v[244:245], 0, s[56:57]
	s_mov_b32 m0, s22
	s_nop 0
	global_load_lds_dwordx4 v[144:145], off
	s_waitcnt vmcnt(8)
	s_waitcnt lgkmcnt(0)
	s_barrier
	s_setprio 1
	s_waitcnt lgkmcnt(0)
	v_mfma_f32_16x16x32_bf16 v[62:65], v[150:153], v[182:185], v[62:65]
	v_mfma_f32_16x16x32_bf16 v[62:65], v[154:157], v[186:189], v[62:65]
	v_mfma_f32_16x16x32_bf16 v[50:53], v[150:153], v[190:193], v[50:53]
	v_mfma_f32_16x16x32_bf16 v[50:53], v[154:157], v[210:213], v[50:53]
	v_mfma_f32_16x16x32_bf16 v[34:37], v[150:153], v[214:217], v[34:37]
	v_mfma_f32_16x16x32_bf16 v[34:37], v[154:157], v[230:233], v[34:37]
	v_mfma_f32_16x16x32_bf16 v[18:21], v[150:153], v[234:237], v[18:21]
	v_mfma_f32_16x16x32_bf16 v[18:21], v[154:157], v[238:241], v[18:21]
	v_mfma_f32_16x16x32_bf16 v[10:13], v[158:161], v[234:237], v[10:13]
	v_mfma_f32_16x16x32_bf16 v[10:13], v[162:165], v[238:241], v[10:13]
	v_mfma_f32_16x16x32_bf16 v[26:29], v[158:161], v[214:217], v[26:29]
	v_mfma_f32_16x16x32_bf16 v[26:29], v[162:165], v[230:233], v[26:29]
	v_mfma_f32_16x16x32_bf16 v[42:45], v[158:161], v[190:193], v[42:45]
	v_mfma_f32_16x16x32_bf16 v[42:45], v[162:165], v[210:213], v[42:45]
	v_mfma_f32_16x16x32_bf16 v[58:61], v[158:161], v[182:185], v[58:61]
	v_mfma_f32_16x16x32_bf16 v[58:61], v[162:165], v[186:189], v[58:61]
	s_setprio 0
	s_setprio 1
	v_mfma_f32_16x16x32_bf16 v[54:57], v[166:169], v[182:185], v[54:57]
	v_mfma_f32_16x16x32_bf16 v[54:57], v[170:173], v[186:189], v[54:57]
	v_mfma_f32_16x16x32_bf16 v[38:41], v[166:169], v[190:193], v[38:41]
	v_mfma_f32_16x16x32_bf16 v[38:41], v[170:173], v[210:213], v[38:41]
	v_mfma_f32_16x16x32_bf16 v[22:25], v[166:169], v[214:217], v[22:25]
	v_mfma_f32_16x16x32_bf16 v[22:25], v[170:173], v[230:233], v[22:25]
	v_mfma_f32_16x16x32_bf16 v[6:9], v[166:169], v[234:237], v[6:9]
	v_mfma_f32_16x16x32_bf16 v[6:9], v[170:173], v[238:241], v[6:9]
	v_mfma_f32_16x16x32_bf16 v[2:5], v[174:177], v[234:237], v[2:5]
	v_mfma_f32_16x16x32_bf16 v[2:5], v[178:181], v[238:241], v[2:5]
	v_mfma_f32_16x16x32_bf16 v[14:17], v[174:177], v[214:217], v[14:17]
	v_mfma_f32_16x16x32_bf16 v[14:17], v[178:181], v[230:233], v[14:17]
	v_mfma_f32_16x16x32_bf16 v[30:33], v[174:177], v[190:193], v[30:33]
	v_mfma_f32_16x16x32_bf16 v[30:33], v[178:181], v[210:213], v[30:33]
	v_mfma_f32_16x16x32_bf16 v[46:49], v[174:177], v[182:185], v[46:49]
	v_mfma_f32_16x16x32_bf16 v[46:49], v[178:181], v[186:189], v[46:49]
	s_setprio 0
	s_barrier
	s_add_i32 s29, s29, 2
	s_add_u32 s27, s27, 0x100
	s_addc_u32 s28, s28, 0
	s_add_u32 s90, s90, 0x100
	s_addc_u32 s91, s91, 0
	s_branch .LBB0_1207

.LBB0_1455:
	s_add_u32 s42, s38, 0xdc00000
	s_waitcnt vmcnt(0)
	v_lshrrev_b32_e32 v18, 1, v16
	s_addc_u32 s43, s39, 0
	v_and_b32_e32 v18, 24, v18
	s_lshl_b32 s16, s16, 5
	v_and_b32_e32 v17, 15, v16
	v_lshlrev_b32_e32 v19, 1, v18
	v_lshlrev_b32_e32 v16, 2, v16
	s_and_b32 s22, s16, 0x60
	v_lshl_or_b32 v142, s17, 6, v17
	v_lshl_or_b32 v17, v17, 6, v19
	s_lshl_b32 s17, s17, 13
	v_and_b32_e32 v16, 32, v16
	s_lshl_b32 s16, s22, 7
	s_add_i32 m0, s12, 0x18000
	v_lshl_add_u64 v[8:9], v[8:9], 0, s[56:57]
	v_bitop3_b32 v19, v17, s17, v16 bitop3:0xde
	v_bitop3_b32 v143, v17, s16, v16 bitop3:0xde
	s_waitcnt vmcnt(2)
	s_barrier
	global_load_lds_dwordx4 v[8:9], off
	v_lshl_add_u64 v[6:7], v[6:7], 0, s[56:57]
	s_add_i32 m0, s12, 0x1a000
	s_add_i32 s16, s12, 0x8000
	s_add_i32 s17, s12, 0xa000
	global_load_lds_dwordx4 v[6:7], off
	v_lshl_add_u64 v[2:3], v[2:3], 0, s[56:57]
	s_mov_b32 m0, s16
	s_add_u32 s20, s54, 0x80080
	global_load_lds_dwordx4 v[2:3], off
	v_lshl_add_u64 v[2:3], v[4:5], 0, s[56:57]
	s_mov_b32 m0, s17
	s_addc_u32 s21, s55, 0
	global_load_lds_dwordx4 v[2:3], off
	s_add_i32 m0, s12, 0x1c000
	v_lshl_add_u64 v[2:3], s[20:21], 0, v[194:195]
	global_load_lds_dwordx4 v[2:3], off
	v_lshl_add_u64 v[2:3], s[20:21], 0, v[134:135]
	s_add_i32 m0, s12, 0x1e000
	s_cmpk_lt_u32 s18, 0x100
	global_load_lds_dwordx4 v[2:3], off
	v_lshlrev_b32_e32 v2, 15, v13
	v_and_b32_e32 v2, 0xffff0000, v2
	v_lshl_add_u32 v2, v14, 12, v2
	v_and_b32_e32 v3, 1, v13
	v_lshl_or_b32 v2, v3, 6, v2
	v_lshl_add_u32 v136, v15, 1, v2
	v_lshlrev_b32_e32 v2, 15, v10
	v_and_b32_e32 v2, 0xffff0000, v2
	s_waitcnt vmcnt(6)
	v_lshl_add_u32 v2, v11, 12, v2
	v_and_b32_e32 v3, 1, v10
	v_lshl_or_b32 v2, v3, 6, v2
	s_sext_i32_i8 s19, s40
	s_cselect_b64 s[44:45], -1, 0
	v_or_b32_e32 v144, s22, v18
	v_mov_b32_e32 v137, v195
	v_lshl_add_u32 v138, v12, 1, v2
	v_mov_b32_e32 v139, v195
	s_mov_b32 s18, 0
	v_add_u32_e32 v145, 0, v19
	s_barrier
	s_mov_b32 s98, 0
	s_branch .LBB0_1458

.LBB0_1458:
	s_add_i32 s18, s18, 1
	s_mul_i32 s20, s18, s2
	s_mul_hi_u32 s21, s18, s33
	s_add_i32 s21, s21, s20
	s_mul_i32 s20, s18, s33
	s_add_u32 s80, s20, s5
	s_addc_u32 s81, s21, s6
	v_cmp_gt_i64_e32 vcc, s[80:81], v[200:201]
	v_cmp_lt_i64_e64 s[38:39], s[80:81], v[198:199]
	s_cbranch_vccnz .LBB0_1464
	s_and_b32 s21, s80, 7
	s_lshr_b32 s20, s80, 3
	s_lshl_b32 s21, s21, 7
	s_add_i32 s20, s20, s21
	s_lshr_b32 s22, s20, 5
	s_lshl_b32 s22, s22, 2
	s_and_b32 s20, s20, 0x1f
	s_lshr_b32 s46, s20, 2
	s_and_b32 s20, s20, 3
	s_add_i32 s52, s22, s20
.LBB0_1464:
	s_ashr_i32 s53, s52, 31
	s_lshl_b64 s[20:21], s[52:53], 20
	s_add_u32 s80, s7, s20
	s_addc_u32 s81, s8, s21
	s_and_b64 s[20:21], s[38:39], exec
	s_cselect_b32 s20, s81, s89
	s_cselect_b32 s21, s80, s88
	s_ashr_i32 s47, s46, 31
	s_lshl_b64 s[22:23], s[46:47], 20
	s_add_u32 s82, s9, s22
	s_addc_u32 s83, s10, s23
	s_and_b64 s[22:23], s[38:39], exec
	s_cselect_b32 s22, s83, s55
	s_cselect_b32 s23, s82, s54
	s_add_u32 s24, s54, 0x100
	s_addc_u32 s25, s55, 0
	s_add_u32 s88, s88, 0x80080
	v_mov_b32_e32 v2, 0
	s_addc_u32 s89, s89, 0
	s_mov_b32 s26, -2
	v_mov_b32_e32 v3, v2
	v_mov_b32_e32 v4, v2
	v_mov_b32_e32 v5, v2
	v_mov_b32_e32 v6, v2
	v_mov_b32_e32 v7, v2
	v_mov_b32_e32 v8, v2
	v_mov_b32_e32 v9, v2
	v_mov_b32_e32 v10, v2
	v_mov_b32_e32 v11, v2
	v_mov_b32_e32 v12, v2
	v_mov_b32_e32 v13, v2
	v_mov_b32_e32 v18, v2
	v_mov_b32_e32 v19, v2
	v_mov_b32_e32 v20, v2
	v_mov_b32_e32 v21, v2
	v_mov_b32_e32 v26, v2
	v_mov_b32_e32 v27, v2
	v_mov_b32_e32 v28, v2
	v_mov_b32_e32 v29, v2
	v_mov_b32_e32 v34, v2
	v_mov_b32_e32 v35, v2
	v_mov_b32_e32 v36, v2
	v_mov_b32_e32 v37, v2
	v_mov_b32_e32 v42, v2
	v_mov_b32_e32 v43, v2
	v_mov_b32_e32 v44, v2
	v_mov_b32_e32 v45, v2
	v_mov_b32_e32 v50, v2
	v_mov_b32_e32 v51, v2
	v_mov_b32_e32 v52, v2
	v_mov_b32_e32 v53, v2
	v_mov_b32_e32 v14, v2
	v_mov_b32_e32 v15, v2
	v_mov_b32_e32 v16, v2
	v_mov_b32_e32 v17, v2
	v_mov_b32_e32 v22, v2
	v_mov_b32_e32 v23, v2
	v_mov_b32_e32 v24, v2
	v_mov_b32_e32 v25, v2
	v_mov_b32_e32 v30, v2
	v_mov_b32_e32 v31, v2
	v_mov_b32_e32 v32, v2
	v_mov_b32_e32 v33, v2
	v_mov_b32_e32 v38, v2
	v_mov_b32_e32 v39, v2
	v_mov_b32_e32 v40, v2
	v_mov_b32_e32 v41, v2
	v_mov_b32_e32 v46, v2
	v_mov_b32_e32 v47, v2
	v_mov_b32_e32 v48, v2
	v_mov_b32_e32 v49, v2
	v_mov_b32_e32 v54, v2
	v_mov_b32_e32 v55, v2
	v_mov_b32_e32 v56, v2
	v_mov_b32_e32 v57, v2
	v_mov_b32_e32 v58, v2
	v_mov_b32_e32 v59, v2
	v_mov_b32_e32 v60, v2
	v_mov_b32_e32 v61, v2
	v_mov_b32_e32 v62, v2
	v_mov_b32_e32 v63, v2
	v_mov_b32_e32 v64, v2
	v_mov_b32_e32 v65, v2
	v_mov_b32_e32 v66, v2
	v_mov_b32_e32 v67, v2
	v_mov_b32_e32 v68, v2
	v_mov_b32_e32 v69, v2
	v_mov_b32_e32 v70, v2
	v_mov_b32_e32 v71, v2
	v_mov_b32_e32 v72, v2
	v_mov_b32_e32 v73, v2
	v_mov_b32_e32 v74, v2
	v_mov_b32_e32 v75, v2
	v_mov_b32_e32 v76, v2
	v_mov_b32_e32 v77, v2
	v_mov_b32_e32 v82, v2
	v_mov_b32_e32 v83, v2
	v_mov_b32_e32 v84, v2
	v_mov_b32_e32 v85, v2
	v_mov_b32_e32 v90, v2
	v_mov_b32_e32 v91, v2
	v_mov_b32_e32 v92, v2
	v_mov_b32_e32 v93, v2
	v_mov_b32_e32 v98, v2
	v_mov_b32_e32 v99, v2
	v_mov_b32_e32 v100, v2
	v_mov_b32_e32 v101, v2
	v_mov_b32_e32 v106, v2
	v_mov_b32_e32 v107, v2
	v_mov_b32_e32 v108, v2
	v_mov_b32_e32 v109, v2
	v_mov_b32_e32 v114, v2
	v_mov_b32_e32 v115, v2
	v_mov_b32_e32 v116, v2
	v_mov_b32_e32 v117, v2
	v_mov_b32_e32 v78, v2
	v_mov_b32_e32 v79, v2
	v_mov_b32_e32 v80, v2
	v_mov_b32_e32 v81, v2
	v_mov_b32_e32 v86, v2
	v_mov_b32_e32 v87, v2
	v_mov_b32_e32 v88, v2
	v_mov_b32_e32 v89, v2
	v_mov_b32_e32 v94, v2
	v_mov_b32_e32 v95, v2
	v_mov_b32_e32 v96, v2
	v_mov_b32_e32 v97, v2
	v_mov_b32_e32 v102, v2
	v_mov_b32_e32 v103, v2
	v_mov_b32_e32 v104, v2
	v_mov_b32_e32 v105, v2
	v_mov_b32_e32 v110, v2
	v_mov_b32_e32 v111, v2
	v_mov_b32_e32 v112, v2
	v_mov_b32_e32 v113, v2
	v_mov_b32_e32 v118, v2
	v_mov_b32_e32 v119, v2
	v_mov_b32_e32 v120, v2
	v_mov_b32_e32 v121, v2
	v_mov_b32_e32 v122, v2
	v_mov_b32_e32 v123, v2
	v_mov_b32_e32 v124, v2
	v_mov_b32_e32 v125, v2
	v_mov_b32_e32 v126, v2
	v_mov_b32_e32 v127, v2
	v_mov_b32_e32 v128, v2
	v_mov_b32_e32 v129, v2
	s_cmp_lg_u32 s98, 0
	s_mov_b32 s98, 1
	s_cbranch_scc0 .LBB0_1465
	s_add_u32 s27, s88, 0xfff80080
	s_addc_u32 s28, s89, -1
	s_add_i32 s29, 0, 0x10000
	s_cmp_eq_u32 s26, 28
	s_cselect_b32 s91, s20, s28
	s_cselect_b32 s90, s21, s27
	v_add_u32_e32 v140, s29, v143
	s_cselect_b32 s55, s22, s25
	s_cselect_b32 s54, s23, s24
	s_add_i32 s27, 0, 0x14000
	ds_read_b128 v[146:149], v140
	ds_read_b128 v[150:153], v140 offset:1024
	ds_read_b128 v[154:157], v140 offset:2048
	ds_read_b128 v[158:161], v140 offset:3072
	v_add_u32_e32 v140, s27, v143
	ds_read_b128 v[162:165], v140
	ds_read_b128 v[166:169], v140 offset:1024
	ds_read_b128 v[170:173], v140 offset:2048
	ds_read_b128 v[174:177], v140 offset:3072
	v_lshl_add_u64 v[140:141], s[88:89], 0, v[138:139]
	s_add_i32 m0, s12, 0xc000
	ds_read_b128 v[178:181], v145
	ds_read_b128 v[182:185], v145 offset:1024
	ds_read_b128 v[186:189], v145 offset:2048
	ds_read_b128 v[190:193], v145 offset:3072
	ds_read_b128 v[210:213], v145 offset:4096
	ds_read_b128 v[214:217], v145 offset:5120
	ds_read_b128 v[230:233], v145 offset:6144
	ds_read_b128 v[234:237], v145 offset:7168
	global_load_lds_dwordx4 v[140:141], off
	v_lshl_add_u64 v[140:141], s[88:89], 0, v[136:137]
	s_add_i32 m0, s12, 0xe000
	s_nop 0
	global_load_lds_dwordx4 v[140:141], off
	s_waitcnt vmcnt(24)
	s_waitcnt lgkmcnt(0)
	s_barrier
	s_setprio 1
	s_waitcnt lgkmcnt(0)
	v_mfma_f32_16x16x32_bf16 v[126:129], v[146:149], v[178:181], v[126:129]
	v_mfma_f32_16x16x32_bf16 v[126:129], v[150:153], v[182:185], v[126:129]
	v_mfma_f32_16x16x32_bf16 v[118:121], v[146:149], v[186:189], v[118:121]
	v_mfma_f32_16x16x32_bf16 v[118:121], v[150:153], v[190:193], v[118:121]
	v_mfma_f32_16x16x32_bf16 v[102:105], v[146:149], v[210:213], v[102:105]
	v_mfma_f32_16x16x32_bf16 v[102:105], v[150:153], v[214:217], v[102:105]
	v_mfma_f32_16x16x32_bf16 v[86:89], v[146:149], v[230:233], v[86:89]
	v_mfma_f32_16x16x32_bf16 v[86:89], v[150:153], v[234:237], v[86:89]
	v_mfma_f32_16x16x32_bf16 v[78:81], v[154:157], v[230:233], v[78:81]
	v_mfma_f32_16x16x32_bf16 v[78:81], v[158:161], v[234:237], v[78:81]
	v_mfma_f32_16x16x32_bf16 v[94:97], v[154:157], v[210:213], v[94:97]
	v_mfma_f32_16x16x32_bf16 v[94:97], v[158:161], v[214:217], v[94:97]
	v_mfma_f32_16x16x32_bf16 v[110:113], v[154:157], v[186:189], v[110:113]
	v_mfma_f32_16x16x32_bf16 v[110:113], v[158:161], v[190:193], v[110:113]
	v_mfma_f32_16x16x32_bf16 v[122:125], v[154:157], v[178:181], v[122:125]
	v_mfma_f32_16x16x32_bf16 v[122:125], v[158:161], v[182:185], v[122:125]
	s_setprio 0
	s_setprio 1
	v_mfma_f32_16x16x32_bf16 v[114:117], v[162:165], v[178:181], v[114:117]
	v_mfma_f32_16x16x32_bf16 v[114:117], v[166:169], v[182:185], v[114:117]
	v_mfma_f32_16x16x32_bf16 v[98:101], v[162:165], v[186:189], v[98:101]
	v_mfma_f32_16x16x32_bf16 v[98:101], v[166:169], v[190:193], v[98:101]
	v_mfma_f32_16x16x32_bf16 v[82:85], v[162:165], v[210:213], v[82:85]
	v_mfma_f32_16x16x32_bf16 v[82:85], v[166:169], v[214:217], v[82:85]
	v_mfma_f32_16x16x32_bf16 v[70:73], v[162:165], v[230:233], v[70:73]
	v_mfma_f32_16x16x32_bf16 v[70:73], v[166:169], v[234:237], v[70:73]
	v_mfma_f32_16x16x32_bf16 v[66:69], v[170:173], v[230:233], v[66:69]
	v_mfma_f32_16x16x32_bf16 v[66:69], v[174:177], v[234:237], v[66:69]
	v_mfma_f32_16x16x32_bf16 v[74:77], v[170:173], v[210:213], v[74:77]
	v_mfma_f32_16x16x32_bf16 v[74:77], v[174:177], v[214:217], v[74:77]
	v_mfma_f32_16x16x32_bf16 v[90:93], v[170:173], v[186:189], v[90:93]
	v_mfma_f32_16x16x32_bf16 v[90:93], v[174:177], v[190:193], v[90:93]
	v_mfma_f32_16x16x32_bf16 v[106:109], v[170:173], v[178:181], v[106:109]
	v_mfma_f32_16x16x32_bf16 v[106:109], v[174:177], v[182:185], v[106:109]
	s_setprio 0
	s_barrier
	s_add_i32 s28, s29, s11
	v_lshl_add_u64 v[140:141], s[54:55], 0, v[194:195]
	s_mov_b32 m0, s28
	ds_read_b128 v[178:181], v145 offset:16384
	ds_read_b128 v[182:185], v145 offset:17408
	ds_read_b128 v[186:189], v145 offset:18432
	ds_read_b128 v[190:193], v145 offset:19456
	ds_read_b128 v[210:213], v145 offset:20480
	ds_read_b128 v[214:217], v145 offset:21504
	ds_read_b128 v[230:233], v145 offset:22528
	ds_read_b128 v[234:237], v145 offset:23552
	global_load_lds_dwordx4 v[140:141], off
	s_add_i32 m0, s28, 0x2000
	s_add_u32 s28, s54, 0x80000
	v_lshl_add_u64 v[218:219], s[54:55], 0, v[134:135]
	s_addc_u32 s29, s55, 0
	s_add_i32 s27, s27, s11
	global_load_lds_dwordx4 v[218:219], off
	v_lshl_add_u64 v[238:239], s[28:29], 0, v[194:195]
	s_mov_b32 m0, s27
	v_lshl_add_u64 v[240:241], s[90:91], 0, v[132:133]
	global_load_lds_dwordx4 v[238:239], off
	v_lshl_add_u64 v[238:239], s[28:29], 0, v[134:135]
	s_add_i32 m0, s27, 0x2000
	s_nop 0
	global_load_lds_dwordx4 v[238:239], off
	v_lshl_add_u64 v[238:239], s[90:91], 0, v[130:131]
	s_mov_b32 m0, s12
	s_nop 0
	global_load_lds_dwordx4 v[238:239], off
	s_mov_b32 m0, s13
	s_nop 0
	global_load_lds_dwordx4 v[240:241], off
	s_waitcnt vmcnt(24)
	s_waitcnt lgkmcnt(0)
	s_barrier
	s_setprio 1
	s_waitcnt lgkmcnt(0)
	v_mfma_f32_16x16x32_bf16 v[62:65], v[146:149], v[178:181], v[62:65]
	v_mfma_f32_16x16x32_bf16 v[62:65], v[150:153], v[182:185], v[62:65]
	v_mfma_f32_16x16x32_bf16 v[54:57], v[146:149], v[186:189], v[54:57]
	v_mfma_f32_16x16x32_bf16 v[54:57], v[150:153], v[190:193], v[54:57]
	v_mfma_f32_16x16x32_bf16 v[38:41], v[146:149], v[210:213], v[38:41]
	v_mfma_f32_16x16x32_bf16 v[38:41], v[150:153], v[214:217], v[38:41]
	v_mfma_f32_16x16x32_bf16 v[22:25], v[146:149], v[230:233], v[22:25]
	v_mfma_f32_16x16x32_bf16 v[22:25], v[150:153], v[234:237], v[22:25]
	v_mfma_f32_16x16x32_bf16 v[14:17], v[154:157], v[230:233], v[14:17]
	v_mfma_f32_16x16x32_bf16 v[14:17], v[158:161], v[234:237], v[14:17]
	v_mfma_f32_16x16x32_bf16 v[30:33], v[154:157], v[210:213], v[30:33]
	v_mfma_f32_16x16x32_bf16 v[30:33], v[158:161], v[214:217], v[30:33]
	v_mfma_f32_16x16x32_bf16 v[46:49], v[154:157], v[186:189], v[46:49]
	v_mfma_f32_16x16x32_bf16 v[46:49], v[158:161], v[190:193], v[46:49]
	v_mfma_f32_16x16x32_bf16 v[58:61], v[154:157], v[178:181], v[58:61]
	v_mfma_f32_16x16x32_bf16 v[58:61], v[158:161], v[182:185], v[58:61]
	s_setprio 0
	s_setprio 1
	v_mfma_f32_16x16x32_bf16 v[50:53], v[162:165], v[178:181], v[50:53]
	v_mfma_f32_16x16x32_bf16 v[50:53], v[166:169], v[182:185], v[50:53]
	v_mfma_f32_16x16x32_bf16 v[34:37], v[162:165], v[186:189], v[34:37]
	v_mfma_f32_16x16x32_bf16 v[34:37], v[166:169], v[190:193], v[34:37]
	v_mfma_f32_16x16x32_bf16 v[18:21], v[162:165], v[210:213], v[18:21]
	v_mfma_f32_16x16x32_bf16 v[18:21], v[166:169], v[214:217], v[18:21]
	v_mfma_f32_16x16x32_bf16 v[6:9], v[162:165], v[230:233], v[6:9]
	v_mfma_f32_16x16x32_bf16 v[6:9], v[166:169], v[234:237], v[6:9]
	v_mfma_f32_16x16x32_bf16 v[2:5], v[170:173], v[230:233], v[2:5]
	v_mfma_f32_16x16x32_bf16 v[2:5], v[174:177], v[234:237], v[2:5]
	v_mfma_f32_16x16x32_bf16 v[10:13], v[170:173], v[210:213], v[10:13]
	v_mfma_f32_16x16x32_bf16 v[10:13], v[174:177], v[214:217], v[10:13]
	v_mfma_f32_16x16x32_bf16 v[26:29], v[170:173], v[186:189], v[26:29]
	v_mfma_f32_16x16x32_bf16 v[26:29], v[174:177], v[190:193], v[26:29]
	v_mfma_f32_16x16x32_bf16 v[42:45], v[170:173], v[178:181], v[42:45]
	v_mfma_f32_16x16x32_bf16 v[42:45], v[174:177], v[182:185], v[42:45]
	s_setprio 0
	s_barrier
	s_add_i32 s27, 0, 0x18000
	s_add_i32 s30, 0, 0x1c000
	v_add_u32_e32 v158, s27, v143
	v_add_u32_e32 v174, s30, v143
	ds_read_b128 v[146:149], v158
	ds_read_b128 v[150:153], v158 offset:1024
	ds_read_b128 v[154:157], v158 offset:2048
	ds_read_b128 v[158:161], v158 offset:3072
	ds_read_b128 v[162:165], v174
	ds_read_b128 v[166:169], v174 offset:1024
	ds_read_b128 v[170:173], v174 offset:2048
	ds_read_b128 v[174:177], v174 offset:3072
	s_add_u32 s28, s90, 0x80000
	s_addc_u32 s29, s91, 0
	s_mov_b32 m0, s14
	v_lshl_add_u64 v[242:243], s[28:29], 0, v[130:131]
	ds_read_b128 v[178:181], v145 offset:32768
	ds_read_b128 v[182:185], v145 offset:33792
	ds_read_b128 v[186:189], v145 offset:34816
	ds_read_b128 v[190:193], v145 offset:35840
	ds_read_b128 v[210:213], v145 offset:36864
	ds_read_b128 v[214:217], v145 offset:37888
	ds_read_b128 v[230:233], v145 offset:38912
	ds_read_b128 v[234:237], v145 offset:39936
	global_load_lds_dwordx4 v[242:243], off
	v_lshl_add_u64 v[242:243], s[28:29], 0, v[132:133]
	s_mov_b32 m0, s15
	s_nop 0
	global_load_lds_dwordx4 v[242:243], off
	s_waitcnt vmcnt(8)
	s_waitcnt lgkmcnt(0)
	s_barrier
	s_setprio 1
	s_waitcnt lgkmcnt(0)
	v_mfma_f32_16x16x32_bf16 v[126:129], v[146:149], v[178:181], v[126:129]
	v_mfma_f32_16x16x32_bf16 v[126:129], v[150:153], v[182:185], v[126:129]
	v_mfma_f32_16x16x32_bf16 v[118:121], v[146:149], v[186:189], v[118:121]
	v_mfma_f32_16x16x32_bf16 v[118:121], v[150:153], v[190:193], v[118:121]
	v_mfma_f32_16x16x32_bf16 v[102:105], v[146:149], v[210:213], v[102:105]
	v_mfma_f32_16x16x32_bf16 v[102:105], v[150:153], v[214:217], v[102:105]
	v_mfma_f32_16x16x32_bf16 v[86:89], v[146:149], v[230:233], v[86:89]
	v_mfma_f32_16x16x32_bf16 v[86:89], v[150:153], v[234:237], v[86:89]
	v_mfma_f32_16x16x32_bf16 v[78:81], v[154:157], v[230:233], v[78:81]
	v_mfma_f32_16x16x32_bf16 v[78:81], v[158:161], v[234:237], v[78:81]
	v_mfma_f32_16x16x32_bf16 v[94:97], v[154:157], v[210:213], v[94:97]
	v_mfma_f32_16x16x32_bf16 v[94:97], v[158:161], v[214:217], v[94:97]
	v_mfma_f32_16x16x32_bf16 v[110:113], v[154:157], v[186:189], v[110:113]
	v_mfma_f32_16x16x32_bf16 v[110:113], v[158:161], v[190:193], v[110:113]
	v_mfma_f32_16x16x32_bf16 v[122:125], v[154:157], v[178:181], v[122:125]
	v_mfma_f32_16x16x32_bf16 v[122:125], v[158:161], v[182:185], v[122:125]
	s_setprio 0
	s_setprio 1
	v_mfma_f32_16x16x32_bf16 v[114:117], v[162:165], v[178:181], v[114:117]
	v_mfma_f32_16x16x32_bf16 v[114:117], v[166:169], v[182:185], v[114:117]
	v_mfma_f32_16x16x32_bf16 v[98:101], v[162:165], v[186:189], v[98:101]
	v_mfma_f32_16x16x32_bf16 v[98:101], v[166:169], v[190:193], v[98:101]
	v_mfma_f32_16x16x32_bf16 v[82:85], v[162:165], v[210:213], v[82:85]
	v_mfma_f32_16x16x32_bf16 v[82:85], v[166:169], v[214:217], v[82:85]
	v_mfma_f32_16x16x32_bf16 v[70:73], v[162:165], v[230:233], v[70:73]
	v_mfma_f32_16x16x32_bf16 v[70:73], v[166:169], v[234:237], v[70:73]
	v_mfma_f32_16x16x32_bf16 v[66:69], v[170:173], v[230:233], v[66:69]
	v_mfma_f32_16x16x32_bf16 v[66:69], v[174:177], v[234:237], v[66:69]
	v_mfma_f32_16x16x32_bf16 v[74:77], v[170:173], v[210:213], v[74:77]
	v_mfma_f32_16x16x32_bf16 v[74:77], v[174:177], v[214:217], v[74:77]
	v_mfma_f32_16x16x32_bf16 v[90:93], v[170:173], v[186:189], v[90:93]
	v_mfma_f32_16x16x32_bf16 v[90:93], v[174:177], v[190:193], v[90:93]
	v_mfma_f32_16x16x32_bf16 v[106:109], v[170:173], v[178:181], v[106:109]
	v_mfma_f32_16x16x32_bf16 v[106:109], v[174:177], v[182:185], v[106:109]
	s_setprio 0
	s_barrier
	s_add_i32 s27, s27, s11
	v_lshl_add_u64 v[140:141], v[140:141], 0, s[56:57]
	s_mov_b32 m0, s27
	ds_read_b128 v[178:181], v145 offset:49152
	ds_read_b128 v[182:185], v145 offset:50176
	ds_read_b128 v[186:189], v145 offset:51200
	ds_read_b128 v[190:193], v145 offset:52224
	ds_read_b128 v[210:213], v145 offset:53248
	ds_read_b128 v[214:217], v145 offset:54272
	ds_read_b128 v[230:233], v145 offset:55296
	ds_read_b128 v[234:237], v145 offset:56320
	global_load_lds_dwordx4 v[140:141], off
	s_add_i32 m0, s27, 0x2000
	s_add_u32 s28, s54, 0x80080
	v_lshl_add_u64 v[140:141], v[218:219], 0, s[56:57]
	s_addc_u32 s29, s55, 0
	s_add_i32 s27, s30, s11
	global_load_lds_dwordx4 v[140:141], off
	v_lshl_add_u64 v[140:141], s[28:29], 0, v[194:195]
	s_mov_b32 m0, s27
	s_nop 0
	global_load_lds_dwordx4 v[140:141], off
	v_lshl_add_u64 v[140:141], s[28:29], 0, v[134:135]
	s_add_i32 m0, s27, 0x2000
	s_nop 0
	global_load_lds_dwordx4 v[140:141], off
	v_lshl_add_u64 v[140:141], v[238:239], 0, s[56:57]
	s_mov_b32 m0, s16
	s_nop 0
	global_load_lds_dwordx4 v[140:141], off
	v_lshl_add_u64 v[140:141], v[240:241], 0, s[56:57]
	s_mov_b32 m0, s17
	s_nop 0
	global_load_lds_dwordx4 v[140:141], off
	s_waitcnt vmcnt(8)
	s_waitcnt lgkmcnt(0)
	s_barrier
	s_setprio 1
	s_waitcnt lgkmcnt(0)
	v_mfma_f32_16x16x32_bf16 v[62:65], v[146:149], v[178:181], v[62:65]
	v_mfma_f32_16x16x32_bf16 v[62:65], v[150:153], v[182:185], v[62:65]
	v_mfma_f32_16x16x32_bf16 v[54:57], v[146:149], v[186:189], v[54:57]
	v_mfma_f32_16x16x32_bf16 v[54:57], v[150:153], v[190:193], v[54:57]
	v_mfma_f32_16x16x32_bf16 v[38:41], v[146:149], v[210:213], v[38:41]
	v_mfma_f32_16x16x32_bf16 v[38:41], v[150:153], v[214:217], v[38:41]
	v_mfma_f32_16x16x32_bf16 v[22:25], v[146:149], v[230:233], v[22:25]
	v_mfma_f32_16x16x32_bf16 v[22:25], v[150:153], v[234:237], v[22:25]
	v_mfma_f32_16x16x32_bf16 v[14:17], v[154:157], v[230:233], v[14:17]
	v_mfma_f32_16x16x32_bf16 v[14:17], v[158:161], v[234:237], v[14:17]
	v_mfma_f32_16x16x32_bf16 v[30:33], v[154:157], v[210:213], v[30:33]
	v_mfma_f32_16x16x32_bf16 v[30:33], v[158:161], v[214:217], v[30:33]
	v_mfma_f32_16x16x32_bf16 v[46:49], v[154:157], v[186:189], v[46:49]
	v_mfma_f32_16x16x32_bf16 v[46:49], v[158:161], v[190:193], v[46:49]
	v_mfma_f32_16x16x32_bf16 v[58:61], v[154:157], v[178:181], v[58:61]
	v_mfma_f32_16x16x32_bf16 v[58:61], v[158:161], v[182:185], v[58:61]
	s_setprio 0
	s_setprio 1
	v_mfma_f32_16x16x32_bf16 v[50:53], v[162:165], v[178:181], v[50:53]
	v_mfma_f32_16x16x32_bf16 v[50:53], v[166:169], v[182:185], v[50:53]
	v_mfma_f32_16x16x32_bf16 v[34:37], v[162:165], v[186:189], v[34:37]
	v_mfma_f32_16x16x32_bf16 v[34:37], v[166:169], v[190:193], v[34:37]
	v_mfma_f32_16x16x32_bf16 v[18:21], v[162:165], v[210:213], v[18:21]
	v_mfma_f32_16x16x32_bf16 v[18:21], v[166:169], v[214:217], v[18:21]
	v_mfma_f32_16x16x32_bf16 v[6:9], v[162:165], v[230:233], v[6:9]
	v_mfma_f32_16x16x32_bf16 v[6:9], v[166:169], v[234:237], v[6:9]
	v_mfma_f32_16x16x32_bf16 v[2:5], v[170:173], v[230:233], v[2:5]
	v_mfma_f32_16x16x32_bf16 v[2:5], v[174:177], v[234:237], v[2:5]
	v_mfma_f32_16x16x32_bf16 v[10:13], v[170:173], v[210:213], v[10:13]
	v_mfma_f32_16x16x32_bf16 v[10:13], v[174:177], v[214:217], v[10:13]
	v_mfma_f32_16x16x32_bf16 v[26:29], v[170:173], v[186:189], v[26:29]
	v_mfma_f32_16x16x32_bf16 v[26:29], v[174:177], v[190:193], v[26:29]
	v_mfma_f32_16x16x32_bf16 v[42:45], v[170:173], v[178:181], v[42:45]
	v_mfma_f32_16x16x32_bf16 v[42:45], v[174:177], v[182:185], v[42:45]
	s_setprio 0
	s_barrier
	s_add_i32 s26, s26, 2
	s_add_u32 s24, s24, 0x100
	s_addc_u32 s25, s25, 0
	s_add_u32 s88, s88, 0x100
	s_addc_u32 s89, s89, 0
	s_branch .LBB0_1465

.LBB0_1599:
	s_waitcnt vmcnt(0)
	v_lshrrev_b32_e32 v18, 1, v16
	v_and_b32_e32 v18, 24, v18
	s_add_u32 s52, s36, 0x2dc00000
	v_and_b32_e32 v17, 15, v16
	v_lshlrev_b32_e32 v19, 1, v18
	v_lshlrev_b32_e32 v16, 2, v16
	s_addc_u32 s53, s37, 0
	v_lshl_or_b32 v142, s18, 6, v17
	v_lshl_or_b32 v17, v17, 6, v19
	s_lshl_b32 s18, s18, 13
	v_and_b32_e32 v16, 32, v16
	v_bitop3_b32 v19, v17, s18, v16 bitop3:0xde
	s_lshl_b32 s18, s19, 5
	s_and_b32 s24, s18, 0x60
	s_lshl_b32 s18, s24, 7
	s_add_i32 m0, s14, 0x18000
	v_lshl_add_u64 v[8:9], v[8:9], 0, s[56:57]
	v_bitop3_b32 v143, v17, s18, v16 bitop3:0xde
	s_waitcnt vmcnt(2)
	s_barrier
	global_load_lds_dwordx4 v[8:9], off
	v_lshl_add_u64 v[6:7], v[6:7], 0, s[56:57]
	s_add_i32 m0, s14, 0x1a000
	s_add_i32 s18, s14, 0x8000
	s_add_i32 s19, s14, 0xa000
	global_load_lds_dwordx4 v[6:7], off
	v_lshl_add_u64 v[2:3], v[2:3], 0, s[56:57]
	s_mov_b32 m0, s18
	s_add_u32 s22, s54, 0x80080
	global_load_lds_dwordx4 v[2:3], off
	v_lshl_add_u64 v[2:3], v[4:5], 0, s[56:57]
	s_mov_b32 m0, s19
	s_addc_u32 s23, s55, 0
	global_load_lds_dwordx4 v[2:3], off
	s_add_i32 m0, s14, 0x1c000
	v_lshl_add_u64 v[2:3], s[22:23], 0, v[194:195]
	global_load_lds_dwordx4 v[2:3], off
	v_lshl_add_u64 v[2:3], s[22:23], 0, v[134:135]
	s_add_i32 m0, s14, 0x1e000
	s_cmpk_lt_u32 s20, 0x100
	global_load_lds_dwordx4 v[2:3], off
	v_lshlrev_b32_e32 v2, 15, v13
	v_and_b32_e32 v2, 0xffff0000, v2
	v_lshl_add_u32 v2, v14, 12, v2
	v_and_b32_e32 v3, 1, v13
	v_lshl_or_b32 v2, v3, 6, v2
	v_lshl_add_u32 v136, v15, 1, v2
	v_lshlrev_b32_e32 v2, 15, v10
	v_and_b32_e32 v2, 0xffff0000, v2
	s_waitcnt vmcnt(6)
	v_lshl_add_u32 v2, v11, 12, v2
	v_and_b32_e32 v3, 1, v10
	v_lshl_or_b32 v2, v3, 6, v2
	s_sext_i32_i16 s21, s38
	s_cselect_b64 s[36:37], -1, 0
	v_or_b32_e32 v144, s24, v18
	v_mov_b32_e32 v137, v195
	v_lshl_add_u32 v138, v12, 1, v2
	v_mov_b32_e32 v139, v195
	s_mov_b32 s20, 0
	v_add_u32_e32 v145, 0, v19
	s_barrier
	s_mov_b32 s98, 0
	s_branch .LBB0_1602

.LBB0_1602:
	s_add_i32 s20, s20, 1
	s_mul_i32 s22, s20, s2
	s_mul_hi_u32 s23, s20, s33
	s_add_i32 s23, s23, s22
	s_mul_i32 s22, s20, s33
	s_add_u32 s82, s22, s7
	s_addc_u32 s83, s23, s8
	v_cmp_gt_i64_e32 vcc, s[82:83], v[204:205]
	v_cmp_lt_i64_e64 s[38:39], s[82:83], v[202:203]
	s_cbranch_vccnz .LBB0_1608
	s_and_b32 s23, s82, 7
	s_lshr_b32 s22, s82, 3
	s_lshl_b32 s23, s23, 8
	s_add_i32 s22, s22, s23
	s_lshr_b32 s24, s22, 8
	s_lshl_b32 s24, s24, 3
	s_and_b32 s22, s22, 0xff
	s_lshr_b32 s78, s22, 3
	s_and_b32 s22, s22, 7
	s_add_i32 s80, s24, s22
.LBB0_1608:
	s_ashr_i32 s81, s80, 31
	s_lshl_b64 s[22:23], s[80:81], 20
	s_add_u32 s82, s9, s22
	s_addc_u32 s83, s10, s23
	s_and_b64 s[22:23], s[38:39], exec
	s_cselect_b32 s22, s83, s91
	s_cselect_b32 s23, s82, s90
	s_ashr_i32 s79, s78, 31
	s_lshl_b64 s[24:25], s[78:79], 20
	s_add_u32 s86, s11, s24
	s_addc_u32 s87, s12, s25
	s_and_b64 s[24:25], s[38:39], exec
	s_cselect_b32 s24, s87, s55
	s_cselect_b32 s25, s86, s54
	s_add_u32 s26, s54, 0x100
	s_addc_u32 s27, s55, 0
	s_add_u32 s90, s90, 0x80080
	v_mov_b32_e32 v2, 0
	s_addc_u32 s91, s91, 0
	s_mov_b32 s28, -2
	v_mov_b32_e32 v3, v2
	v_mov_b32_e32 v4, v2
	v_mov_b32_e32 v5, v2
	v_mov_b32_e32 v6, v2
	v_mov_b32_e32 v7, v2
	v_mov_b32_e32 v8, v2
	v_mov_b32_e32 v9, v2
	v_mov_b32_e32 v18, v2
	v_mov_b32_e32 v19, v2
	v_mov_b32_e32 v20, v2
	v_mov_b32_e32 v21, v2
	v_mov_b32_e32 v22, v2
	v_mov_b32_e32 v23, v2
	v_mov_b32_e32 v24, v2
	v_mov_b32_e32 v25, v2
	v_mov_b32_e32 v34, v2
	v_mov_b32_e32 v35, v2
	v_mov_b32_e32 v36, v2
	v_mov_b32_e32 v37, v2
	v_mov_b32_e32 v38, v2
	v_mov_b32_e32 v39, v2
	v_mov_b32_e32 v40, v2
	v_mov_b32_e32 v41, v2
	v_mov_b32_e32 v50, v2
	v_mov_b32_e32 v51, v2
	v_mov_b32_e32 v52, v2
	v_mov_b32_e32 v53, v2
	v_mov_b32_e32 v54, v2
	v_mov_b32_e32 v55, v2
	v_mov_b32_e32 v56, v2
	v_mov_b32_e32 v57, v2
	v_mov_b32_e32 v10, v2
	v_mov_b32_e32 v11, v2
	v_mov_b32_e32 v12, v2
	v_mov_b32_e32 v13, v2
	v_mov_b32_e32 v14, v2
	v_mov_b32_e32 v15, v2
	v_mov_b32_e32 v16, v2
	v_mov_b32_e32 v17, v2
	v_mov_b32_e32 v26, v2
	v_mov_b32_e32 v27, v2
	v_mov_b32_e32 v28, v2
	v_mov_b32_e32 v29, v2
	v_mov_b32_e32 v30, v2
	v_mov_b32_e32 v31, v2
	v_mov_b32_e32 v32, v2
	v_mov_b32_e32 v33, v2
	v_mov_b32_e32 v42, v2
	v_mov_b32_e32 v43, v2
	v_mov_b32_e32 v44, v2
	v_mov_b32_e32 v45, v2
	v_mov_b32_e32 v46, v2
	v_mov_b32_e32 v47, v2
	v_mov_b32_e32 v48, v2
	v_mov_b32_e32 v49, v2
	v_mov_b32_e32 v58, v2
	v_mov_b32_e32 v59, v2
	v_mov_b32_e32 v60, v2
	v_mov_b32_e32 v61, v2
	v_mov_b32_e32 v62, v2
	v_mov_b32_e32 v63, v2
	v_mov_b32_e32 v64, v2
	v_mov_b32_e32 v65, v2
	v_mov_b32_e32 v66, v2
	v_mov_b32_e32 v67, v2
	v_mov_b32_e32 v68, v2
	v_mov_b32_e32 v69, v2
	v_mov_b32_e32 v70, v2
	v_mov_b32_e32 v71, v2
	v_mov_b32_e32 v72, v2
	v_mov_b32_e32 v73, v2
	v_mov_b32_e32 v82, v2
	v_mov_b32_e32 v83, v2
	v_mov_b32_e32 v84, v2
	v_mov_b32_e32 v85, v2
	v_mov_b32_e32 v86, v2
	v_mov_b32_e32 v87, v2
	v_mov_b32_e32 v88, v2
	v_mov_b32_e32 v89, v2
	v_mov_b32_e32 v98, v2
	v_mov_b32_e32 v99, v2
	v_mov_b32_e32 v100, v2
	v_mov_b32_e32 v101, v2
	v_mov_b32_e32 v102, v2
	v_mov_b32_e32 v103, v2
	v_mov_b32_e32 v104, v2
	v_mov_b32_e32 v105, v2
	v_mov_b32_e32 v114, v2
	v_mov_b32_e32 v115, v2
	v_mov_b32_e32 v116, v2
	v_mov_b32_e32 v117, v2
	v_mov_b32_e32 v118, v2
	v_mov_b32_e32 v119, v2
	v_mov_b32_e32 v120, v2
	v_mov_b32_e32 v121, v2
	v_mov_b32_e32 v74, v2
	v_mov_b32_e32 v75, v2
	v_mov_b32_e32 v76, v2
	v_mov_b32_e32 v77, v2
	v_mov_b32_e32 v78, v2
	v_mov_b32_e32 v79, v2
	v_mov_b32_e32 v80, v2
	v_mov_b32_e32 v81, v2
	v_mov_b32_e32 v90, v2
	v_mov_b32_e32 v91, v2
	v_mov_b32_e32 v92, v2
	v_mov_b32_e32 v93, v2
	v_mov_b32_e32 v94, v2
	v_mov_b32_e32 v95, v2
	v_mov_b32_e32 v96, v2
	v_mov_b32_e32 v97, v2
	v_mov_b32_e32 v106, v2
	v_mov_b32_e32 v107, v2
	v_mov_b32_e32 v108, v2
	v_mov_b32_e32 v109, v2
	v_mov_b32_e32 v110, v2
	v_mov_b32_e32 v111, v2
	v_mov_b32_e32 v112, v2
	v_mov_b32_e32 v113, v2
	v_mov_b32_e32 v122, v2
	v_mov_b32_e32 v123, v2
	v_mov_b32_e32 v124, v2
	v_mov_b32_e32 v125, v2
	v_mov_b32_e32 v126, v2
	v_mov_b32_e32 v127, v2
	v_mov_b32_e32 v128, v2
	v_mov_b32_e32 v129, v2
	s_cmp_lg_u32 s98, 0
	s_mov_b32 s98, 1
	s_cbranch_scc0 .LBB0_1609
	s_add_u32 s29, s90, 0xfff80080
	s_addc_u32 s30, s91, -1
	s_add_i32 s31, 0, 0x10000
	s_cmp_eq_u32 s28, 28
	s_cselect_b32 vcc_hi, s22, s30
	s_cselect_b32 vcc_lo, s23, s29
	v_add_u32_e32 v140, s31, v143
	s_cselect_b32 s55, s24, s27
	s_cselect_b32 s54, s25, s26
	s_add_i32 s29, 0, 0x14000
	ds_read_b128 v[146:149], v140
	ds_read_b128 v[150:153], v140 offset:1024
	ds_read_b128 v[154:157], v140 offset:2048
	ds_read_b128 v[158:161], v140 offset:3072
	v_add_u32_e32 v140, s29, v143
	ds_read_b128 v[162:165], v140
	ds_read_b128 v[166:169], v140 offset:1024
	ds_read_b128 v[170:173], v140 offset:2048
	ds_read_b128 v[174:177], v140 offset:3072
	v_lshl_add_u64 v[140:141], s[90:91], 0, v[138:139]
	s_add_i32 m0, s14, 0xc000
	ds_read_b128 v[178:181], v145
	ds_read_b128 v[182:185], v145 offset:1024
	ds_read_b128 v[186:189], v145 offset:2048
	ds_read_b128 v[190:193], v145 offset:3072
	ds_read_b128 v[210:213], v145 offset:4096
	ds_read_b128 v[214:217], v145 offset:5120
	ds_read_b128 v[230:233], v145 offset:6144
	ds_read_b128 v[234:237], v145 offset:7168
	global_load_lds_dwordx4 v[140:141], off
	v_lshl_add_u64 v[140:141], s[90:91], 0, v[136:137]
	s_add_i32 m0, s14, 0xe000
	s_nop 0
	global_load_lds_dwordx4 v[140:141], off
	s_waitcnt vmcnt(24)
	s_waitcnt lgkmcnt(0)
	s_barrier
	s_setprio 1
	s_waitcnt lgkmcnt(0)
	v_mfma_f32_16x16x32_bf16 v[126:129], v[146:149], v[178:181], v[126:129]
	v_mfma_f32_16x16x32_bf16 v[126:129], v[150:153], v[182:185], v[126:129]
	v_mfma_f32_16x16x32_bf16 v[110:113], v[146:149], v[186:189], v[110:113]
	v_mfma_f32_16x16x32_bf16 v[110:113], v[150:153], v[190:193], v[110:113]
	v_mfma_f32_16x16x32_bf16 v[94:97], v[146:149], v[210:213], v[94:97]
	v_mfma_f32_16x16x32_bf16 v[94:97], v[150:153], v[214:217], v[94:97]
	v_mfma_f32_16x16x32_bf16 v[78:81], v[146:149], v[230:233], v[78:81]
	v_mfma_f32_16x16x32_bf16 v[78:81], v[150:153], v[234:237], v[78:81]
	v_mfma_f32_16x16x32_bf16 v[74:77], v[154:157], v[230:233], v[74:77]
	v_mfma_f32_16x16x32_bf16 v[74:77], v[158:161], v[234:237], v[74:77]
	v_mfma_f32_16x16x32_bf16 v[90:93], v[154:157], v[210:213], v[90:93]
	v_mfma_f32_16x16x32_bf16 v[90:93], v[158:161], v[214:217], v[90:93]
	v_mfma_f32_16x16x32_bf16 v[106:109], v[154:157], v[186:189], v[106:109]
	v_mfma_f32_16x16x32_bf16 v[106:109], v[158:161], v[190:193], v[106:109]
	v_mfma_f32_16x16x32_bf16 v[122:125], v[154:157], v[178:181], v[122:125]
	v_mfma_f32_16x16x32_bf16 v[122:125], v[158:161], v[182:185], v[122:125]
	s_setprio 0
	s_setprio 1
	v_mfma_f32_16x16x32_bf16 v[118:121], v[162:165], v[178:181], v[118:121]
	v_mfma_f32_16x16x32_bf16 v[118:121], v[166:169], v[182:185], v[118:121]
	v_mfma_f32_16x16x32_bf16 v[102:105], v[162:165], v[186:189], v[102:105]
	v_mfma_f32_16x16x32_bf16 v[102:105], v[166:169], v[190:193], v[102:105]
	v_mfma_f32_16x16x32_bf16 v[86:89], v[162:165], v[210:213], v[86:89]
	v_mfma_f32_16x16x32_bf16 v[86:89], v[166:169], v[214:217], v[86:89]
	v_mfma_f32_16x16x32_bf16 v[70:73], v[162:165], v[230:233], v[70:73]
	v_mfma_f32_16x16x32_bf16 v[70:73], v[166:169], v[234:237], v[70:73]
	v_mfma_f32_16x16x32_bf16 v[66:69], v[170:173], v[230:233], v[66:69]
	v_mfma_f32_16x16x32_bf16 v[66:69], v[174:177], v[234:237], v[66:69]
	v_mfma_f32_16x16x32_bf16 v[82:85], v[170:173], v[210:213], v[82:85]
	v_mfma_f32_16x16x32_bf16 v[82:85], v[174:177], v[214:217], v[82:85]
	v_mfma_f32_16x16x32_bf16 v[98:101], v[170:173], v[186:189], v[98:101]
	v_mfma_f32_16x16x32_bf16 v[98:101], v[174:177], v[190:193], v[98:101]
	v_mfma_f32_16x16x32_bf16 v[114:117], v[170:173], v[178:181], v[114:117]
	v_mfma_f32_16x16x32_bf16 v[114:117], v[174:177], v[182:185], v[114:117]
	s_setprio 0
	s_barrier
	s_add_i32 s30, s31, s13
	v_lshl_add_u64 v[140:141], s[54:55], 0, v[194:195]
	s_mov_b32 m0, s30
	ds_read_b128 v[178:181], v145 offset:16384
	ds_read_b128 v[182:185], v145 offset:17408
	ds_read_b128 v[186:189], v145 offset:18432
	ds_read_b128 v[190:193], v145 offset:19456
	ds_read_b128 v[210:213], v145 offset:20480
	ds_read_b128 v[214:217], v145 offset:21504
	ds_read_b128 v[230:233], v145 offset:22528
	ds_read_b128 v[234:237], v145 offset:23552
	global_load_lds_dwordx4 v[140:141], off
	s_add_i32 m0, s30, 0x2000
	s_add_u32 s30, s54, 0x80000
	v_lshl_add_u64 v[218:219], s[54:55], 0, v[134:135]
	s_addc_u32 s31, s55, 0
	s_add_i32 s29, s29, s13
	global_load_lds_dwordx4 v[218:219], off
	v_lshl_add_u64 v[238:239], s[30:31], 0, v[194:195]
	s_mov_b32 m0, s29
	v_lshl_add_u64 v[240:241], vcc, 0, v[132:133]
	global_load_lds_dwordx4 v[238:239], off
	v_lshl_add_u64 v[238:239], s[30:31], 0, v[134:135]
	s_add_i32 m0, s29, 0x2000
	s_nop 0
	global_load_lds_dwordx4 v[238:239], off
	v_lshl_add_u64 v[238:239], vcc, 0, v[130:131]
	s_mov_b32 m0, s14
	s_nop 0
	global_load_lds_dwordx4 v[238:239], off
	s_mov_b32 m0, s15
	s_nop 0
	global_load_lds_dwordx4 v[240:241], off
	s_waitcnt vmcnt(24)
	s_waitcnt lgkmcnt(0)
	s_barrier
	s_setprio 1
	s_waitcnt lgkmcnt(0)
	v_mfma_f32_16x16x32_bf16 v[62:65], v[146:149], v[178:181], v[62:65]
	v_mfma_f32_16x16x32_bf16 v[62:65], v[150:153], v[182:185], v[62:65]
	v_mfma_f32_16x16x32_bf16 v[46:49], v[146:149], v[186:189], v[46:49]
	v_mfma_f32_16x16x32_bf16 v[46:49], v[150:153], v[190:193], v[46:49]
	v_mfma_f32_16x16x32_bf16 v[30:33], v[146:149], v[210:213], v[30:33]
	v_mfma_f32_16x16x32_bf16 v[30:33], v[150:153], v[214:217], v[30:33]
	v_mfma_f32_16x16x32_bf16 v[14:17], v[146:149], v[230:233], v[14:17]
	v_mfma_f32_16x16x32_bf16 v[14:17], v[150:153], v[234:237], v[14:17]
	v_mfma_f32_16x16x32_bf16 v[10:13], v[154:157], v[230:233], v[10:13]
	v_mfma_f32_16x16x32_bf16 v[10:13], v[158:161], v[234:237], v[10:13]
	v_mfma_f32_16x16x32_bf16 v[26:29], v[154:157], v[210:213], v[26:29]
	v_mfma_f32_16x16x32_bf16 v[26:29], v[158:161], v[214:217], v[26:29]
	v_mfma_f32_16x16x32_bf16 v[42:45], v[154:157], v[186:189], v[42:45]
	v_mfma_f32_16x16x32_bf16 v[42:45], v[158:161], v[190:193], v[42:45]
	v_mfma_f32_16x16x32_bf16 v[58:61], v[154:157], v[178:181], v[58:61]
	v_mfma_f32_16x16x32_bf16 v[58:61], v[158:161], v[182:185], v[58:61]
	s_setprio 0
	s_setprio 1
	v_mfma_f32_16x16x32_bf16 v[54:57], v[162:165], v[178:181], v[54:57]
	v_mfma_f32_16x16x32_bf16 v[54:57], v[166:169], v[182:185], v[54:57]
	v_mfma_f32_16x16x32_bf16 v[38:41], v[162:165], v[186:189], v[38:41]
	v_mfma_f32_16x16x32_bf16 v[38:41], v[166:169], v[190:193], v[38:41]
	v_mfma_f32_16x16x32_bf16 v[22:25], v[162:165], v[210:213], v[22:25]
	v_mfma_f32_16x16x32_bf16 v[22:25], v[166:169], v[214:217], v[22:25]
	v_mfma_f32_16x16x32_bf16 v[6:9], v[162:165], v[230:233], v[6:9]
	v_mfma_f32_16x16x32_bf16 v[6:9], v[166:169], v[234:237], v[6:9]
	v_mfma_f32_16x16x32_bf16 v[2:5], v[170:173], v[230:233], v[2:5]
	v_mfma_f32_16x16x32_bf16 v[2:5], v[174:177], v[234:237], v[2:5]
	v_mfma_f32_16x16x32_bf16 v[18:21], v[170:173], v[210:213], v[18:21]
	v_mfma_f32_16x16x32_bf16 v[18:21], v[174:177], v[214:217], v[18:21]
	v_mfma_f32_16x16x32_bf16 v[34:37], v[170:173], v[186:189], v[34:37]
	v_mfma_f32_16x16x32_bf16 v[34:37], v[174:177], v[190:193], v[34:37]
	v_mfma_f32_16x16x32_bf16 v[50:53], v[170:173], v[178:181], v[50:53]
	v_mfma_f32_16x16x32_bf16 v[50:53], v[174:177], v[182:185], v[50:53]
	s_setprio 0
	s_barrier
	s_add_i32 s29, 0, 0x18000
	s_add_i32 s45, 0, 0x1c000
	v_add_u32_e32 v158, s29, v143
	v_add_u32_e32 v174, s45, v143
	ds_read_b128 v[146:149], v158
	ds_read_b128 v[150:153], v158 offset:1024
	ds_read_b128 v[154:157], v158 offset:2048
	ds_read_b128 v[158:161], v158 offset:3072
	ds_read_b128 v[162:165], v174
	ds_read_b128 v[166:169], v174 offset:1024
	ds_read_b128 v[170:173], v174 offset:2048
	ds_read_b128 v[174:177], v174 offset:3072
	s_add_u32 s30, vcc_lo, 0x80000
	s_addc_u32 s31, vcc_hi, 0
	s_mov_b32 m0, s16
	v_lshl_add_u64 v[242:243], s[30:31], 0, v[130:131]
	ds_read_b128 v[178:181], v145 offset:32768
	ds_read_b128 v[182:185], v145 offset:33792
	ds_read_b128 v[186:189], v145 offset:34816
	ds_read_b128 v[190:193], v145 offset:35840
	ds_read_b128 v[210:213], v145 offset:36864
	ds_read_b128 v[214:217], v145 offset:37888
	ds_read_b128 v[230:233], v145 offset:38912
	ds_read_b128 v[234:237], v145 offset:39936
	global_load_lds_dwordx4 v[242:243], off
	v_lshl_add_u64 v[242:243], s[30:31], 0, v[132:133]
	s_mov_b32 m0, s17
	s_nop 0
	global_load_lds_dwordx4 v[242:243], off
	s_waitcnt vmcnt(8)
	s_waitcnt lgkmcnt(0)
	s_barrier
	s_setprio 1
	s_waitcnt lgkmcnt(0)
	v_mfma_f32_16x16x32_bf16 v[126:129], v[146:149], v[178:181], v[126:129]
	v_mfma_f32_16x16x32_bf16 v[126:129], v[150:153], v[182:185], v[126:129]
	v_mfma_f32_16x16x32_bf16 v[110:113], v[146:149], v[186:189], v[110:113]
	v_mfma_f32_16x16x32_bf16 v[110:113], v[150:153], v[190:193], v[110:113]
	v_mfma_f32_16x16x32_bf16 v[94:97], v[146:149], v[210:213], v[94:97]
	v_mfma_f32_16x16x32_bf16 v[94:97], v[150:153], v[214:217], v[94:97]
	v_mfma_f32_16x16x32_bf16 v[78:81], v[146:149], v[230:233], v[78:81]
	v_mfma_f32_16x16x32_bf16 v[78:81], v[150:153], v[234:237], v[78:81]
	v_mfma_f32_16x16x32_bf16 v[74:77], v[154:157], v[230:233], v[74:77]
	v_mfma_f32_16x16x32_bf16 v[74:77], v[158:161], v[234:237], v[74:77]
	v_mfma_f32_16x16x32_bf16 v[90:93], v[154:157], v[210:213], v[90:93]
	v_mfma_f32_16x16x32_bf16 v[90:93], v[158:161], v[214:217], v[90:93]
	v_mfma_f32_16x16x32_bf16 v[106:109], v[154:157], v[186:189], v[106:109]
	v_mfma_f32_16x16x32_bf16 v[106:109], v[158:161], v[190:193], v[106:109]
	v_mfma_f32_16x16x32_bf16 v[122:125], v[154:157], v[178:181], v[122:125]
	v_mfma_f32_16x16x32_bf16 v[122:125], v[158:161], v[182:185], v[122:125]
	s_setprio 0
	s_setprio 1
	v_mfma_f32_16x16x32_bf16 v[118:121], v[162:165], v[178:181], v[118:121]
	v_mfma_f32_16x16x32_bf16 v[118:121], v[166:169], v[182:185], v[118:121]
	v_mfma_f32_16x16x32_bf16 v[102:105], v[162:165], v[186:189], v[102:105]
	v_mfma_f32_16x16x32_bf16 v[102:105], v[166:169], v[190:193], v[102:105]
	v_mfma_f32_16x16x32_bf16 v[86:89], v[162:165], v[210:213], v[86:89]
	v_mfma_f32_16x16x32_bf16 v[86:89], v[166:169], v[214:217], v[86:89]
	v_mfma_f32_16x16x32_bf16 v[70:73], v[162:165], v[230:233], v[70:73]
	v_mfma_f32_16x16x32_bf16 v[70:73], v[166:169], v[234:237], v[70:73]
	v_mfma_f32_16x16x32_bf16 v[66:69], v[170:173], v[230:233], v[66:69]
	v_mfma_f32_16x16x32_bf16 v[66:69], v[174:177], v[234:237], v[66:69]
	v_mfma_f32_16x16x32_bf16 v[82:85], v[170:173], v[210:213], v[82:85]
	v_mfma_f32_16x16x32_bf16 v[82:85], v[174:177], v[214:217], v[82:85]
	v_mfma_f32_16x16x32_bf16 v[98:101], v[170:173], v[186:189], v[98:101]
	v_mfma_f32_16x16x32_bf16 v[98:101], v[174:177], v[190:193], v[98:101]
	v_mfma_f32_16x16x32_bf16 v[114:117], v[170:173], v[178:181], v[114:117]
	v_mfma_f32_16x16x32_bf16 v[114:117], v[174:177], v[182:185], v[114:117]
	s_setprio 0
	s_barrier
	s_add_i32 s29, s29, s13
	v_lshl_add_u64 v[140:141], v[140:141], 0, s[56:57]
	s_mov_b32 m0, s29
	ds_read_b128 v[178:181], v145 offset:49152
	ds_read_b128 v[182:185], v145 offset:50176
	ds_read_b128 v[186:189], v145 offset:51200
	ds_read_b128 v[190:193], v145 offset:52224
	ds_read_b128 v[210:213], v145 offset:53248
	ds_read_b128 v[214:217], v145 offset:54272
	ds_read_b128 v[230:233], v145 offset:55296
	ds_read_b128 v[234:237], v145 offset:56320
	global_load_lds_dwordx4 v[140:141], off
	s_add_i32 m0, s29, 0x2000
	s_add_u32 s30, s54, 0x80080
	v_lshl_add_u64 v[140:141], v[218:219], 0, s[56:57]
	s_addc_u32 s31, s55, 0
	s_add_i32 s29, s45, s13
	global_load_lds_dwordx4 v[140:141], off
	v_lshl_add_u64 v[140:141], s[30:31], 0, v[194:195]
	s_mov_b32 m0, s29
	s_nop 0
	global_load_lds_dwordx4 v[140:141], off
	v_lshl_add_u64 v[140:141], s[30:31], 0, v[134:135]
	s_add_i32 m0, s29, 0x2000
	s_nop 0
	global_load_lds_dwordx4 v[140:141], off
	v_lshl_add_u64 v[140:141], v[238:239], 0, s[56:57]
	s_mov_b32 m0, s18
	s_nop 0
	global_load_lds_dwordx4 v[140:141], off
	v_lshl_add_u64 v[140:141], v[240:241], 0, s[56:57]
	s_mov_b32 m0, s19
	s_nop 0
	global_load_lds_dwordx4 v[140:141], off
	s_waitcnt vmcnt(8)
	s_waitcnt lgkmcnt(0)
	s_barrier
	s_setprio 1
	s_waitcnt lgkmcnt(0)
	v_mfma_f32_16x16x32_bf16 v[62:65], v[146:149], v[178:181], v[62:65]
	v_mfma_f32_16x16x32_bf16 v[62:65], v[150:153], v[182:185], v[62:65]
	v_mfma_f32_16x16x32_bf16 v[46:49], v[146:149], v[186:189], v[46:49]
	v_mfma_f32_16x16x32_bf16 v[46:49], v[150:153], v[190:193], v[46:49]
	v_mfma_f32_16x16x32_bf16 v[30:33], v[146:149], v[210:213], v[30:33]
	v_mfma_f32_16x16x32_bf16 v[30:33], v[150:153], v[214:217], v[30:33]
	v_mfma_f32_16x16x32_bf16 v[14:17], v[146:149], v[230:233], v[14:17]
	v_mfma_f32_16x16x32_bf16 v[14:17], v[150:153], v[234:237], v[14:17]
	v_mfma_f32_16x16x32_bf16 v[10:13], v[154:157], v[230:233], v[10:13]
	v_mfma_f32_16x16x32_bf16 v[10:13], v[158:161], v[234:237], v[10:13]
	v_mfma_f32_16x16x32_bf16 v[26:29], v[154:157], v[210:213], v[26:29]
	v_mfma_f32_16x16x32_bf16 v[26:29], v[158:161], v[214:217], v[26:29]
	v_mfma_f32_16x16x32_bf16 v[42:45], v[154:157], v[186:189], v[42:45]
	v_mfma_f32_16x16x32_bf16 v[42:45], v[158:161], v[190:193], v[42:45]
	v_mfma_f32_16x16x32_bf16 v[58:61], v[154:157], v[178:181], v[58:61]
	v_mfma_f32_16x16x32_bf16 v[58:61], v[158:161], v[182:185], v[58:61]
	s_setprio 0
	s_setprio 1
	v_mfma_f32_16x16x32_bf16 v[54:57], v[162:165], v[178:181], v[54:57]
	v_mfma_f32_16x16x32_bf16 v[54:57], v[166:169], v[182:185], v[54:57]
	v_mfma_f32_16x16x32_bf16 v[38:41], v[162:165], v[186:189], v[38:41]
	v_mfma_f32_16x16x32_bf16 v[38:41], v[166:169], v[190:193], v[38:41]
	v_mfma_f32_16x16x32_bf16 v[22:25], v[162:165], v[210:213], v[22:25]
	v_mfma_f32_16x16x32_bf16 v[22:25], v[166:169], v[214:217], v[22:25]
	v_mfma_f32_16x16x32_bf16 v[6:9], v[162:165], v[230:233], v[6:9]
	v_mfma_f32_16x16x32_bf16 v[6:9], v[166:169], v[234:237], v[6:9]
	v_mfma_f32_16x16x32_bf16 v[2:5], v[170:173], v[230:233], v[2:5]
	v_mfma_f32_16x16x32_bf16 v[2:5], v[174:177], v[234:237], v[2:5]
	v_mfma_f32_16x16x32_bf16 v[18:21], v[170:173], v[210:213], v[18:21]
	v_mfma_f32_16x16x32_bf16 v[18:21], v[174:177], v[214:217], v[18:21]
	v_mfma_f32_16x16x32_bf16 v[34:37], v[170:173], v[186:189], v[34:37]
	v_mfma_f32_16x16x32_bf16 v[34:37], v[174:177], v[190:193], v[34:37]
	v_mfma_f32_16x16x32_bf16 v[50:53], v[170:173], v[178:181], v[50:53]
	v_mfma_f32_16x16x32_bf16 v[50:53], v[174:177], v[182:185], v[50:53]
	s_setprio 0
	s_barrier
	s_add_i32 s28, s28, 2
	s_add_u32 s26, s26, 0x100
	s_addc_u32 s27, s27, 0
	s_add_u32 s90, s90, 0x100
	s_addc_u32 s91, s91, 0
	s_branch .LBB0_1609

.LBB0_1678:
	s_lshl_b64 s[22:23], s[40:41], 12
	s_add_u32 s21, s38, s22
	s_addc_u32 s22, s39, s23
	s_sext_i32_i8 s20, s42
	s_add_u32 s42, s21, 0xdc00000
	s_waitcnt vmcnt(0)
	v_lshrrev_b32_e32 v18, 1, v16
	s_addc_u32 s43, s22, 0
	v_and_b32_e32 v18, 24, v18
	s_lshl_b32 s17, s17, 5
	v_and_b32_e32 v17, 15, v16
	v_lshlrev_b32_e32 v19, 1, v18
	v_lshlrev_b32_e32 v16, 2, v16
	s_and_b32 s21, s17, 0x60
	v_lshl_or_b32 v142, s18, 6, v17
	v_lshl_or_b32 v17, v17, 6, v19
	s_lshl_b32 s18, s18, 13
	v_and_b32_e32 v16, 32, v16
	s_lshl_b32 s17, s21, 7
	s_add_i32 m0, s13, 0x18000
	v_lshl_add_u64 v[8:9], v[8:9], 0, s[56:57]
	v_bitop3_b32 v19, v17, s18, v16 bitop3:0xde
	v_bitop3_b32 v143, v17, s17, v16 bitop3:0xde
	s_waitcnt vmcnt(2)
	s_barrier
	global_load_lds_dwordx4 v[8:9], off
	v_lshl_add_u64 v[6:7], v[6:7], 0, s[56:57]
	s_add_i32 m0, s13, 0x1a000
	s_add_i32 s17, s13, 0x8000
	s_add_i32 s18, s13, 0xa000
	global_load_lds_dwordx4 v[6:7], off
	v_lshl_add_u64 v[2:3], v[2:3], 0, s[56:57]
	s_mov_b32 m0, s17
	s_add_u32 s22, s54, 0x200080
	global_load_lds_dwordx4 v[2:3], off
	v_lshl_add_u64 v[2:3], v[4:5], 0, s[56:57]
	s_mov_b32 m0, s18
	s_addc_u32 s23, s55, 0
	global_load_lds_dwordx4 v[2:3], off
	s_add_i32 m0, s13, 0x1c000
	v_lshl_add_u64 v[2:3], s[22:23], 0, v[194:195]
	global_load_lds_dwordx4 v[2:3], off
	v_lshl_add_u64 v[2:3], s[22:23], 0, v[134:135]
	s_add_i32 m0, s13, 0x1e000
	s_cmpk_lt_u32 s19, 0x100
	global_load_lds_dwordx4 v[2:3], off
	v_lshlrev_b32_e32 v2, 17, v13
	v_and_b32_e32 v2, 0xfffc0000, v2
	v_lshl_add_u32 v2, v14, 14, v2
	v_and_b32_e32 v3, 1, v13
	v_lshl_or_b32 v2, v3, 6, v2
	v_lshl_add_u32 v136, v15, 1, v2
	v_lshlrev_b32_e32 v2, 17, v10
	v_and_b32_e32 v2, 0xfffc0000, v2
	s_waitcnt vmcnt(6)
	v_lshl_add_u32 v2, v11, 14, v2
	v_and_b32_e32 v3, 1, v10
	v_lshl_or_b32 v2, v3, 6, v2
	s_cselect_b64 s[52:53], -1, 0
	v_or_b32_e32 v144, s21, v18
	v_mov_b32_e32 v137, v195
	v_lshl_add_u32 v138, v12, 1, v2
	v_mov_b32_e32 v139, v195
	s_mov_b32 s19, 0
	v_add_u32_e32 v145, 0, v19
	s_barrier
	s_mov_b32 s98, 0
	s_branch .LBB0_1681

.LBB0_1681:
	s_add_i32 s19, s19, 1
	s_mul_i32 s21, s19, s2
	s_mul_hi_u32 s22, s19, s33
	s_add_i32 s22, s22, s21
	s_mul_i32 s21, s19, s33
	s_add_u32 s86, s21, s6
	s_addc_u32 s87, s22, s7
	v_cmp_gt_i64_e32 vcc, s[86:87], v[208:209]
	v_cmp_lt_i64_e64 s[38:39], s[86:87], v[206:207]
	s_cbranch_vccnz .LBB0_1687
	s_and_b32 s22, s86, 7
	s_lshr_b32 s21, s86, 3
	s_lshl_b32 s22, s22, 6
	s_add_i32 s21, s21, s22
	s_lshr_b32 s23, s21, 5
	s_lshl_b32 s23, s23, 2
	s_and_b32 s21, s21, 0x1f
	s_lshr_b32 s78, s21, 2
	s_and_b32 s21, s21, 3
	s_add_i32 s80, s23, s21
.LBB0_1687:
	s_ashr_i32 s81, s80, 31
	s_lshl_b64 s[22:23], s[80:81], 22
	s_add_u32 s86, s8, s22
	s_addc_u32 s87, s9, s23
	s_and_b64 s[22:23], s[38:39], exec
	s_cselect_b32 s21, s87, s91
	s_cselect_b32 s22, s86, s90
	s_ashr_i32 s79, s78, 31
	s_lshl_b64 s[24:25], s[78:79], 22
	s_add_u32 s88, s10, s24
	s_addc_u32 s89, s11, s25
	s_and_b64 s[24:25], s[38:39], exec
	s_cselect_b32 s23, s89, s55
	s_cselect_b32 s24, s88, s54
	s_add_u32 s25, s54, 0x100
	s_addc_u32 s26, s55, 0
	s_add_u32 s90, s90, 0x200080
	v_mov_b32_e32 v2, 0
	s_addc_u32 s91, s91, 0
	s_mov_b32 s27, -2
	v_mov_b32_e32 v3, v2
	v_mov_b32_e32 v4, v2
	v_mov_b32_e32 v5, v2
	v_mov_b32_e32 v6, v2
	v_mov_b32_e32 v7, v2
	v_mov_b32_e32 v8, v2
	v_mov_b32_e32 v9, v2
	v_mov_b32_e32 v10, v2
	v_mov_b32_e32 v11, v2
	v_mov_b32_e32 v12, v2
	v_mov_b32_e32 v13, v2
	v_mov_b32_e32 v18, v2
	v_mov_b32_e32 v19, v2
	v_mov_b32_e32 v20, v2
	v_mov_b32_e32 v21, v2
	v_mov_b32_e32 v26, v2
	v_mov_b32_e32 v27, v2
	v_mov_b32_e32 v28, v2
	v_mov_b32_e32 v29, v2
	v_mov_b32_e32 v34, v2
	v_mov_b32_e32 v35, v2
	v_mov_b32_e32 v36, v2
	v_mov_b32_e32 v37, v2
	v_mov_b32_e32 v42, v2
	v_mov_b32_e32 v43, v2
	v_mov_b32_e32 v44, v2
	v_mov_b32_e32 v45, v2
	v_mov_b32_e32 v50, v2
	v_mov_b32_e32 v51, v2
	v_mov_b32_e32 v52, v2
	v_mov_b32_e32 v53, v2
	v_mov_b32_e32 v14, v2
	v_mov_b32_e32 v15, v2
	v_mov_b32_e32 v16, v2
	v_mov_b32_e32 v17, v2
	v_mov_b32_e32 v22, v2
	v_mov_b32_e32 v23, v2
	v_mov_b32_e32 v24, v2
	v_mov_b32_e32 v25, v2
	v_mov_b32_e32 v30, v2
	v_mov_b32_e32 v31, v2
	v_mov_b32_e32 v32, v2
	v_mov_b32_e32 v33, v2
	v_mov_b32_e32 v38, v2
	v_mov_b32_e32 v39, v2
	v_mov_b32_e32 v40, v2
	v_mov_b32_e32 v41, v2
	v_mov_b32_e32 v46, v2
	v_mov_b32_e32 v47, v2
	v_mov_b32_e32 v48, v2
	v_mov_b32_e32 v49, v2
	v_mov_b32_e32 v54, v2
	v_mov_b32_e32 v55, v2
	v_mov_b32_e32 v56, v2
	v_mov_b32_e32 v57, v2
	v_mov_b32_e32 v58, v2
	v_mov_b32_e32 v59, v2
	v_mov_b32_e32 v60, v2
	v_mov_b32_e32 v61, v2
	v_mov_b32_e32 v62, v2
	v_mov_b32_e32 v63, v2
	v_mov_b32_e32 v64, v2
	v_mov_b32_e32 v65, v2
	v_mov_b32_e32 v66, v2
	v_mov_b32_e32 v67, v2
	v_mov_b32_e32 v68, v2
	v_mov_b32_e32 v69, v2
	v_mov_b32_e32 v70, v2
	v_mov_b32_e32 v71, v2
	v_mov_b32_e32 v72, v2
	v_mov_b32_e32 v73, v2
	v_mov_b32_e32 v74, v2
	v_mov_b32_e32 v75, v2
	v_mov_b32_e32 v76, v2
	v_mov_b32_e32 v77, v2
	v_mov_b32_e32 v82, v2
	v_mov_b32_e32 v83, v2
	v_mov_b32_e32 v84, v2
	v_mov_b32_e32 v85, v2
	v_mov_b32_e32 v90, v2
	v_mov_b32_e32 v91, v2
	v_mov_b32_e32 v92, v2
	v_mov_b32_e32 v93, v2
	v_mov_b32_e32 v98, v2
	v_mov_b32_e32 v99, v2
	v_mov_b32_e32 v100, v2
	v_mov_b32_e32 v101, v2
	v_mov_b32_e32 v106, v2
	v_mov_b32_e32 v107, v2
	v_mov_b32_e32 v108, v2
	v_mov_b32_e32 v109, v2
	v_mov_b32_e32 v114, v2
	v_mov_b32_e32 v115, v2
	v_mov_b32_e32 v116, v2
	v_mov_b32_e32 v117, v2
	v_mov_b32_e32 v78, v2
	v_mov_b32_e32 v79, v2
	v_mov_b32_e32 v80, v2
	v_mov_b32_e32 v81, v2
	v_mov_b32_e32 v86, v2
	v_mov_b32_e32 v87, v2
	v_mov_b32_e32 v88, v2
	v_mov_b32_e32 v89, v2
	v_mov_b32_e32 v94, v2
	v_mov_b32_e32 v95, v2
	v_mov_b32_e32 v96, v2
	v_mov_b32_e32 v97, v2
	v_mov_b32_e32 v102, v2
	v_mov_b32_e32 v103, v2
	v_mov_b32_e32 v104, v2
	v_mov_b32_e32 v105, v2
	v_mov_b32_e32 v110, v2
	v_mov_b32_e32 v111, v2
	v_mov_b32_e32 v112, v2
	v_mov_b32_e32 v113, v2
	v_mov_b32_e32 v118, v2
	v_mov_b32_e32 v119, v2
	v_mov_b32_e32 v120, v2
	v_mov_b32_e32 v121, v2
	v_mov_b32_e32 v122, v2
	v_mov_b32_e32 v123, v2
	v_mov_b32_e32 v124, v2
	v_mov_b32_e32 v125, v2
	v_mov_b32_e32 v126, v2
	v_mov_b32_e32 v127, v2
	v_mov_b32_e32 v128, v2
	v_mov_b32_e32 v129, v2
	s_cmp_lg_u32 s98, 0
	s_mov_b32 s98, 1
	s_cbranch_scc0 .LBB0_1688
	s_add_u32 s28, s90, 0xffe00080
	s_addc_u32 s29, s91, -1
	s_add_i32 s30, 0, 0x10000
	s_cmpk_eq_i32 s27, 0x7c
	s_cselect_b32 vcc_hi, s21, s29
	s_cselect_b32 vcc_lo, s22, s28
	v_add_u32_e32 v140, s30, v143
	s_cselect_b32 s55, s23, s26
	s_cselect_b32 s54, s24, s25
	s_add_i32 s31, 0, 0x14000
	ds_read_b128 v[146:149], v140
	ds_read_b128 v[150:153], v140 offset:1024
	ds_read_b128 v[154:157], v140 offset:2048
	ds_read_b128 v[158:161], v140 offset:3072
	v_add_u32_e32 v140, s31, v143
	ds_read_b128 v[162:165], v140
	ds_read_b128 v[166:169], v140 offset:1024
	ds_read_b128 v[170:173], v140 offset:2048
	ds_read_b128 v[174:177], v140 offset:3072
	v_lshl_add_u64 v[140:141], s[90:91], 0, v[138:139]
	s_add_i32 m0, s13, 0xc000
	ds_read_b128 v[178:181], v145
	ds_read_b128 v[182:185], v145 offset:1024
	ds_read_b128 v[186:189], v145 offset:2048
	ds_read_b128 v[190:193], v145 offset:3072
	ds_read_b128 v[210:213], v145 offset:4096
	ds_read_b128 v[214:217], v145 offset:5120
	ds_read_b128 v[230:233], v145 offset:6144
	ds_read_b128 v[234:237], v145 offset:7168
	global_load_lds_dwordx4 v[140:141], off
	v_lshl_add_u64 v[140:141], s[90:91], 0, v[136:137]
	s_add_i32 m0, s13, 0xe000
	s_nop 0
	global_load_lds_dwordx4 v[140:141], off
	s_waitcnt vmcnt(24)
	s_waitcnt lgkmcnt(0)
	s_barrier
	s_setprio 1
	s_waitcnt lgkmcnt(0)
	v_mfma_f32_16x16x32_bf16 v[126:129], v[146:149], v[178:181], v[126:129]
	v_mfma_f32_16x16x32_bf16 v[126:129], v[150:153], v[182:185], v[126:129]
	v_mfma_f32_16x16x32_bf16 v[118:121], v[146:149], v[186:189], v[118:121]
	v_mfma_f32_16x16x32_bf16 v[118:121], v[150:153], v[190:193], v[118:121]
	v_mfma_f32_16x16x32_bf16 v[102:105], v[146:149], v[210:213], v[102:105]
	v_mfma_f32_16x16x32_bf16 v[102:105], v[150:153], v[214:217], v[102:105]
	v_mfma_f32_16x16x32_bf16 v[86:89], v[146:149], v[230:233], v[86:89]
	v_mfma_f32_16x16x32_bf16 v[86:89], v[150:153], v[234:237], v[86:89]
	v_mfma_f32_16x16x32_bf16 v[78:81], v[154:157], v[230:233], v[78:81]
	v_mfma_f32_16x16x32_bf16 v[78:81], v[158:161], v[234:237], v[78:81]
	v_mfma_f32_16x16x32_bf16 v[94:97], v[154:157], v[210:213], v[94:97]
	v_mfma_f32_16x16x32_bf16 v[94:97], v[158:161], v[214:217], v[94:97]
	v_mfma_f32_16x16x32_bf16 v[110:113], v[154:157], v[186:189], v[110:113]
	v_mfma_f32_16x16x32_bf16 v[110:113], v[158:161], v[190:193], v[110:113]
	v_mfma_f32_16x16x32_bf16 v[122:125], v[154:157], v[178:181], v[122:125]
	v_mfma_f32_16x16x32_bf16 v[122:125], v[158:161], v[182:185], v[122:125]
	s_setprio 0
	s_setprio 1
	v_mfma_f32_16x16x32_bf16 v[114:117], v[162:165], v[178:181], v[114:117]
	v_mfma_f32_16x16x32_bf16 v[114:117], v[166:169], v[182:185], v[114:117]
	v_mfma_f32_16x16x32_bf16 v[98:101], v[162:165], v[186:189], v[98:101]
	v_mfma_f32_16x16x32_bf16 v[98:101], v[166:169], v[190:193], v[98:101]
	v_mfma_f32_16x16x32_bf16 v[82:85], v[162:165], v[210:213], v[82:85]
	v_mfma_f32_16x16x32_bf16 v[82:85], v[166:169], v[214:217], v[82:85]
	v_mfma_f32_16x16x32_bf16 v[70:73], v[162:165], v[230:233], v[70:73]
	v_mfma_f32_16x16x32_bf16 v[70:73], v[166:169], v[234:237], v[70:73]
	v_mfma_f32_16x16x32_bf16 v[66:69], v[170:173], v[230:233], v[66:69]
	v_mfma_f32_16x16x32_bf16 v[66:69], v[174:177], v[234:237], v[66:69]
	v_mfma_f32_16x16x32_bf16 v[74:77], v[170:173], v[210:213], v[74:77]
	v_mfma_f32_16x16x32_bf16 v[74:77], v[174:177], v[214:217], v[74:77]
	v_mfma_f32_16x16x32_bf16 v[90:93], v[170:173], v[186:189], v[90:93]
	v_mfma_f32_16x16x32_bf16 v[90:93], v[174:177], v[190:193], v[90:93]
	v_mfma_f32_16x16x32_bf16 v[106:109], v[170:173], v[178:181], v[106:109]
	v_mfma_f32_16x16x32_bf16 v[106:109], v[174:177], v[182:185], v[106:109]
	s_setprio 0
	s_barrier
	s_add_i32 s28, s30, s12
	v_lshl_add_u64 v[140:141], s[54:55], 0, v[194:195]
	s_mov_b32 m0, s28
	ds_read_b128 v[178:181], v145 offset:16384
	ds_read_b128 v[182:185], v145 offset:17408
	ds_read_b128 v[186:189], v145 offset:18432
	ds_read_b128 v[190:193], v145 offset:19456
	ds_read_b128 v[210:213], v145 offset:20480
	ds_read_b128 v[214:217], v145 offset:21504
	ds_read_b128 v[230:233], v145 offset:22528
	ds_read_b128 v[234:237], v145 offset:23552
	global_load_lds_dwordx4 v[140:141], off
	s_add_i32 m0, s28, 0x2000
	s_add_u32 s28, s54, 0x200000
	v_lshl_add_u64 v[218:219], s[54:55], 0, v[134:135]
	s_addc_u32 s29, s55, 0
	s_add_i32 s30, s31, s12
	global_load_lds_dwordx4 v[218:219], off
	v_lshl_add_u64 v[238:239], s[28:29], 0, v[194:195]
	s_mov_b32 m0, s30
	v_lshl_add_u64 v[240:241], vcc, 0, v[132:133]
	global_load_lds_dwordx4 v[238:239], off
	v_lshl_add_u64 v[238:239], s[28:29], 0, v[134:135]
	s_add_i32 m0, s30, 0x2000
	s_nop 0
	global_load_lds_dwordx4 v[238:239], off
	v_lshl_add_u64 v[238:239], vcc, 0, v[130:131]
	s_mov_b32 m0, s13
	s_nop 0
	global_load_lds_dwordx4 v[238:239], off
	s_mov_b32 m0, s14
	s_nop 0
	global_load_lds_dwordx4 v[240:241], off
	s_waitcnt vmcnt(24)
	s_waitcnt lgkmcnt(0)
	s_barrier
	s_setprio 1
	s_waitcnt lgkmcnt(0)
	v_mfma_f32_16x16x32_bf16 v[62:65], v[146:149], v[178:181], v[62:65]
	v_mfma_f32_16x16x32_bf16 v[62:65], v[150:153], v[182:185], v[62:65]
	v_mfma_f32_16x16x32_bf16 v[54:57], v[146:149], v[186:189], v[54:57]
	v_mfma_f32_16x16x32_bf16 v[54:57], v[150:153], v[190:193], v[54:57]
	v_mfma_f32_16x16x32_bf16 v[38:41], v[146:149], v[210:213], v[38:41]
	v_mfma_f32_16x16x32_bf16 v[38:41], v[150:153], v[214:217], v[38:41]
	v_mfma_f32_16x16x32_bf16 v[22:25], v[146:149], v[230:233], v[22:25]
	v_mfma_f32_16x16x32_bf16 v[22:25], v[150:153], v[234:237], v[22:25]
	v_mfma_f32_16x16x32_bf16 v[14:17], v[154:157], v[230:233], v[14:17]
	v_mfma_f32_16x16x32_bf16 v[14:17], v[158:161], v[234:237], v[14:17]
	v_mfma_f32_16x16x32_bf16 v[30:33], v[154:157], v[210:213], v[30:33]
	v_mfma_f32_16x16x32_bf16 v[30:33], v[158:161], v[214:217], v[30:33]
	v_mfma_f32_16x16x32_bf16 v[46:49], v[154:157], v[186:189], v[46:49]
	v_mfma_f32_16x16x32_bf16 v[46:49], v[158:161], v[190:193], v[46:49]
	v_mfma_f32_16x16x32_bf16 v[58:61], v[154:157], v[178:181], v[58:61]
	v_mfma_f32_16x16x32_bf16 v[58:61], v[158:161], v[182:185], v[58:61]
	s_setprio 0
	s_setprio 1
	v_mfma_f32_16x16x32_bf16 v[50:53], v[162:165], v[178:181], v[50:53]
	v_mfma_f32_16x16x32_bf16 v[50:53], v[166:169], v[182:185], v[50:53]
	v_mfma_f32_16x16x32_bf16 v[34:37], v[162:165], v[186:189], v[34:37]
	v_mfma_f32_16x16x32_bf16 v[34:37], v[166:169], v[190:193], v[34:37]
	v_mfma_f32_16x16x32_bf16 v[18:21], v[162:165], v[210:213], v[18:21]
	v_mfma_f32_16x16x32_bf16 v[18:21], v[166:169], v[214:217], v[18:21]
	v_mfma_f32_16x16x32_bf16 v[6:9], v[162:165], v[230:233], v[6:9]
	v_mfma_f32_16x16x32_bf16 v[6:9], v[166:169], v[234:237], v[6:9]
	v_mfma_f32_16x16x32_bf16 v[2:5], v[170:173], v[230:233], v[2:5]
	v_mfma_f32_16x16x32_bf16 v[2:5], v[174:177], v[234:237], v[2:5]
	v_mfma_f32_16x16x32_bf16 v[10:13], v[170:173], v[210:213], v[10:13]
	v_mfma_f32_16x16x32_bf16 v[10:13], v[174:177], v[214:217], v[10:13]
	v_mfma_f32_16x16x32_bf16 v[26:29], v[170:173], v[186:189], v[26:29]
	v_mfma_f32_16x16x32_bf16 v[26:29], v[174:177], v[190:193], v[26:29]
	v_mfma_f32_16x16x32_bf16 v[42:45], v[170:173], v[178:181], v[42:45]
	v_mfma_f32_16x16x32_bf16 v[42:45], v[174:177], v[182:185], v[42:45]
	s_setprio 0
	s_barrier
	s_add_i32 s30, 0, 0x18000
	s_add_i32 s31, 0, 0x1c000
	v_add_u32_e32 v158, s30, v143
	v_add_u32_e32 v174, s31, v143
	ds_read_b128 v[146:149], v158
	ds_read_b128 v[150:153], v158 offset:1024
	ds_read_b128 v[154:157], v158 offset:2048
	ds_read_b128 v[158:161], v158 offset:3072
	ds_read_b128 v[162:165], v174
	ds_read_b128 v[166:169], v174 offset:1024
	ds_read_b128 v[170:173], v174 offset:2048
	ds_read_b128 v[174:177], v174 offset:3072
	s_add_u32 s28, vcc_lo, 0x200000
	s_addc_u32 s29, vcc_hi, 0
	s_mov_b32 m0, s15
	v_lshl_add_u64 v[242:243], s[28:29], 0, v[130:131]
	ds_read_b128 v[178:181], v145 offset:32768
	ds_read_b128 v[182:185], v145 offset:33792
	ds_read_b128 v[186:189], v145 offset:34816
	ds_read_b128 v[190:193], v145 offset:35840
	ds_read_b128 v[210:213], v145 offset:36864
	ds_read_b128 v[214:217], v145 offset:37888
	ds_read_b128 v[230:233], v145 offset:38912
	ds_read_b128 v[234:237], v145 offset:39936
	global_load_lds_dwordx4 v[242:243], off
	v_lshl_add_u64 v[242:243], s[28:29], 0, v[132:133]
	s_mov_b32 m0, s16
	s_nop 0
	global_load_lds_dwordx4 v[242:243], off
	s_waitcnt vmcnt(8)
	s_waitcnt lgkmcnt(0)
	s_barrier
	s_setprio 1
	s_waitcnt lgkmcnt(0)
	v_mfma_f32_16x16x32_bf16 v[126:129], v[146:149], v[178:181], v[126:129]
	v_mfma_f32_16x16x32_bf16 v[126:129], v[150:153], v[182:185], v[126:129]
	v_mfma_f32_16x16x32_bf16 v[118:121], v[146:149], v[186:189], v[118:121]
	v_mfma_f32_16x16x32_bf16 v[118:121], v[150:153], v[190:193], v[118:121]
	v_mfma_f32_16x16x32_bf16 v[102:105], v[146:149], v[210:213], v[102:105]
	v_mfma_f32_16x16x32_bf16 v[102:105], v[150:153], v[214:217], v[102:105]
	v_mfma_f32_16x16x32_bf16 v[86:89], v[146:149], v[230:233], v[86:89]
	v_mfma_f32_16x16x32_bf16 v[86:89], v[150:153], v[234:237], v[86:89]
	v_mfma_f32_16x16x32_bf16 v[78:81], v[154:157], v[230:233], v[78:81]
	v_mfma_f32_16x16x32_bf16 v[78:81], v[158:161], v[234:237], v[78:81]
	v_mfma_f32_16x16x32_bf16 v[94:97], v[154:157], v[210:213], v[94:97]
	v_mfma_f32_16x16x32_bf16 v[94:97], v[158:161], v[214:217], v[94:97]
	v_mfma_f32_16x16x32_bf16 v[110:113], v[154:157], v[186:189], v[110:113]
	v_mfma_f32_16x16x32_bf16 v[110:113], v[158:161], v[190:193], v[110:113]
	v_mfma_f32_16x16x32_bf16 v[122:125], v[154:157], v[178:181], v[122:125]
	v_mfma_f32_16x16x32_bf16 v[122:125], v[158:161], v[182:185], v[122:125]
	s_setprio 0
	s_setprio 1
	v_mfma_f32_16x16x32_bf16 v[114:117], v[162:165], v[178:181], v[114:117]
	v_mfma_f32_16x16x32_bf16 v[114:117], v[166:169], v[182:185], v[114:117]
	v_mfma_f32_16x16x32_bf16 v[98:101], v[162:165], v[186:189], v[98:101]
	v_mfma_f32_16x16x32_bf16 v[98:101], v[166:169], v[190:193], v[98:101]
	v_mfma_f32_16x16x32_bf16 v[82:85], v[162:165], v[210:213], v[82:85]
	v_mfma_f32_16x16x32_bf16 v[82:85], v[166:169], v[214:217], v[82:85]
	v_mfma_f32_16x16x32_bf16 v[70:73], v[162:165], v[230:233], v[70:73]
	v_mfma_f32_16x16x32_bf16 v[70:73], v[166:169], v[234:237], v[70:73]
	v_mfma_f32_16x16x32_bf16 v[66:69], v[170:173], v[230:233], v[66:69]
	v_mfma_f32_16x16x32_bf16 v[66:69], v[174:177], v[234:237], v[66:69]
	v_mfma_f32_16x16x32_bf16 v[74:77], v[170:173], v[210:213], v[74:77]
	v_mfma_f32_16x16x32_bf16 v[74:77], v[174:177], v[214:217], v[74:77]
	v_mfma_f32_16x16x32_bf16 v[90:93], v[170:173], v[186:189], v[90:93]
	v_mfma_f32_16x16x32_bf16 v[90:93], v[174:177], v[190:193], v[90:93]
	v_mfma_f32_16x16x32_bf16 v[106:109], v[170:173], v[178:181], v[106:109]
	v_mfma_f32_16x16x32_bf16 v[106:109], v[174:177], v[182:185], v[106:109]
	s_setprio 0
	s_barrier
	s_add_i32 s28, s30, s12
	v_lshl_add_u64 v[140:141], v[140:141], 0, s[56:57]
	s_mov_b32 m0, s28
	ds_read_b128 v[178:181], v145 offset:49152
	ds_read_b128 v[182:185], v145 offset:50176
	ds_read_b128 v[186:189], v145 offset:51200
	ds_read_b128 v[190:193], v145 offset:52224
	ds_read_b128 v[210:213], v145 offset:53248
	ds_read_b128 v[214:217], v145 offset:54272
	ds_read_b128 v[230:233], v145 offset:55296
	ds_read_b128 v[234:237], v145 offset:56320
	global_load_lds_dwordx4 v[140:141], off
	s_add_i32 m0, s28, 0x2000
	s_add_u32 s28, s54, 0x200080
	v_lshl_add_u64 v[140:141], v[218:219], 0, s[56:57]
	s_addc_u32 s29, s55, 0
	s_add_i32 s30, s31, s12
	global_load_lds_dwordx4 v[140:141], off
	v_lshl_add_u64 v[140:141], s[28:29], 0, v[194:195]
	s_mov_b32 m0, s30
	s_nop 0
	global_load_lds_dwordx4 v[140:141], off
	v_lshl_add_u64 v[140:141], s[28:29], 0, v[134:135]
	s_add_i32 m0, s30, 0x2000
	s_nop 0
	global_load_lds_dwordx4 v[140:141], off
	v_lshl_add_u64 v[140:141], v[238:239], 0, s[56:57]
	s_mov_b32 m0, s17
	s_nop 0
	global_load_lds_dwordx4 v[140:141], off
	v_lshl_add_u64 v[140:141], v[240:241], 0, s[56:57]
	s_mov_b32 m0, s18
	s_nop 0
	global_load_lds_dwordx4 v[140:141], off
	s_waitcnt vmcnt(8)
	s_waitcnt lgkmcnt(0)
	s_barrier
	s_setprio 1
	s_waitcnt lgkmcnt(0)
	v_mfma_f32_16x16x32_bf16 v[62:65], v[146:149], v[178:181], v[62:65]
	v_mfma_f32_16x16x32_bf16 v[62:65], v[150:153], v[182:185], v[62:65]
	v_mfma_f32_16x16x32_bf16 v[54:57], v[146:149], v[186:189], v[54:57]
	v_mfma_f32_16x16x32_bf16 v[54:57], v[150:153], v[190:193], v[54:57]
	v_mfma_f32_16x16x32_bf16 v[38:41], v[146:149], v[210:213], v[38:41]
	v_mfma_f32_16x16x32_bf16 v[38:41], v[150:153], v[214:217], v[38:41]
	v_mfma_f32_16x16x32_bf16 v[22:25], v[146:149], v[230:233], v[22:25]
	v_mfma_f32_16x16x32_bf16 v[22:25], v[150:153], v[234:237], v[22:25]
	v_mfma_f32_16x16x32_bf16 v[14:17], v[154:157], v[230:233], v[14:17]
	v_mfma_f32_16x16x32_bf16 v[14:17], v[158:161], v[234:237], v[14:17]
	v_mfma_f32_16x16x32_bf16 v[30:33], v[154:157], v[210:213], v[30:33]
	v_mfma_f32_16x16x32_bf16 v[30:33], v[158:161], v[214:217], v[30:33]
	v_mfma_f32_16x16x32_bf16 v[46:49], v[154:157], v[186:189], v[46:49]
	v_mfma_f32_16x16x32_bf16 v[46:49], v[158:161], v[190:193], v[46:49]
	v_mfma_f32_16x16x32_bf16 v[58:61], v[154:157], v[178:181], v[58:61]
	v_mfma_f32_16x16x32_bf16 v[58:61], v[158:161], v[182:185], v[58:61]
	s_setprio 0
	s_setprio 1
	v_mfma_f32_16x16x32_bf16 v[50:53], v[162:165], v[178:181], v[50:53]
	v_mfma_f32_16x16x32_bf16 v[50:53], v[166:169], v[182:185], v[50:53]
	v_mfma_f32_16x16x32_bf16 v[34:37], v[162:165], v[186:189], v[34:37]
	v_mfma_f32_16x16x32_bf16 v[34:37], v[166:169], v[190:193], v[34:37]
	v_mfma_f32_16x16x32_bf16 v[18:21], v[162:165], v[210:213], v[18:21]
	v_mfma_f32_16x16x32_bf16 v[18:21], v[166:169], v[214:217], v[18:21]
	v_mfma_f32_16x16x32_bf16 v[6:9], v[162:165], v[230:233], v[6:9]
	v_mfma_f32_16x16x32_bf16 v[6:9], v[166:169], v[234:237], v[6:9]
	v_mfma_f32_16x16x32_bf16 v[2:5], v[170:173], v[230:233], v[2:5]
	v_mfma_f32_16x16x32_bf16 v[2:5], v[174:177], v[234:237], v[2:5]
	v_mfma_f32_16x16x32_bf16 v[10:13], v[170:173], v[210:213], v[10:13]
	v_mfma_f32_16x16x32_bf16 v[10:13], v[174:177], v[214:217], v[10:13]
	v_mfma_f32_16x16x32_bf16 v[26:29], v[170:173], v[186:189], v[26:29]
	v_mfma_f32_16x16x32_bf16 v[26:29], v[174:177], v[190:193], v[26:29]
	v_mfma_f32_16x16x32_bf16 v[42:45], v[170:173], v[178:181], v[42:45]
	v_mfma_f32_16x16x32_bf16 v[42:45], v[174:177], v[182:185], v[42:45]
	s_setprio 0
	s_barrier
	s_add_i32 s27, s27, 2
	s_add_u32 s25, s25, 0x100
	s_addc_u32 s26, s26, 0
	s_add_u32 s90, s90, 0x100
	s_addc_u32 s91, s91, 0
	s_branch .LBB0_1688
